# gelu peepholes, wider: select rewritten at 80 sites (results placed where the packed ops were when the select's destination is free there), abs at 169 sites
# baseline (speedup 1.0000x reference)
.LBB0_443:
	s_waitcnt vmcnt(0)
	v_mov_b32_e32 v55, v0
	s_mov_b64 s[12:13], s[74:75]
	v_readfirstlane_b32 s0, v55
	s_ashr_i32 s10, s0, 6
	s_add_u32 s4, s12, 0x696e000
	v_bfe_u32 v3, v55, 4, 2
	s_addc_u32 s5, s13, 0
	s_lshl_b32 s11, s10, 4
	s_ashr_i32 s71, s70, 31
	v_or_b32_e32 v16, s11, v3
	s_lshl_b64 s[6:7], s[70:71], 7
	v_ashrrev_i32_e32 v17, 31, v16
	v_lshl_add_u64 v[4:5], s[6:7], 0, v[16:17]
	v_and_b32_e32 v54, 15, v55
	v_lshlrev_b64 v[4:5], 11, v[4:5]
	v_lshl_add_u64 v[4:5], s[4:5], 0, v[4:5]
	v_lshlrev_b32_e32 v6, 4, v54
	s_waitcnt lgkmcnt(0)
	v_mov_b32_e32 v7, v2
	v_lshl_add_u64 v[20:21], v[4:5], 0, v[6:7]
	s_barrier
	global_load_dwordx4 v[8:11], v[20:21], off
	global_load_dwordx4 v[4:7], v[20:21], off offset:256
	v_mov_b64_e32 v[18:19], s[44:45]
	v_mov_b32_e32 v13, v2
	s_waitcnt vmcnt(1)
	v_lshlrev_b32_e32 v24, 16, v10
	v_and_b32_e32 v25, 0xffff0000, v10
	v_and_b32_e32 v15, 0xffff0000, v8
	v_and_b32_e32 v23, 0xffff0000, v9
	v_lshlrev_b32_e32 v22, 16, v9
	v_lshlrev_b32_e32 v14, 16, v8
	v_lshlrev_b32_e32 v8, 16, v11
	v_and_b32_e32 v9, 0xffff0000, v11
	v_fma_f32 v10, |v24|, s40, 1.0
	v_fma_f32 v11, |v25|, s40, 1.0
	v_fma_f32 v28, |v14|, s40, 1.0
	v_fma_f32 v29, |v15|, s40, 1.0
	v_rcp_f32_e32 v10, v10
	v_rcp_f32_e32 v11, v11
	v_fma_f32 v32, |v22|, s40, 1.0
	v_fma_f32 v33, |v23|, s40, 1.0
	v_rcp_f32_e32 v28, v28
	v_rcp_f32_e32 v29, v29
	v_rcp_f32_e32 v32, v32
	v_rcp_f32_e32 v33, v33
	v_pk_mul_f32 v[26:27], v[24:25], v[24:25]
	v_pk_mul_f32 v[30:31], v[14:15], v[14:15]
	v_pk_mul_f32 v[26:27], v[26:27], s[64:65] op_sel_hi:[1,0]
	v_pk_fma_f32 v[36:37], v[10:11], s[42:43], v[18:19] op_sel_hi:[1,0,0]
	v_pk_mul_f32 v[34:35], v[22:23], v[22:23]
	v_pk_mul_f32 v[30:31], v[30:31], s[64:65] op_sel_hi:[1,0]
	v_exp_f32_e32 v26, v26
	v_exp_f32_e32 v27, v27
	v_pk_fma_f32 v[38:39], v[28:29], s[42:43], v[18:19] op_sel_hi:[1,0,0]
	v_pk_fma_f32 v[36:37], v[10:11], v[36:37], s[48:49] op_sel_hi:[1,1,0]
	v_pk_mul_f32 v[34:35], v[34:35], s[64:65] op_sel_hi:[1,0]
	v_exp_f32_e32 v30, v30
	v_exp_f32_e32 v31, v31
	v_pk_fma_f32 v[40:41], v[32:33], s[42:43], v[18:19] op_sel_hi:[1,0,0]
	v_pk_fma_f32 v[38:39], v[28:29], v[38:39], s[48:49] op_sel_hi:[1,1,0]
	v_pk_fma_f32 v[36:37], v[10:11], v[36:37], s[50:51] op_sel_hi:[1,1,0]
	v_exp_f32_e32 v34, v34
	v_exp_f32_e32 v35, v35
	v_pk_fma_f32 v[40:41], v[32:33], v[40:41], s[48:49] op_sel_hi:[1,1,0]
	v_pk_fma_f32 v[38:39], v[28:29], v[38:39], s[50:51] op_sel_hi:[1,1,0]
	v_pk_fma_f32 v[36:37], v[10:11], v[36:37], s[56:57] op_sel_hi:[1,1,0]
	v_pk_fma_f32 v[40:41], v[32:33], v[40:41], s[50:51] op_sel_hi:[1,1,0]
	v_pk_fma_f32 v[38:39], v[28:29], v[38:39], s[56:57] op_sel_hi:[1,1,0]
	v_pk_mul_f32 v[10:11], v[10:11], v[36:37]
	v_pk_fma_f32 v[40:41], v[32:33], v[40:41], s[56:57] op_sel_hi:[1,1,0]
	v_pk_mul_f32 v[28:29], v[28:29], v[38:39]
	v_pk_mul_f32 v[10:11], v[26:27], v[10:11]
	v_pk_mul_f32 v[32:33], v[32:33], v[40:41]
	v_pk_mul_f32 v[26:27], v[30:31], v[28:29]
	v_max_f32_e32 v80, 0, v24
	v_fma_f32 v37, -|v24|, v10, v80
	v_max_f32_e32 v81, 0, v25
	v_fma_f32 v11, -|v25|, v11, v81
	v_pk_mul_f32 v[28:29], v[34:35], v[32:33]
	v_pk_mul_f32 v[32:33], v[26:27], v[14:15]
	v_max_f32_e32 v82, 0, v22
	v_fma_f32 v25, -|v22|, v28, v82
	v_max_f32_e32 v83, 0, v23
	v_fma_f32 v23, -|v23|, v29, v83
	v_pk_fma_f32 v[26:27], v[26:27], v[14:15], v[14:15] neg_lo:[1,0,0] neg_hi:[1,0,0]
	v_mul_f32_e32 v36, v37, v37
	v_cmp_gt_f32_e32 vcc, 0, v14
	v_mov_b32_e32 v14, v25
	v_mul_f32_e32 v10, v11, v11
	v_cndmask_b32_e32 v24, v26, v32, vcc
	v_cmp_gt_f32_e32 vcc, 0, v15
	v_mul_f32_e32 v26, v24, v24
	v_pk_add_f32 v[10:11], v[36:37], v[10:11]
	v_cndmask_b32_e32 v15, v27, v33, vcc
	v_mov_b32_e32 v27, v25
	v_mul_f32_e32 v22, v15, v15
	v_mul_f32_e32 v12, v23, v23
	v_pk_add_f32 v[22:23], v[26:27], v[22:23]
	v_pk_mul_f32 v[26:27], v[24:25], v[14:15] op_sel:[1,0] op_sel_hi:[0,1]
	v_pk_add_f32 v[14:15], v[24:25], v[14:15] op_sel:[1,0] op_sel_hi:[0,1]
	v_mov_b32_e32 v27, v15
	v_fma_f32 v14, |v8|, s40, 1.0
	v_fma_f32 v15, |v9|, s40, 1.0
	v_pk_add_f32 v[12:13], v[26:27], v[12:13]
	v_rcp_f32_e32 v14, v14
	v_rcp_f32_e32 v15, v15
	v_pk_add_f32 v[12:13], v[22:23], v[12:13]
	v_cmp_gt_f32_e32 vcc, 0, v8
	v_pk_add_f32 v[22:23], v[10:11], v[12:13]
	v_pk_mul_f32 v[12:13], v[8:9], v[8:9]
	v_pk_fma_f32 v[10:11], v[14:15], s[42:43], v[18:19] op_sel_hi:[1,0,0]
	v_pk_mul_f32 v[12:13], v[12:13], s[64:65] op_sel_hi:[1,0]
	v_pk_fma_f32 v[10:11], v[14:15], v[10:11], s[48:49] op_sel_hi:[1,1,0]
	v_exp_f32_e32 v12, v12
	v_exp_f32_e32 v13, v13
	v_pk_fma_f32 v[10:11], v[14:15], v[10:11], s[50:51] op_sel_hi:[1,1,0]
	s_waitcnt vmcnt(0)
	v_lshlrev_b32_e32 v36, 16, v6
	v_pk_fma_f32 v[10:11], v[14:15], v[10:11], s[56:57] op_sel_hi:[1,1,0]
	v_and_b32_e32 v37, 0xffff0000, v6
	v_pk_mul_f32 v[10:11], v[14:15], v[10:11]
	v_pk_mul_f32 v[10:11], v[12:13], v[10:11]
	v_pk_mul_f32 v[12:13], v[8:9], v[10:11]
	v_pk_fma_f32 v[10:11], v[8:9], v[10:11], v[8:9] neg_lo:[1,0,0] neg_hi:[1,0,0]
	v_fma_f32 v32, |v36|, s40, 1.0
	v_fma_f32 v33, |v37|, s40, 1.0
	v_cndmask_b32_e32 v15, v10, v12, vcc
	v_cmp_gt_f32_e32 vcc, 0, v9
	v_lshlrev_b32_e32 v12, 16, v4
	v_and_b32_e32 v10, 0x7fffffff, v12
	v_cndmask_b32_e32 v9, v11, v13, vcc
	v_and_b32_e32 v13, 0xffff0000, v4
	v_and_b32_e32 v11, 0x7fffffff, v13
	v_pk_fma_f32 v[10:11], v[10:11], s[40:41], 1.0 op_sel_hi:[1,0,0]
	v_mul_f32_e32 v14, v15, v15
	v_rcp_f32_e32 v10, v10
	v_rcp_f32_e32 v11, v11
	v_mul_f32_e32 v8, v9, v9
	v_pk_add_f32 v[24:25], v[14:15], v[8:9]
	v_pk_mul_f32 v[14:15], v[12:13], v[12:13]
	v_pk_fma_f32 v[8:9], v[10:11], s[42:43], v[18:19] op_sel_hi:[1,0,0]
	v_pk_mul_f32 v[14:15], v[14:15], s[64:65] op_sel_hi:[1,0]
	v_pk_fma_f32 v[8:9], v[10:11], v[8:9], s[48:49] op_sel_hi:[1,1,0]
	v_exp_f32_e32 v14, v14
	v_exp_f32_e32 v15, v15
	v_pk_fma_f32 v[8:9], v[10:11], v[8:9], s[50:51] op_sel_hi:[1,1,0]
	v_lshlrev_b32_e32 v4, 16, v5
	v_pk_fma_f32 v[8:9], v[10:11], v[8:9], s[56:57] op_sel_hi:[1,1,0]
	v_and_b32_e32 v5, 0xffff0000, v5
	v_pk_mul_f32 v[8:9], v[10:11], v[8:9]
	v_pk_mul_f32 v[14:15], v[14:15], v[8:9]
	global_load_dwordx4 v[8:11], v[20:21], off offset:512
	v_fma_f32 v30, |v4|, s40, 1.0
	v_fma_f32 v31, |v5|, s40, 1.0
	v_rcp_f32_e32 v30, v30
	v_rcp_f32_e32 v31, v31
	v_max_f32_e32 v84, 0, v12
	v_fma_f32 v27, -|v12|, v14, v84
	v_max_f32_e32 v85, 0, v13
	v_fma_f32 v29, -|v13|, v15, v85
	v_rcp_f32_e32 v34, v32
	v_rcp_f32_e32 v35, v33
	v_pk_fma_f32 v[12:13], v[30:31], s[42:43], v[18:19] op_sel_hi:[1,0,0]
	v_mul_f32_e32 v26, v27, v27
	v_pk_mul_f32 v[14:15], v[4:5], v[4:5]
	v_pk_fma_f32 v[12:13], v[30:31], v[12:13], s[48:49] op_sel_hi:[1,1,0]
	v_pk_mul_f32 v[14:15], v[14:15], s[64:65] op_sel_hi:[1,0]
	v_pk_fma_f32 v[12:13], v[30:31], v[12:13], s[50:51] op_sel_hi:[1,1,0]
	v_exp_f32_e32 v14, v14
	v_exp_f32_e32 v15, v15
	v_pk_fma_f32 v[12:13], v[30:31], v[12:13], s[56:57] op_sel_hi:[1,1,0]
	v_cmp_gt_f32_e32 vcc, 0, v4
	v_pk_mul_f32 v[12:13], v[30:31], v[12:13]
	v_mul_f32_e32 v28, v29, v29
	v_pk_mul_f32 v[12:13], v[14:15], v[12:13]
	v_pk_add_f32 v[22:23], v[24:25], v[22:23]
	v_pk_mul_f32 v[14:15], v[4:5], v[12:13]
	v_pk_fma_f32 v[12:13], v[4:5], v[12:13], v[4:5] neg_lo:[1,0,0] neg_hi:[1,0,0]
	v_pk_add_f32 v[24:25], v[26:27], v[28:29]
	v_cndmask_b32_e32 v31, v12, v14, vcc
	v_cmp_gt_f32_e32 vcc, 0, v5
	v_pk_fma_f32 v[4:5], v[34:35], s[42:43], v[18:19] op_sel_hi:[1,0,0]
	v_lshlrev_b32_e32 v14, 16, v7
	v_cndmask_b32_e32 v33, v13, v15, vcc
	v_pk_mul_f32 v[12:13], v[36:37], v[36:37]
	v_pk_fma_f32 v[4:5], v[34:35], v[4:5], s[48:49] op_sel_hi:[1,1,0]
	v_pk_mul_f32 v[12:13], v[12:13], s[64:65] op_sel_hi:[1,0]
	v_pk_fma_f32 v[4:5], v[34:35], v[4:5], s[50:51] op_sel_hi:[1,1,0]
	v_exp_f32_e32 v12, v12
	v_exp_f32_e32 v13, v13
	v_and_b32_e32 v15, 0xffff0000, v7
	v_pk_fma_f32 v[4:5], v[34:35], v[4:5], s[56:57] op_sel_hi:[1,1,0]
	v_pk_mul_f32 v[4:5], v[34:35], v[4:5]
	v_fma_f32 v6, |v14|, s40, 1.0
	v_fma_f32 v7, |v15|, s40, 1.0
	v_pk_mul_f32 v[4:5], v[12:13], v[4:5]
	v_rcp_f32_e32 v6, v6
	v_rcp_f32_e32 v7, v7
	v_max_f32_e32 v86, 0, v36
	v_fma_f32 v35, -|v36|, v4, v86
	v_max_f32_e32 v90, 0, v37
	v_fma_f32 v37, -|v37|, v5, v90
	v_mul_f32_e32 v30, v31, v31
	v_mul_f32_e32 v32, v33, v33
	v_mul_f32_e32 v34, v35, v35
	v_pk_add_f32 v[22:23], v[24:25], v[22:23]
	v_pk_mul_f32 v[12:13], v[14:15], v[14:15]
	v_pk_fma_f32 v[4:5], v[6:7], s[42:43], v[18:19] op_sel_hi:[1,0,0]
	v_pk_mul_f32 v[12:13], v[12:13], s[64:65] op_sel_hi:[1,0]
	v_pk_fma_f32 v[4:5], v[6:7], v[4:5], s[48:49] op_sel_hi:[1,1,0]
	v_exp_f32_e32 v12, v12
	v_exp_f32_e32 v13, v13
	v_pk_fma_f32 v[4:5], v[6:7], v[4:5], s[50:51] op_sel_hi:[1,1,0]
	v_cmp_gt_f32_e32 vcc, 0, v14
	v_pk_fma_f32 v[4:5], v[6:7], v[4:5], s[56:57] op_sel_hi:[1,1,0]
	v_mul_f32_e32 v36, v37, v37
	v_pk_mul_f32 v[4:5], v[6:7], v[4:5]
	v_pk_add_f32 v[24:25], v[30:31], v[32:33]
	v_pk_mul_f32 v[4:5], v[12:13], v[4:5]
	v_pk_add_f32 v[22:23], v[24:25], v[22:23]
	v_pk_mul_f32 v[12:13], v[14:15], v[4:5]
	v_pk_fma_f32 v[40:41], v[14:15], v[4:5], v[14:15] neg_lo:[1,0,0] neg_hi:[1,0,0]
	global_load_dwordx4 v[4:7], v[20:21], off offset:768
	v_cndmask_b32_e32 v39, v40, v12, vcc
	v_cmp_gt_f32_e32 vcc, 0, v15
	v_mul_f32_e32 v38, v39, v39
	s_waitcnt vmcnt(1)
	v_lshlrev_b32_e32 v44, 16, v8
	v_and_b32_e32 v45, 0xffff0000, v8
	v_fma_f32 v42, |v44|, s40, 1.0
	v_fma_f32 v43, |v45|, s40, 1.0
	v_pk_mul_f32 v[14:15], v[44:45], v[44:45]
	v_rcp_f32_e32 v42, v42
	v_rcp_f32_e32 v43, v43
	v_cndmask_b32_e32 v41, v41, v13, vcc
	v_pk_mul_f32 v[14:15], v[14:15], s[64:65] op_sel_hi:[1,0]
	v_lshlrev_b32_e32 v46, 16, v9
	v_pk_fma_f32 v[12:13], v[42:43], s[42:43], v[18:19] op_sel_hi:[1,0,0]
	v_exp_f32_e32 v14, v14
	v_pk_fma_f32 v[12:13], v[42:43], v[12:13], s[48:49] op_sel_hi:[1,1,0]
	v_exp_f32_e32 v15, v15
	v_and_b32_e32 v47, 0xffff0000, v9
	v_pk_fma_f32 v[12:13], v[42:43], v[12:13], s[50:51] op_sel_hi:[1,1,0]
	v_pk_fma_f32 v[12:13], v[42:43], v[12:13], s[56:57] op_sel_hi:[1,1,0]
	v_fma_f32 v8, |v46|, s40, 1.0
	v_fma_f32 v9, |v47|, s40, 1.0
	v_pk_mul_f32 v[12:13], v[42:43], v[12:13]
	v_rcp_f32_e32 v48, v8
	v_rcp_f32_e32 v49, v9
	v_pk_mul_f32 v[12:13], v[14:15], v[12:13]
	v_cmp_gt_f32_e32 vcc, 0, v44
	v_pk_mul_f32 v[14:15], v[44:45], v[12:13]
	v_pk_fma_f32 v[12:13], v[44:45], v[12:13], v[44:45] neg_lo:[1,0,0] neg_hi:[1,0,0]
	v_lshlrev_b32_e32 v50, 16, v10
	v_cndmask_b32_e32 v43, v12, v14, vcc
	v_cmp_gt_f32_e32 vcc, 0, v45
	v_and_b32_e32 v51, 0xffff0000, v10
	v_lshlrev_b32_e32 v10, 16, v11
	v_cndmask_b32_e32 v9, v13, v15, vcc
	v_pk_fma_f32 v[12:13], v[48:49], s[42:43], v[18:19] op_sel_hi:[1,0,0]
	v_pk_mul_f32 v[14:15], v[46:47], v[46:47]
	v_pk_fma_f32 v[12:13], v[48:49], v[12:13], s[48:49] op_sel_hi:[1,1,0]
	v_pk_mul_f32 v[14:15], v[14:15], s[64:65] op_sel_hi:[1,0]
	v_pk_fma_f32 v[12:13], v[48:49], v[12:13], s[50:51] op_sel_hi:[1,1,0]
	v_exp_f32_e32 v14, v14
	v_exp_f32_e32 v15, v15
	v_pk_fma_f32 v[12:13], v[48:49], v[12:13], s[56:57] op_sel_hi:[1,1,0]
	v_cmp_gt_f32_e32 vcc, 0, v46
	v_pk_mul_f32 v[12:13], v[48:49], v[12:13]
	v_fma_f32 v48, |v50|, s40, 1.0
	v_fma_f32 v49, |v51|, s40, 1.0
	v_pk_mul_f32 v[12:13], v[14:15], v[12:13]
	v_rcp_f32_e32 v48, v48
	v_rcp_f32_e32 v49, v49
	v_pk_mul_f32 v[14:15], v[46:47], v[12:13]
	v_pk_fma_f32 v[12:13], v[46:47], v[12:13], v[46:47] neg_lo:[1,0,0] neg_hi:[1,0,0]
	v_and_b32_e32 v11, 0xffff0000, v11
	v_cndmask_b32_e32 v45, v12, v14, vcc
	v_cmp_gt_f32_e32 vcc, 0, v47
	v_cndmask_b32_e32 v47, v13, v15, vcc
	v_pk_mul_f32 v[14:15], v[50:51], v[50:51]
	v_pk_fma_f32 v[12:13], v[48:49], s[42:43], v[18:19] op_sel_hi:[1,0,0]
	v_pk_mul_f32 v[14:15], v[14:15], s[64:65] op_sel_hi:[1,0]
	v_pk_fma_f32 v[12:13], v[48:49], v[12:13], s[48:49] op_sel_hi:[1,1,0]
	v_exp_f32_e32 v14, v14
	v_exp_f32_e32 v15, v15
	v_pk_fma_f32 v[12:13], v[48:49], v[12:13], s[50:51] op_sel_hi:[1,1,0]
	v_fma_f32 v52, |v10|, s40, 1.0
	v_fma_f32 v53, |v11|, s40, 1.0
	v_pk_fma_f32 v[12:13], v[48:49], v[12:13], s[56:57] op_sel_hi:[1,1,0]
	v_rcp_f32_e32 v52, v52
	v_pk_mul_f32 v[12:13], v[48:49], v[12:13]
	v_rcp_f32_e32 v53, v53
	v_pk_mul_f32 v[12:13], v[14:15], v[12:13]
	v_cmp_gt_f32_e32 vcc, 0, v50
	v_pk_mul_f32 v[14:15], v[50:51], v[12:13]
	v_pk_fma_f32 v[12:13], v[50:51], v[12:13], v[50:51] neg_lo:[1,0,0] neg_hi:[1,0,0]
	v_mul_f32_e32 v40, v41, v41
	v_cndmask_b32_e32 v49, v12, v14, vcc
	v_cmp_gt_f32_e32 vcc, 0, v51
	s_waitcnt vmcnt(0)
	v_lshlrev_b32_e32 v56, 16, v4
	v_and_b32_e32 v57, 0xffff0000, v4
	v_cndmask_b32_e32 v51, v13, v15, vcc
	v_pk_mul_f32 v[14:15], v[10:11], v[10:11]
	v_pk_fma_f32 v[12:13], v[52:53], s[42:43], v[18:19] op_sel_hi:[1,0,0]
	v_pk_mul_f32 v[14:15], v[14:15], s[64:65] op_sel_hi:[1,0]
	v_pk_fma_f32 v[12:13], v[52:53], v[12:13], s[48:49] op_sel_hi:[1,1,0]
	v_exp_f32_e32 v14, v14
	v_exp_f32_e32 v15, v15
	v_pk_fma_f32 v[12:13], v[52:53], v[12:13], s[50:51] op_sel_hi:[1,1,0]
	v_pk_fma_f32 v[12:13], v[52:53], v[12:13], s[56:57] op_sel_hi:[1,1,0]
	v_pk_mul_f32 v[12:13], v[52:53], v[12:13]
	v_fma_f32 v58, |v56|, s40, 1.0
	v_fma_f32 v59, |v57|, s40, 1.0
	v_pk_mul_f32 v[12:13], v[14:15], v[12:13]
	v_rcp_f32_e32 v58, v58
	v_rcp_f32_e32 v59, v59
	v_max_f32_e32 v91, 0, v10
	v_fma_f32 v53, -|v10|, v12, v91
	v_max_f32_e32 v92, 0, v11
	v_fma_f32 v11, -|v11|, v13, v92
	v_lshlrev_b32_e32 v4, 16, v5
	v_and_b32_e32 v5, 0xffff0000, v5
	v_pk_mul_f32 v[14:15], v[56:57], v[56:57]
	v_pk_fma_f32 v[12:13], v[58:59], s[42:43], v[18:19] op_sel_hi:[1,0,0]
	v_pk_mul_f32 v[14:15], v[14:15], s[64:65] op_sel_hi:[1,0]
	v_pk_fma_f32 v[12:13], v[58:59], v[12:13], s[48:49] op_sel_hi:[1,1,0]
	v_exp_f32_e32 v14, v14
	v_exp_f32_e32 v15, v15
	v_pk_fma_f32 v[12:13], v[58:59], v[12:13], s[50:51] op_sel_hi:[1,1,0]
	v_fma_f32 v60, |v4|, s40, 1.0
	v_fma_f32 v61, |v5|, s40, 1.0
	v_pk_fma_f32 v[12:13], v[58:59], v[12:13], s[56:57] op_sel_hi:[1,1,0]
	v_rcp_f32_e32 v60, v60
	v_pk_mul_f32 v[12:13], v[58:59], v[12:13]
	v_rcp_f32_e32 v61, v61
	v_pk_mul_f32 v[12:13], v[14:15], v[12:13]
	v_cmp_gt_f32_e32 vcc, 0, v56
	v_pk_mul_f32 v[14:15], v[56:57], v[12:13]
	v_pk_fma_f32 v[12:13], v[56:57], v[12:13], v[56:57] neg_lo:[1,0,0] neg_hi:[1,0,0]
	v_pk_add_f32 v[24:25], v[34:35], v[36:37]
	v_cndmask_b32_e32 v59, v12, v14, vcc
	v_cmp_gt_f32_e32 vcc, 0, v57
	v_mul_f32_e32 v42, v43, v43
	v_mul_f32_e32 v8, v9, v9
	v_cndmask_b32_e32 v57, v13, v15, vcc
	v_pk_fma_f32 v[12:13], v[60:61], s[42:43], v[18:19] op_sel_hi:[1,0,0]
	v_pk_mul_f32 v[14:15], v[4:5], v[4:5]
	v_pk_fma_f32 v[12:13], v[60:61], v[12:13], s[48:49] op_sel_hi:[1,1,0]
	v_pk_mul_f32 v[14:15], v[14:15], s[64:65] op_sel_hi:[1,0]
	v_pk_fma_f32 v[12:13], v[60:61], v[12:13], s[50:51] op_sel_hi:[1,1,0]
	v_exp_f32_e32 v62, v14
	v_exp_f32_e32 v63, v15
	v_pk_fma_f32 v[64:65], v[60:61], v[12:13], s[56:57] op_sel_hi:[1,1,0]
	global_load_dwordx4 v[12:15], v[20:21], off offset:1024
	v_pk_add_f32 v[22:23], v[24:25], v[22:23]
	v_pk_add_f32 v[24:25], v[38:39], v[40:41]
	v_mul_f32_e32 v44, v45, v45
	v_mul_f32_e32 v46, v47, v47
	v_pk_add_f32 v[22:23], v[24:25], v[22:23]
	v_pk_add_f32 v[8:9], v[42:43], v[8:9]
	v_mul_f32_e32 v48, v49, v49
	v_mul_f32_e32 v50, v51, v51
	v_pk_mul_f32 v[60:61], v[60:61], v[64:65]
	v_pk_add_f32 v[8:9], v[8:9], v[22:23]
	v_pk_add_f32 v[22:23], v[44:45], v[46:47]
	v_pk_mul_f32 v[60:61], v[62:63], v[60:61]
	v_pk_add_f32 v[8:9], v[22:23], v[8:9]
	v_pk_add_f32 v[22:23], v[48:49], v[50:51]
	v_lshlrev_b32_e32 v24, 16, v6
	v_and_b32_e32 v25, 0xffff0000, v6
	v_max_f32_e32 v93, 0, v4
	v_fma_f32 v65, -|v4|, v60, v93
	v_max_f32_e32 v94, 0, v5
	v_fma_f32 v5, -|v5|, v61, v94
	v_pk_add_f32 v[8:9], v[22:23], v[8:9]
	v_mul_f32_e32 v52, v53, v53
	v_mul_f32_e32 v10, v11, v11
	v_fma_f32 v22, |v24|, s40, 1.0
	v_fma_f32 v23, |v25|, s40, 1.0
	v_mul_f32_e32 v58, v59, v59
	v_mul_f32_e32 v56, v57, v57
	v_pk_add_f32 v[10:11], v[52:53], v[10:11]
	v_rcp_f32_e32 v26, v22
	v_rcp_f32_e32 v27, v23
	v_mul_f32_e32 v64, v65, v65
	v_mul_f32_e32 v4, v5, v5
	v_pk_add_f32 v[8:9], v[10:11], v[8:9]
	v_pk_add_f32 v[10:11], v[58:59], v[56:57]
	v_pk_add_f32 v[4:5], v[64:65], v[4:5]
	v_pk_add_f32 v[8:9], v[10:11], v[8:9]
	v_cmp_gt_f32_e32 vcc, 0, v24
	v_pk_add_f32 v[22:23], v[4:5], v[8:9]
	v_pk_mul_f32 v[8:9], v[24:25], v[24:25]
	v_pk_fma_f32 v[4:5], v[26:27], s[42:43], v[18:19] op_sel_hi:[1,0,0]
	v_pk_mul_f32 v[8:9], v[8:9], s[64:65] op_sel_hi:[1,0]
	v_pk_fma_f32 v[4:5], v[26:27], v[4:5], s[48:49] op_sel_hi:[1,1,0]
	v_exp_f32_e32 v8, v8
	v_exp_f32_e32 v9, v9
	v_pk_fma_f32 v[4:5], v[26:27], v[4:5], s[50:51] op_sel_hi:[1,1,0]
	v_lshlrev_b32_e32 v6, 16, v7
	v_pk_fma_f32 v[4:5], v[26:27], v[4:5], s[56:57] op_sel_hi:[1,1,0]
	v_and_b32_e32 v7, 0xffff0000, v7
	v_pk_mul_f32 v[4:5], v[26:27], v[4:5]
	s_nop 0
	v_pk_mul_f32 v[4:5], v[8:9], v[4:5]
	s_nop 0
	v_pk_mul_f32 v[8:9], v[24:25], v[4:5]
	v_pk_fma_f32 v[4:5], v[24:25], v[4:5], v[24:25] neg_lo:[1,0,0] neg_hi:[1,0,0]
	s_nop 0
	v_cndmask_b32_e32 v11, v4, v8, vcc
	v_cmp_gt_f32_e32 vcc, 0, v25
	v_and_b32_e32 v8, 0x7fffffff, v6
	v_mul_f32_e32 v10, v11, v11
	v_cndmask_b32_e32 v5, v5, v9, vcc
	v_and_b32_e32 v9, 0x7fffffff, v7
	v_pk_fma_f32 v[8:9], v[8:9], s[40:41], 1.0 op_sel_hi:[1,0,0]
	v_mul_f32_e32 v4, v5, v5
	v_rcp_f32_e32 v8, v8
	v_rcp_f32_e32 v9, v9
	v_pk_add_f32 v[24:25], v[10:11], v[4:5]
	v_pk_mul_f32 v[10:11], v[6:7], v[6:7]
	v_cmp_gt_f32_e32 vcc, 0, v6
	v_pk_fma_f32 v[4:5], v[8:9], s[42:43], v[18:19] op_sel_hi:[1,0,0]
	v_pk_mul_f32 v[10:11], v[10:11], s[64:65] op_sel_hi:[1,0]
	v_pk_fma_f32 v[4:5], v[8:9], v[4:5], s[48:49] op_sel_hi:[1,1,0]
	v_exp_f32_e32 v10, v10
	v_exp_f32_e32 v11, v11
	v_pk_fma_f32 v[4:5], v[8:9], v[4:5], s[50:51] op_sel_hi:[1,1,0]
	v_pk_add_f32 v[22:23], v[24:25], v[22:23]
	v_pk_fma_f32 v[4:5], v[8:9], v[4:5], s[56:57] op_sel_hi:[1,1,0]
	s_nop 0
	v_pk_mul_f32 v[4:5], v[8:9], v[4:5]
	s_nop 0
	v_pk_mul_f32 v[4:5], v[10:11], v[4:5]
	global_load_dwordx4 v[8:11], v[20:21], off offset:1280
	s_waitcnt vmcnt(1)
	v_lshlrev_b32_e32 v32, 16, v12
	v_and_b32_e32 v33, 0xffff0000, v12
	v_fma_f32 v30, |v32|, s40, 1.0
	v_fma_f32 v31, |v33|, s40, 1.0
	v_pk_mul_f32 v[28:29], v[6:7], v[4:5]
	v_rcp_f32_e32 v30, v30
	v_rcp_f32_e32 v31, v31
	v_pk_fma_f32 v[4:5], v[6:7], v[4:5], v[6:7] neg_lo:[1,0,0] neg_hi:[1,0,0]
	v_lshlrev_b32_e32 v34, 16, v13
	v_cndmask_b32_e32 v27, v4, v28, vcc
	v_cmp_gt_f32_e32 vcc, 0, v7
	v_pk_mul_f32 v[6:7], v[32:33], v[32:33]
	v_and_b32_e32 v35, 0xffff0000, v13
	v_cndmask_b32_e32 v29, v5, v29, vcc
	v_pk_fma_f32 v[4:5], v[30:31], s[42:43], v[18:19] op_sel_hi:[1,0,0]
	v_pk_mul_f32 v[6:7], v[6:7], s[64:65] op_sel_hi:[1,0]
	v_pk_fma_f32 v[4:5], v[30:31], v[4:5], s[48:49] op_sel_hi:[1,1,0]
	v_exp_f32_e32 v6, v6
	v_exp_f32_e32 v7, v7
	v_pk_fma_f32 v[4:5], v[30:31], v[4:5], s[50:51] op_sel_hi:[1,1,0]
	v_pk_fma_f32 v[4:5], v[30:31], v[4:5], s[56:57] op_sel_hi:[1,1,0]
	v_fma_f32 v12, |v34|, s40, 1.0
	v_fma_f32 v13, |v35|, s40, 1.0
	v_pk_mul_f32 v[4:5], v[30:31], v[4:5]
	v_rcp_f32_e32 v36, v12
	v_rcp_f32_e32 v37, v13
	v_pk_mul_f32 v[4:5], v[6:7], v[4:5]
	v_cmp_gt_f32_e32 vcc, 0, v32
	v_pk_mul_f32 v[6:7], v[32:33], v[4:5]
	v_pk_fma_f32 v[4:5], v[32:33], v[4:5], v[32:33] neg_lo:[1,0,0] neg_hi:[1,0,0]
	v_lshlrev_b32_e32 v38, 16, v14
	v_cndmask_b32_e32 v31, v4, v6, vcc
	v_cmp_gt_f32_e32 vcc, 0, v33
	v_and_b32_e32 v39, 0xffff0000, v14
	v_lshlrev_b32_e32 v40, 16, v15
	v_cndmask_b32_e32 v13, v5, v7, vcc
	v_pk_fma_f32 v[4:5], v[36:37], s[42:43], v[18:19] op_sel_hi:[1,0,0]
	v_pk_mul_f32 v[6:7], v[34:35], v[34:35]
	v_pk_fma_f32 v[4:5], v[36:37], v[4:5], s[48:49] op_sel_hi:[1,1,0]
	v_pk_mul_f32 v[6:7], v[6:7], s[64:65] op_sel_hi:[1,0]
	v_pk_fma_f32 v[4:5], v[36:37], v[4:5], s[50:51] op_sel_hi:[1,1,0]
	v_exp_f32_e32 v6, v6
	v_exp_f32_e32 v7, v7
	v_pk_fma_f32 v[4:5], v[36:37], v[4:5], s[56:57] op_sel_hi:[1,1,0]
	v_cmp_gt_f32_e32 vcc, 0, v34
	v_pk_mul_f32 v[4:5], v[36:37], v[4:5]
	v_fma_f32 v36, |v38|, s40, 1.0
	v_fma_f32 v37, |v39|, s40, 1.0
	v_pk_mul_f32 v[4:5], v[6:7], v[4:5]
	v_rcp_f32_e32 v36, v36
	v_rcp_f32_e32 v37, v37
	v_pk_mul_f32 v[6:7], v[34:35], v[4:5]
	v_pk_fma_f32 v[4:5], v[34:35], v[4:5], v[34:35] neg_lo:[1,0,0] neg_hi:[1,0,0]
	v_and_b32_e32 v41, 0xffff0000, v15
	v_cndmask_b32_e32 v33, v4, v6, vcc
	v_cmp_gt_f32_e32 vcc, 0, v35
	v_cndmask_b32_e32 v35, v5, v7, vcc
	v_pk_mul_f32 v[6:7], v[38:39], v[38:39]
	v_pk_fma_f32 v[4:5], v[36:37], s[42:43], v[18:19] op_sel_hi:[1,0,0]
	v_pk_mul_f32 v[6:7], v[6:7], s[64:65] op_sel_hi:[1,0]
	v_pk_fma_f32 v[4:5], v[36:37], v[4:5], s[48:49] op_sel_hi:[1,1,0]
	v_exp_f32_e32 v6, v6
	v_exp_f32_e32 v7, v7
	v_pk_fma_f32 v[4:5], v[36:37], v[4:5], s[50:51] op_sel_hi:[1,1,0]
	v_fma_f32 v14, |v40|, s40, 1.0
	v_fma_f32 v15, |v41|, s40, 1.0
	v_pk_fma_f32 v[4:5], v[36:37], v[4:5], s[56:57] op_sel_hi:[1,1,0]
	v_rcp_f32_e32 v42, v14
	v_pk_mul_f32 v[4:5], v[36:37], v[4:5]
	v_rcp_f32_e32 v43, v15
	v_pk_mul_f32 v[4:5], v[6:7], v[4:5]
	v_cmp_gt_f32_e32 vcc, 0, v38
	v_pk_mul_f32 v[6:7], v[38:39], v[4:5]
	v_pk_fma_f32 v[4:5], v[38:39], v[4:5], v[38:39] neg_lo:[1,0,0] neg_hi:[1,0,0]
	v_mul_f32_e32 v26, v27, v27
	v_cndmask_b32_e32 v37, v4, v6, vcc
	v_cmp_gt_f32_e32 vcc, 0, v39
	s_waitcnt vmcnt(0)
	v_lshlrev_b32_e32 v44, 16, v8
	v_and_b32_e32 v45, 0xffff0000, v8
	v_cndmask_b32_e32 v15, v5, v7, vcc
	v_pk_fma_f32 v[4:5], v[42:43], s[42:43], v[18:19] op_sel_hi:[1,0,0]
	v_pk_mul_f32 v[6:7], v[40:41], v[40:41]
	v_pk_fma_f32 v[4:5], v[42:43], v[4:5], s[48:49] op_sel_hi:[1,1,0]
	v_pk_mul_f32 v[6:7], v[6:7], s[64:65] op_sel_hi:[1,0]
	v_pk_fma_f32 v[4:5], v[42:43], v[4:5], s[50:51] op_sel_hi:[1,1,0]
	v_exp_f32_e32 v6, v6
	v_exp_f32_e32 v7, v7
	v_pk_fma_f32 v[4:5], v[42:43], v[4:5], s[56:57] op_sel_hi:[1,1,0]
	v_cmp_gt_f32_e32 vcc, 0, v40
	v_pk_mul_f32 v[4:5], v[42:43], v[4:5]
	v_fma_f32 v42, |v44|, s40, 1.0
	v_fma_f32 v43, |v45|, s40, 1.0
	v_pk_mul_f32 v[4:5], v[6:7], v[4:5]
	v_rcp_f32_e32 v42, v42
	v_rcp_f32_e32 v43, v43
	v_pk_mul_f32 v[6:7], v[40:41], v[4:5]
	v_pk_fma_f32 v[4:5], v[40:41], v[4:5], v[40:41] neg_lo:[1,0,0] neg_hi:[1,0,0]
	v_lshlrev_b32_e32 v50, 16, v9
	v_cndmask_b32_e32 v39, v4, v6, vcc
	v_cmp_gt_f32_e32 vcc, 0, v41
	v_and_b32_e32 v51, 0xffff0000, v9
	v_cndmask_b32_e32 v41, v5, v7, vcc
	v_pk_mul_f32 v[6:7], v[44:45], v[44:45]
	v_pk_fma_f32 v[4:5], v[42:43], s[42:43], v[18:19] op_sel_hi:[1,0,0]
	v_pk_mul_f32 v[6:7], v[6:7], s[64:65] op_sel_hi:[1,0]
	v_pk_fma_f32 v[4:5], v[42:43], v[4:5], s[48:49] op_sel_hi:[1,1,0]
	v_exp_f32_e32 v6, v6
	v_exp_f32_e32 v7, v7
	v_pk_fma_f32 v[4:5], v[42:43], v[4:5], s[50:51] op_sel_hi:[1,1,0]
	v_pk_fma_f32 v[4:5], v[42:43], v[4:5], s[56:57] op_sel_hi:[1,1,0]
	v_fma_f32 v8, |v50|, s40, 1.0
	v_fma_f32 v9, |v51|, s40, 1.0
	v_pk_mul_f32 v[4:5], v[42:43], v[4:5]
	v_rcp_f32_e32 v52, v8
	v_pk_mul_f32 v[42:43], v[6:7], v[4:5]
	global_load_dwordx4 v[4:7], v[20:21], off offset:1536
	v_rcp_f32_e32 v53, v9
	v_max_f32_e32 v96, 0, v45
	v_fma_f32 v9, -|v45|, v43, v96
	v_max_f32_e32 v95, 0, v44
	v_fma_f32 v43, -|v44|, v42, v95
	v_lshlrev_b32_e32 v58, 16, v11
	v_and_b32_e32 v59, 0xffff0000, v11
	v_pk_fma_f32 v[44:45], v[52:53], s[42:43], v[18:19] op_sel_hi:[1,0,0]
	v_and_b32_e32 v11, 0x7fffffff, v59
	v_pk_fma_f32 v[44:45], v[52:53], v[44:45], s[48:49] op_sel_hi:[1,1,0]
	v_pk_mul_f32 v[46:47], v[50:51], v[50:51]
	v_pk_fma_f32 v[44:45], v[52:53], v[44:45], s[50:51] op_sel_hi:[1,1,0]
	v_pk_mul_f32 v[46:47], v[46:47], s[64:65] op_sel_hi:[1,0]
	v_pk_fma_f32 v[44:45], v[52:53], v[44:45], s[56:57] op_sel_hi:[1,1,0]
	v_exp_f32_e32 v46, v46
	v_exp_f32_e32 v47, v47
	v_pk_mul_f32 v[44:45], v[52:53], v[44:45]
	v_lshlrev_b32_e32 v52, 16, v10
	v_and_b32_e32 v53, 0xffff0000, v10
	v_fma_f32 v56, |v52|, s40, 1.0
	v_fma_f32 v57, |v53|, s40, 1.0
	v_pk_mul_f32 v[44:45], v[46:47], v[44:45]
	v_rcp_f32_e32 v56, v56
	v_rcp_f32_e32 v57, v57
	v_max_f32_e32 v98, 0, v51
	v_fma_f32 v47, -|v51|, v45, v98
	v_max_f32_e32 v97, 0, v50
	v_fma_f32 v45, -|v50|, v44, v97
	v_and_b32_e32 v10, 0x7fffffff, v58
	v_pk_fma_f32 v[10:11], v[10:11], s[40:41], 1.0 op_sel_hi:[1,0,0]
	v_pk_mul_f32 v[50:51], v[52:53], v[52:53]
	v_rcp_f32_e32 v60, v10
	v_pk_fma_f32 v[48:49], v[56:57], s[42:43], v[18:19] op_sel_hi:[1,0,0]
	v_pk_mul_f32 v[50:51], v[50:51], s[64:65] op_sel_hi:[1,0]
	v_pk_fma_f32 v[48:49], v[56:57], v[48:49], s[48:49] op_sel_hi:[1,1,0]
	v_exp_f32_e32 v50, v50
	v_exp_f32_e32 v51, v51
	v_pk_fma_f32 v[48:49], v[56:57], v[48:49], s[50:51] op_sel_hi:[1,1,0]
	v_rcp_f32_e32 v61, v11
	v_pk_fma_f32 v[48:49], v[56:57], v[48:49], s[56:57] op_sel_hi:[1,1,0]
	v_cmp_gt_f32_e32 vcc, 0, v52
	v_pk_mul_f32 v[48:49], v[56:57], v[48:49]
	v_mul_f32_e32 v28, v29, v29
	v_pk_mul_f32 v[48:49], v[50:51], v[48:49]
	v_mul_f32_e32 v30, v31, v31
	v_pk_mul_f32 v[50:51], v[52:53], v[48:49]
	v_pk_fma_f32 v[56:57], v[52:53], v[48:49], v[52:53] neg_lo:[1,0,0] neg_hi:[1,0,0]
	v_mul_f32_e32 v12, v13, v13
	v_cndmask_b32_e32 v49, v56, v50, vcc
	v_cmp_gt_f32_e32 vcc, 0, v53
	v_pk_mul_f32 v[52:53], v[58:59], v[58:59]
	v_pk_add_f32 v[24:25], v[26:27], v[28:29]
	v_cndmask_b32_e32 v11, v57, v51, vcc
	v_pk_fma_f32 v[50:51], v[60:61], s[42:43], v[18:19] op_sel_hi:[1,0,0]
	v_pk_mul_f32 v[52:53], v[52:53], s[64:65] op_sel_hi:[1,0]
	v_pk_fma_f32 v[50:51], v[60:61], v[50:51], s[48:49] op_sel_hi:[1,1,0]
	v_exp_f32_e32 v52, v52
	v_exp_f32_e32 v53, v53
	v_pk_fma_f32 v[50:51], v[60:61], v[50:51], s[50:51] op_sel_hi:[1,1,0]
	v_cmp_gt_f32_e32 vcc, 0, v58
	v_pk_fma_f32 v[50:51], v[60:61], v[50:51], s[56:57] op_sel_hi:[1,1,0]
	v_mul_f32_e32 v32, v33, v33
	v_pk_mul_f32 v[50:51], v[60:61], v[50:51]
	v_mul_f32_e32 v34, v35, v35
	v_pk_mul_f32 v[50:51], v[52:53], v[50:51]
	v_pk_add_f32 v[22:23], v[24:25], v[22:23]
	v_pk_mul_f32 v[56:57], v[58:59], v[50:51]
	v_pk_fma_f32 v[60:61], v[58:59], v[50:51], v[58:59] neg_lo:[1,0,0] neg_hi:[1,0,0]
	global_load_dwordx4 v[50:53], v[20:21], off offset:1792
	v_cndmask_b32_e32 v63, v60, v56, vcc
	v_cmp_gt_f32_e32 vcc, 0, v59
	v_pk_add_f32 v[12:13], v[30:31], v[12:13]
	v_mul_f32_e32 v36, v37, v37
	v_cndmask_b32_e32 v57, v61, v57, vcc
	s_waitcnt vmcnt(1)
	v_lshlrev_b32_e32 v20, 16, v4
	v_and_b32_e32 v21, 0xffff0000, v4
	v_fma_f32 v64, |v20|, s40, 1.0
	v_fma_f32 v65, |v21|, s40, 1.0
	v_pk_mul_f32 v[60:61], v[20:21], v[20:21]
	v_rcp_f32_e32 v64, v64
	v_rcp_f32_e32 v65, v65
	v_mul_f32_e32 v14, v15, v15
	v_pk_mul_f32 v[60:61], v[60:61], s[64:65] op_sel_hi:[1,0]
	v_pk_add_f32 v[12:13], v[12:13], v[22:23]
	v_pk_fma_f32 v[58:59], v[64:65], s[42:43], v[18:19] op_sel_hi:[1,0,0]
	v_pk_add_f32 v[22:23], v[32:33], v[34:35]
	v_mul_f32_e32 v38, v39, v39
	v_mul_f32_e32 v40, v41, v41
	v_pk_fma_f32 v[58:59], v[64:65], v[58:59], s[48:49] op_sel_hi:[1,1,0]
	v_exp_f32_e32 v60, v60
	v_exp_f32_e32 v61, v61
	v_pk_add_f32 v[12:13], v[22:23], v[12:13]
	v_pk_add_f32 v[14:15], v[36:37], v[14:15]
	v_mul_f32_e32 v42, v43, v43
	v_mul_f32_e32 v8, v9, v9
	v_pk_fma_f32 v[58:59], v[64:65], v[58:59], s[50:51] op_sel_hi:[1,1,0]
	v_pk_add_f32 v[12:13], v[14:15], v[12:13]
	v_pk_add_f32 v[14:15], v[38:39], v[40:41]
	v_mul_f32_e32 v44, v45, v45
	v_mul_f32_e32 v46, v47, v47
	v_pk_fma_f32 v[58:59], v[64:65], v[58:59], s[56:57] op_sel_hi:[1,1,0]
	v_pk_add_f32 v[12:13], v[14:15], v[12:13]
	v_pk_add_f32 v[8:9], v[42:43], v[8:9]
	v_pk_mul_f32 v[58:59], v[64:65], v[58:59]
	v_pk_add_f32 v[8:9], v[8:9], v[12:13]
	v_pk_add_f32 v[12:13], v[44:45], v[46:47]
	v_lshlrev_b32_e32 v4, 16, v5
	v_and_b32_e32 v5, 0xffff0000, v5
	v_pk_mul_f32 v[58:59], v[60:61], v[58:59]
	v_pk_add_f32 v[8:9], v[12:13], v[8:9]
	v_max_f32_e32 v99, 0, v20
	v_fma_f32 v65, -|v20|, v58, v99
	v_max_f32_e32 v100, 0, v21
	v_fma_f32 v21, -|v21|, v59, v100
	v_fma_f32 v12, |v4|, s40, 1.0
	v_fma_f32 v13, |v5|, s40, 1.0
	v_mul_f32_e32 v48, v49, v49
	v_mul_f32_e32 v10, v11, v11
	v_rcp_f32_e32 v12, v12
	v_rcp_f32_e32 v13, v13
	v_mul_f32_e32 v62, v63, v63
	v_mul_f32_e32 v56, v57, v57
	v_pk_add_f32 v[10:11], v[48:49], v[10:11]
	v_mul_f32_e32 v64, v65, v65
	v_mul_f32_e32 v20, v21, v21
	v_pk_add_f32 v[8:9], v[10:11], v[8:9]
	v_pk_add_f32 v[10:11], v[62:63], v[56:57]
	v_pk_mul_f32 v[14:15], v[4:5], v[4:5]
	v_pk_add_f32 v[8:9], v[10:11], v[8:9]
	v_pk_add_f32 v[10:11], v[64:65], v[20:21]
	v_pk_mul_f32 v[14:15], v[14:15], s[64:65] op_sel_hi:[1,0]
	v_pk_add_f32 v[8:9], v[10:11], v[8:9]
	v_pk_fma_f32 v[10:11], v[12:13], s[42:43], v[18:19] op_sel_hi:[1,0,0]
	v_exp_f32_e32 v14, v14
	v_pk_fma_f32 v[10:11], v[12:13], v[10:11], s[48:49] op_sel_hi:[1,1,0]
	v_exp_f32_e32 v15, v15
	v_pk_fma_f32 v[10:11], v[12:13], v[10:11], s[50:51] op_sel_hi:[1,1,0]
	v_cmp_gt_f32_e32 vcc, 0, v4
	v_pk_fma_f32 v[10:11], v[12:13], v[10:11], s[56:57] op_sel_hi:[1,1,0]
	s_waitcnt vmcnt(0)
	v_lshlrev_b32_e32 v24, 16, v50
	v_pk_mul_f32 v[10:11], v[12:13], v[10:11]
	v_and_b32_e32 v25, 0xffff0000, v50
	v_pk_mul_f32 v[10:11], v[14:15], v[10:11]
	v_and_b32_e32 v27, 0x7fffffff, v25
	v_pk_mul_f32 v[12:13], v[4:5], v[10:11]
	v_pk_fma_f32 v[10:11], v[4:5], v[10:11], v[4:5] neg_lo:[1,0,0] neg_hi:[1,0,0]
	v_and_b32_e32 v26, 0x7fffffff, v24
	v_cndmask_b32_e32 v15, v10, v12, vcc
	v_cmp_gt_f32_e32 vcc, 0, v5
	v_lshlrev_b32_e32 v10, 16, v6
	v_and_b32_e32 v12, 0x7fffffff, v10
	v_cndmask_b32_e32 v5, v11, v13, vcc
	v_and_b32_e32 v11, 0xffff0000, v6
	v_and_b32_e32 v13, 0x7fffffff, v11
	v_pk_fma_f32 v[12:13], v[12:13], s[40:41], 1.0 op_sel_hi:[1,0,0]
	v_mul_f32_e32 v14, v15, v15
	v_rcp_f32_e32 v12, v12
	v_rcp_f32_e32 v13, v13
	v_mul_f32_e32 v4, v5, v5
	v_pk_mul_f32 v[20:21], v[10:11], v[10:11]
	v_pk_add_f32 v[4:5], v[14:15], v[4:5]
	v_pk_fma_f32 v[14:15], v[12:13], s[42:43], v[18:19] op_sel_hi:[1,0,0]
	v_pk_mul_f32 v[20:21], v[20:21], s[64:65] op_sel_hi:[1,0]
	v_pk_fma_f32 v[14:15], v[12:13], v[14:15], s[48:49] op_sel_hi:[1,1,0]
	v_exp_f32_e32 v20, v20
	v_exp_f32_e32 v21, v21
	v_pk_fma_f32 v[14:15], v[12:13], v[14:15], s[50:51] op_sel_hi:[1,1,0]
	v_lshlrev_b32_e32 v6, 16, v7
	v_and_b32_e32 v7, 0xffff0000, v7
	v_pk_fma_f32 v[14:15], v[12:13], v[14:15], s[56:57] op_sel_hi:[1,1,0]
	v_pk_mul_f32 v[12:13], v[12:13], v[14:15]
	v_fma_f32 v22, |v6|, s40, 1.0
	v_fma_f32 v23, |v7|, s40, 1.0
	v_pk_mul_f32 v[12:13], v[20:21], v[12:13]
	v_rcp_f32_e32 v22, v22
	v_rcp_f32_e32 v23, v23
	v_max_f32_e32 v104, 0, v10
	v_fma_f32 v21, -|v10|, v12, v104
	v_max_f32_e32 v105, 0, v11
	v_fma_f32 v11, -|v11|, v13, v105
	v_pk_fma_f32 v[26:27], v[26:27], s[40:41], 1.0 op_sel_hi:[1,0,0]
	v_lshlrev_b32_e32 v28, 16, v51
	v_rcp_f32_e32 v26, v26
	v_rcp_f32_e32 v27, v27
	v_pk_mul_f32 v[14:15], v[6:7], v[6:7]
	v_pk_fma_f32 v[12:13], v[22:23], s[42:43], v[18:19] op_sel_hi:[1,0,0]
	v_pk_mul_f32 v[14:15], v[14:15], s[64:65] op_sel_hi:[1,0]
	v_pk_fma_f32 v[12:13], v[22:23], v[12:13], s[48:49] op_sel_hi:[1,1,0]
	v_exp_f32_e32 v14, v14
	v_exp_f32_e32 v15, v15
	v_pk_fma_f32 v[12:13], v[22:23], v[12:13], s[50:51] op_sel_hi:[1,1,0]
	v_cmp_gt_f32_e32 vcc, 0, v6
	v_pk_fma_f32 v[12:13], v[22:23], v[12:13], s[56:57] op_sel_hi:[1,1,0]
	v_and_b32_e32 v29, 0xffff0000, v51
	v_pk_mul_f32 v[12:13], v[22:23], v[12:13]
	v_pk_mul_f32 v[12:13], v[14:15], v[12:13]
	v_pk_mul_f32 v[14:15], v[6:7], v[12:13]
	v_pk_fma_f32 v[12:13], v[6:7], v[12:13], v[6:7] neg_lo:[1,0,0] neg_hi:[1,0,0]
	v_fma_f32 v30, |v28|, s40, 1.0
	v_fma_f32 v31, |v29|, s40, 1.0
	v_cndmask_b32_e32 v23, v12, v14, vcc
	v_cmp_gt_f32_e32 vcc, 0, v7
	v_rcp_f32_e32 v30, v30
	v_rcp_f32_e32 v31, v31
	v_cndmask_b32_e32 v7, v13, v15, vcc
	v_pk_mul_f32 v[14:15], v[24:25], v[24:25]
	v_pk_fma_f32 v[12:13], v[26:27], s[42:43], v[18:19] op_sel_hi:[1,0,0]
	v_pk_mul_f32 v[14:15], v[14:15], s[64:65] op_sel_hi:[1,0]
	v_pk_fma_f32 v[12:13], v[26:27], v[12:13], s[48:49] op_sel_hi:[1,1,0]
	v_exp_f32_e32 v14, v14
	v_exp_f32_e32 v15, v15
	v_pk_fma_f32 v[12:13], v[26:27], v[12:13], s[50:51] op_sel_hi:[1,1,0]
	v_cmp_gt_f32_e32 vcc, 0, v24
	v_pk_fma_f32 v[12:13], v[26:27], v[12:13], s[56:57] op_sel_hi:[1,1,0]
	v_lshlrev_b32_e32 v32, 16, v52
	v_pk_mul_f32 v[12:13], v[26:27], v[12:13]
	v_and_b32_e32 v33, 0xffff0000, v52
	v_pk_mul_f32 v[12:13], v[14:15], v[12:13]
	v_pk_mul_f32 v[14:15], v[24:25], v[12:13]
	v_pk_fma_f32 v[12:13], v[24:25], v[12:13], v[24:25] neg_lo:[1,0,0] neg_hi:[1,0,0]
	v_cndmask_b32_e32 v27, v12, v14, vcc
	v_cmp_gt_f32_e32 vcc, 0, v25
	v_pk_mul_f32 v[24:25], v[28:29], v[28:29]
	v_fma_f32 v34, |v32|, s40, 1.0
	v_fma_f32 v35, |v33|, s40, 1.0
	v_cndmask_b32_e32 v13, v13, v15, vcc
	v_pk_fma_f32 v[14:15], v[30:31], s[42:43], v[18:19] op_sel_hi:[1,0,0]
	v_pk_mul_f32 v[24:25], v[24:25], s[64:65] op_sel_hi:[1,0]
	v_pk_fma_f32 v[14:15], v[30:31], v[14:15], s[48:49] op_sel_hi:[1,1,0]
	v_exp_f32_e32 v24, v24
	v_exp_f32_e32 v25, v25
	v_pk_fma_f32 v[14:15], v[30:31], v[14:15], s[50:51] op_sel_hi:[1,1,0]
	v_rcp_f32_e32 v34, v34
	v_pk_fma_f32 v[14:15], v[30:31], v[14:15], s[56:57] op_sel_hi:[1,1,0]
	v_rcp_f32_e32 v35, v35
	v_pk_mul_f32 v[14:15], v[30:31], v[14:15]
	v_cmp_gt_f32_e32 vcc, 0, v28
	v_pk_mul_f32 v[14:15], v[24:25], v[14:15]
	v_lshlrev_b32_e32 v36, 16, v53
	v_pk_mul_f32 v[24:25], v[28:29], v[14:15]
	v_pk_fma_f32 v[14:15], v[28:29], v[14:15], v[28:29] neg_lo:[1,0,0] neg_hi:[1,0,0]
	v_and_b32_e32 v37, 0xffff0000, v53
	v_cndmask_b32_e32 v31, v14, v24, vcc
	v_cmp_gt_f32_e32 vcc, 0, v29
	v_pk_mul_f32 v[28:29], v[32:33], v[32:33]
	v_cndmask_b32_e32 v15, v15, v25, vcc
	v_pk_fma_f32 v[24:25], v[34:35], s[42:43], v[18:19] op_sel_hi:[1,0,0]
	v_pk_mul_f32 v[28:29], v[28:29], s[64:65] op_sel_hi:[1,0]
	v_pk_fma_f32 v[24:25], v[34:35], v[24:25], s[48:49] op_sel_hi:[1,1,0]
	v_exp_f32_e32 v28, v28
	v_exp_f32_e32 v29, v29
	v_pk_fma_f32 v[24:25], v[34:35], v[24:25], s[50:51] op_sel_hi:[1,1,0]
	v_pk_fma_f32 v[24:25], v[34:35], v[24:25], s[56:57] op_sel_hi:[1,1,0]
	v_fma_f32 v38, |v36|, s40, 1.0
	v_fma_f32 v39, |v37|, s40, 1.0
	v_pk_mul_f32 v[24:25], v[34:35], v[24:25]
	v_rcp_f32_e32 v38, v38
	v_pk_mul_f32 v[24:25], v[28:29], v[24:25]
	v_rcp_f32_e32 v39, v39
	v_max_f32_e32 v106, 0, v32
	v_fma_f32 v35, -|v32|, v24, v106
	v_max_f32_e32 v107, 0, v33
	v_fma_f32 v25, -|v33|, v25, v107
	v_pk_fma_f32 v[18:19], v[38:39], s[42:43], v[18:19] op_sel_hi:[1,0,0]
	v_mul_f32_e32 v20, v21, v21
	v_pk_fma_f32 v[18:19], v[38:39], v[18:19], s[48:49] op_sel_hi:[1,1,0]
	v_mul_f32_e32 v10, v11, v11
	v_pk_mul_f32 v[28:29], v[36:37], v[36:37]
	v_pk_fma_f32 v[18:19], v[38:39], v[18:19], s[50:51] op_sel_hi:[1,1,0]
	v_pk_mul_f32 v[28:29], v[28:29], s[64:65] op_sel_hi:[1,0]
	v_pk_fma_f32 v[18:19], v[38:39], v[18:19], s[56:57] op_sel_hi:[1,1,0]
	v_exp_f32_e32 v28, v28
	v_exp_f32_e32 v29, v29
	v_pk_mul_f32 v[18:19], v[38:39], v[18:19]
	v_mul_f32_e32 v22, v23, v23
	v_mul_f32_e32 v6, v7, v7
	v_pk_mul_f32 v[18:19], v[28:29], v[18:19]
	v_pk_add_f32 v[4:5], v[4:5], v[8:9]
	v_pk_add_f32 v[8:9], v[20:21], v[10:11]
	v_mul_f32_e32 v26, v27, v27
	v_mul_f32_e32 v12, v13, v13
	v_max_f32_e32 v108, 0, v36
	v_fma_f32 v33, -|v36|, v18, v108
	v_max_f32_e32 v109, 0, v37
	v_fma_f32 v19, -|v37|, v19, v109
	v_pk_add_f32 v[4:5], v[8:9], v[4:5]
	v_pk_add_f32 v[6:7], v[22:23], v[6:7]
	v_mul_f32_e32 v30, v31, v31
	v_mul_f32_e32 v14, v15, v15
	v_pk_add_f32 v[4:5], v[6:7], v[4:5]
	v_pk_add_f32 v[6:7], v[26:27], v[12:13]
	v_mul_f32_e32 v34, v35, v35
	v_mul_f32_e32 v24, v25, v25
	v_pk_add_f32 v[4:5], v[6:7], v[4:5]
	v_pk_add_f32 v[6:7], v[30:31], v[14:15]
	v_mul_f32_e32 v32, v33, v33
	v_mul_f32_e32 v18, v19, v19
	v_cmp_lt_i32_e32 vcc, v167, v161
	v_pk_add_f32 v[4:5], v[6:7], v[4:5]
	v_pk_add_f32 v[6:7], v[34:35], v[24:25]
	v_cndmask_b32_e32 v17, v160, v167, vcc
	v_pk_add_f32 v[4:5], v[6:7], v[4:5]
	v_pk_add_f32 v[6:7], v[32:33], v[18:19]
	v_lshlrev_b32_e32 v56, 2, v17
	v_pk_add_f32 v[4:5], v[6:7], v[4:5]
	ds_bpermute_b32 v7, v56, v5
	ds_bpermute_b32 v6, v56, v4
	v_cmp_lt_i32_e32 vcc, v166, v161
	s_waitcnt lgkmcnt(0)
	v_pk_add_f32 v[4:5], v[4:5], v[6:7]
	v_cndmask_b32_e32 v8, v160, v166, vcc
	v_lshlrev_b32_e32 v57, 2, v8
	ds_bpermute_b32 v7, v57, v5
	ds_bpermute_b32 v6, v57, v4
	v_cmp_lt_i32_e32 vcc, v165, v161
	s_waitcnt lgkmcnt(0)
	v_pk_add_f32 v[4:5], v[4:5], v[6:7]
	v_cndmask_b32_e32 v8, v160, v165, vcc
	v_lshlrev_b32_e32 v58, 2, v8
	ds_bpermute_b32 v7, v58, v5
	ds_bpermute_b32 v6, v58, v4
	v_cmp_lt_i32_e32 vcc, v164, v161
	s_waitcnt lgkmcnt(0)
	v_pk_add_f32 v[4:5], v[4:5], v[6:7]
	v_cndmask_b32_e32 v6, v160, v164, vcc
	v_lshlrev_b32_e32 v59, 2, v6
	ds_bpermute_b32 v7, v59, v5
	ds_bpermute_b32 v6, v59, v4
	v_cmp_eq_u32_e32 vcc, 0, v54
	s_and_saveexec_b64 s[8:9], vcc
	s_cbranch_execz .LBB0_445
	s_waitcnt lgkmcnt(0)
	v_pk_add_f32 v[4:5], v[4:5], v[6:7]
	s_nop 0
	v_pk_mul_f32 v[4:5], v[4:5], s[66:67] op_sel_hi:[1,0]
	s_nop 0
	v_fma_f32 v4, -v5, v5, v4
	v_max_f32_e32 v4, 0, v4
	v_add_f32_e32 v4, 0x358637bd, v4
	v_mul_f32_e32 v6, 0x4b800000, v4
	v_cmp_gt_f32_e64 s[0:1], s36, v4
	s_nop 1
	v_cndmask_b32_e64 v4, v4, v6, s[0:1]
	v_rsq_f32_e32 v4, v4
	v_lshl_add_u32 v6, v16, 2, 0
	v_add_u32_e32 v7, 0x11000, v6
	ds_write_b32 v7, v5
	v_mul_f32_e32 v5, 0x45800000, v4
	v_cndmask_b32_e64 v4, v4, v5, s[0:1]
	v_add_u32_e32 v5, 0x11200, v6
	ds_write_b32 v5, v4
.LBB0_445:
	s_or_b64 exec, exec, s[8:9]
	v_or_b32_e32 v20, 4, v16
	v_ashrrev_i32_e32 v21, 31, v20
	v_lshl_add_u64 v[4:5], s[6:7], 0, v[20:21]
	s_waitcnt lgkmcnt(0)
	v_lshlrev_b32_e32 v6, 3, v54
	v_lshlrev_b64 v[4:5], 11, v[4:5]
	v_lshl_add_u64 v[4:5], s[4:5], 0, v[4:5]
	v_lshlrev_b32_e32 v18, 1, v6
	v_mov_b32_e32 v19, v2
	v_lshl_add_u64 v[24:25], v[4:5], 0, v[18:19]
	global_load_dwordx4 v[8:11], v[24:25], off
	global_load_dwordx4 v[4:7], v[24:25], off offset:256
	v_mov_b64_e32 v[22:23], s[44:45]
	v_mov_b32_e32 v13, v2
	s_waitcnt vmcnt(1)
	v_lshlrev_b32_e32 v28, 16, v10
	v_and_b32_e32 v29, 0xffff0000, v10
	v_and_b32_e32 v15, 0xffff0000, v8
	v_and_b32_e32 v27, 0xffff0000, v9
	v_lshlrev_b32_e32 v26, 16, v9
	v_lshlrev_b32_e32 v14, 16, v8
	v_lshlrev_b32_e32 v8, 16, v11
	v_and_b32_e32 v9, 0xffff0000, v11
	v_fma_f32 v10, |v28|, s40, 1.0
	v_fma_f32 v11, |v29|, s40, 1.0
	v_fma_f32 v32, |v14|, s40, 1.0
	v_fma_f32 v33, |v15|, s40, 1.0
	v_rcp_f32_e32 v10, v10
	v_rcp_f32_e32 v11, v11
	v_fma_f32 v36, |v26|, s40, 1.0
	v_fma_f32 v37, |v27|, s40, 1.0
	v_rcp_f32_e32 v32, v32
	v_rcp_f32_e32 v33, v33
	v_rcp_f32_e32 v36, v36
	v_rcp_f32_e32 v37, v37
	v_pk_mul_f32 v[30:31], v[28:29], v[28:29]
	v_pk_mul_f32 v[34:35], v[14:15], v[14:15]
	v_pk_mul_f32 v[30:31], v[30:31], s[64:65] op_sel_hi:[1,0]
	v_pk_fma_f32 v[44:45], v[10:11], s[42:43], v[22:23] op_sel_hi:[1,0,0]
	v_pk_mul_f32 v[38:39], v[26:27], v[26:27]
	v_pk_mul_f32 v[34:35], v[34:35], s[64:65] op_sel_hi:[1,0]
	v_exp_f32_e32 v30, v30
	v_exp_f32_e32 v31, v31
	v_pk_fma_f32 v[46:47], v[32:33], s[42:43], v[22:23] op_sel_hi:[1,0,0]
	v_pk_fma_f32 v[44:45], v[10:11], v[44:45], s[48:49] op_sel_hi:[1,1,0]
	v_pk_mul_f32 v[38:39], v[38:39], s[64:65] op_sel_hi:[1,0]
	v_exp_f32_e32 v34, v34
	v_exp_f32_e32 v35, v35
	v_pk_fma_f32 v[48:49], v[36:37], s[42:43], v[22:23] op_sel_hi:[1,0,0]
	v_pk_fma_f32 v[46:47], v[32:33], v[46:47], s[48:49] op_sel_hi:[1,1,0]
	v_pk_fma_f32 v[44:45], v[10:11], v[44:45], s[50:51] op_sel_hi:[1,1,0]
	v_exp_f32_e32 v38, v38
	v_exp_f32_e32 v39, v39
	v_pk_fma_f32 v[48:49], v[36:37], v[48:49], s[48:49] op_sel_hi:[1,1,0]
	v_pk_fma_f32 v[46:47], v[32:33], v[46:47], s[50:51] op_sel_hi:[1,1,0]
	v_pk_fma_f32 v[44:45], v[10:11], v[44:45], s[56:57] op_sel_hi:[1,1,0]
	v_pk_fma_f32 v[48:49], v[36:37], v[48:49], s[50:51] op_sel_hi:[1,1,0]
	v_pk_fma_f32 v[46:47], v[32:33], v[46:47], s[56:57] op_sel_hi:[1,1,0]
	v_pk_mul_f32 v[10:11], v[10:11], v[44:45]
	v_pk_fma_f32 v[48:49], v[36:37], v[48:49], s[56:57] op_sel_hi:[1,1,0]
	v_pk_mul_f32 v[32:33], v[32:33], v[46:47]
	v_pk_mul_f32 v[10:11], v[30:31], v[10:11]
	v_pk_mul_f32 v[36:37], v[36:37], v[48:49]
	v_pk_mul_f32 v[30:31], v[34:35], v[32:33]
	v_max_f32_e32 v110, 0, v28
	v_fma_f32 v45, -|v28|, v10, v110
	v_max_f32_e32 v111, 0, v29
	v_fma_f32 v11, -|v29|, v11, v111
	v_pk_mul_f32 v[32:33], v[38:39], v[36:37]
	v_pk_mul_f32 v[36:37], v[30:31], v[14:15]
	v_max_f32_e32 v112, 0, v26
	v_fma_f32 v29, -|v26|, v32, v112
	v_max_f32_e32 v113, 0, v27
	v_fma_f32 v27, -|v27|, v33, v113
	v_pk_fma_f32 v[30:31], v[30:31], v[14:15], v[14:15] neg_lo:[1,0,0] neg_hi:[1,0,0]
	v_cmp_gt_f32_e64 s[0:1], 0, v14
	v_fma_f32 v40, |v8|, s40, 1.0
	v_fma_f32 v41, |v9|, s40, 1.0
	v_cndmask_b32_e64 v28, v30, v36, s[0:1]
	v_cmp_gt_f32_e64 s[0:1], 0, v15
	v_mul_f32_e32 v30, v28, v28
	v_mov_b32_e32 v14, v29
	v_cndmask_b32_e64 v15, v31, v37, s[0:1]
	v_mov_b32_e32 v31, v29
	v_mul_f32_e32 v26, v15, v15
	v_rcp_f32_e32 v40, v40
	v_rcp_f32_e32 v41, v41
	v_mul_f32_e32 v12, v27, v27
	v_pk_add_f32 v[26:27], v[30:31], v[26:27]
	v_pk_mul_f32 v[30:31], v[28:29], v[14:15] op_sel:[1,0] op_sel_hi:[0,1]
	v_pk_add_f32 v[14:15], v[28:29], v[14:15] op_sel:[1,0] op_sel_hi:[0,1]
	v_mov_b32_e32 v31, v15
	v_mul_f32_e32 v44, v45, v45
	v_mul_f32_e32 v10, v11, v11
	v_pk_add_f32 v[12:13], v[30:31], v[12:13]
	v_pk_mul_f32 v[42:43], v[8:9], v[8:9]
	v_pk_add_f32 v[10:11], v[44:45], v[10:11]
	v_pk_add_f32 v[12:13], v[26:27], v[12:13]
	v_pk_fma_f32 v[50:51], v[40:41], s[42:43], v[22:23] op_sel_hi:[1,0,0]
	v_pk_add_f32 v[26:27], v[10:11], v[12:13]
	v_pk_mul_f32 v[10:11], v[42:43], s[64:65] op_sel_hi:[1,0]
	v_pk_fma_f32 v[50:51], v[40:41], v[50:51], s[48:49] op_sel_hi:[1,1,0]
	v_exp_f32_e32 v10, v10
	v_exp_f32_e32 v11, v11
	v_pk_fma_f32 v[12:13], v[40:41], v[50:51], s[50:51] op_sel_hi:[1,1,0]
	v_cmp_gt_f32_e64 s[0:1], 0, v8
	v_pk_fma_f32 v[12:13], v[40:41], v[12:13], s[56:57] op_sel_hi:[1,1,0]
	s_nop 0
	v_pk_mul_f32 v[12:13], v[40:41], v[12:13]
	s_waitcnt vmcnt(0)
	v_lshlrev_b32_e32 v40, 16, v6
	v_pk_mul_f32 v[10:11], v[10:11], v[12:13]
	v_and_b32_e32 v41, 0xffff0000, v6
	v_pk_mul_f32 v[12:13], v[8:9], v[10:11]
	v_pk_fma_f32 v[10:11], v[8:9], v[10:11], v[8:9] neg_lo:[1,0,0] neg_hi:[1,0,0]
	v_and_b32_e32 v37, 0x7fffffff, v41
	v_cndmask_b32_e64 v15, v10, v12, s[0:1]
	v_cmp_gt_f32_e64 s[0:1], 0, v9
	v_lshlrev_b32_e32 v12, 16, v4
	v_and_b32_e32 v10, 0x7fffffff, v12
	v_cndmask_b32_e64 v9, v11, v13, s[0:1]
	v_and_b32_e32 v13, 0xffff0000, v4
	v_and_b32_e32 v11, 0x7fffffff, v13
	v_pk_fma_f32 v[10:11], v[10:11], s[40:41], 1.0 op_sel_hi:[1,0,0]
	v_mul_f32_e32 v14, v15, v15
	v_rcp_f32_e32 v10, v10
	v_rcp_f32_e32 v11, v11
	v_mul_f32_e32 v8, v9, v9
	v_pk_add_f32 v[28:29], v[14:15], v[8:9]
	v_pk_mul_f32 v[14:15], v[12:13], v[12:13]
	v_pk_fma_f32 v[8:9], v[10:11], s[42:43], v[22:23] op_sel_hi:[1,0,0]
	v_pk_mul_f32 v[14:15], v[14:15], s[64:65] op_sel_hi:[1,0]
	v_pk_fma_f32 v[8:9], v[10:11], v[8:9], s[48:49] op_sel_hi:[1,1,0]
	v_exp_f32_e32 v14, v14
	v_exp_f32_e32 v15, v15
	v_pk_fma_f32 v[8:9], v[10:11], v[8:9], s[50:51] op_sel_hi:[1,1,0]
	v_lshlrev_b32_e32 v4, 16, v5
	v_pk_fma_f32 v[8:9], v[10:11], v[8:9], s[56:57] op_sel_hi:[1,1,0]
	v_and_b32_e32 v5, 0xffff0000, v5
	v_pk_mul_f32 v[8:9], v[10:11], v[8:9]
	v_pk_mul_f32 v[14:15], v[14:15], v[8:9]
	global_load_dwordx4 v[8:11], v[24:25], off offset:512
	v_fma_f32 v34, |v4|, s40, 1.0
	v_fma_f32 v35, |v5|, s40, 1.0
	v_rcp_f32_e32 v34, v34
	v_rcp_f32_e32 v35, v35
	v_max_f32_e32 v114, 0, v12
	v_fma_f32 v31, -|v12|, v14, v114
	v_max_f32_e32 v115, 0, v13
	v_fma_f32 v33, -|v13|, v15, v115
	v_and_b32_e32 v36, 0x7fffffff, v40
	v_pk_fma_f32 v[36:37], v[36:37], s[40:41], 1.0 op_sel_hi:[1,0,0]
	v_pk_fma_f32 v[12:13], v[34:35], s[42:43], v[22:23] op_sel_hi:[1,0,0]
	v_rcp_f32_e32 v38, v36
	v_pk_mul_f32 v[14:15], v[4:5], v[4:5]
	v_pk_fma_f32 v[12:13], v[34:35], v[12:13], s[48:49] op_sel_hi:[1,1,0]
	v_pk_mul_f32 v[14:15], v[14:15], s[64:65] op_sel_hi:[1,0]
	v_pk_fma_f32 v[12:13], v[34:35], v[12:13], s[50:51] op_sel_hi:[1,1,0]
	v_exp_f32_e32 v14, v14
	v_exp_f32_e32 v15, v15
	v_pk_fma_f32 v[12:13], v[34:35], v[12:13], s[56:57] op_sel_hi:[1,1,0]
	v_rcp_f32_e32 v39, v37
	v_pk_mul_f32 v[12:13], v[34:35], v[12:13]
	v_cmp_gt_f32_e64 s[0:1], 0, v4
	v_pk_mul_f32 v[12:13], v[14:15], v[12:13]
	v_mul_f32_e32 v30, v31, v31
	v_pk_mul_f32 v[14:15], v[4:5], v[12:13]
	v_pk_fma_f32 v[12:13], v[4:5], v[12:13], v[4:5] neg_lo:[1,0,0] neg_hi:[1,0,0]
	v_mul_f32_e32 v32, v33, v33
	v_cndmask_b32_e64 v35, v12, v14, s[0:1]
	v_cmp_gt_f32_e64 s[0:1], 0, v5
	v_pk_fma_f32 v[4:5], v[38:39], s[42:43], v[22:23] op_sel_hi:[1,0,0]
	v_lshlrev_b32_e32 v14, 16, v7
	v_cndmask_b32_e64 v37, v13, v15, s[0:1]
	v_pk_mul_f32 v[12:13], v[40:41], v[40:41]
	v_pk_fma_f32 v[4:5], v[38:39], v[4:5], s[48:49] op_sel_hi:[1,1,0]
	v_pk_mul_f32 v[12:13], v[12:13], s[64:65] op_sel_hi:[1,0]
	v_pk_fma_f32 v[4:5], v[38:39], v[4:5], s[50:51] op_sel_hi:[1,1,0]
	v_exp_f32_e32 v12, v12
	v_exp_f32_e32 v13, v13
	v_and_b32_e32 v15, 0xffff0000, v7
	v_pk_fma_f32 v[4:5], v[38:39], v[4:5], s[56:57] op_sel_hi:[1,1,0]
	v_pk_mul_f32 v[4:5], v[38:39], v[4:5]
	v_fma_f32 v6, |v14|, s40, 1.0
	v_fma_f32 v7, |v15|, s40, 1.0
	v_pk_mul_f32 v[4:5], v[12:13], v[4:5]
	v_rcp_f32_e32 v6, v6
	v_rcp_f32_e32 v7, v7
	v_max_f32_e32 v116, 0, v40
	v_fma_f32 v39, -|v40|, v4, v116
	v_max_f32_e32 v117, 0, v41
	v_fma_f32 v41, -|v41|, v5, v117
	v_mul_f32_e32 v34, v35, v35
	v_mul_f32_e32 v36, v37, v37
	v_pk_add_f32 v[26:27], v[28:29], v[26:27]
	v_pk_add_f32 v[28:29], v[30:31], v[32:33]
	v_pk_mul_f32 v[12:13], v[14:15], v[14:15]
	v_pk_fma_f32 v[4:5], v[6:7], s[42:43], v[22:23] op_sel_hi:[1,0,0]
	v_pk_mul_f32 v[12:13], v[12:13], s[64:65] op_sel_hi:[1,0]
	v_pk_fma_f32 v[4:5], v[6:7], v[4:5], s[48:49] op_sel_hi:[1,1,0]
	v_exp_f32_e32 v12, v12
	v_exp_f32_e32 v13, v13
	v_pk_fma_f32 v[4:5], v[6:7], v[4:5], s[50:51] op_sel_hi:[1,1,0]
	v_cmp_gt_f32_e64 s[0:1], 0, v14
	v_pk_fma_f32 v[4:5], v[6:7], v[4:5], s[56:57] op_sel_hi:[1,1,0]
	v_mul_f32_e32 v38, v39, v39
	v_pk_mul_f32 v[4:5], v[6:7], v[4:5]
	v_mul_f32_e32 v40, v41, v41
	v_pk_mul_f32 v[4:5], v[12:13], v[4:5]
	v_pk_add_f32 v[26:27], v[28:29], v[26:27]
	v_pk_mul_f32 v[12:13], v[14:15], v[4:5]
	v_pk_fma_f32 v[44:45], v[14:15], v[4:5], v[14:15] neg_lo:[1,0,0] neg_hi:[1,0,0]
	global_load_dwordx4 v[4:7], v[24:25], off offset:768
	v_cndmask_b32_e64 v43, v44, v12, s[0:1]
	v_cmp_gt_f32_e64 s[0:1], 0, v15
	v_pk_add_f32 v[28:29], v[34:35], v[36:37]
	s_waitcnt vmcnt(1)
	v_lshlrev_b32_e32 v48, 16, v8
	v_and_b32_e32 v49, 0xffff0000, v8
	v_fma_f32 v46, |v48|, s40, 1.0
	v_fma_f32 v47, |v49|, s40, 1.0
	v_pk_mul_f32 v[14:15], v[48:49], v[48:49]
	v_rcp_f32_e32 v46, v46
	v_rcp_f32_e32 v47, v47
	v_cndmask_b32_e64 v45, v45, v13, s[0:1]
	v_pk_mul_f32 v[14:15], v[14:15], s[64:65] op_sel_hi:[1,0]
	v_lshlrev_b32_e32 v50, 16, v9
	v_pk_fma_f32 v[12:13], v[46:47], s[42:43], v[22:23] op_sel_hi:[1,0,0]
	v_exp_f32_e32 v14, v14
	v_pk_fma_f32 v[12:13], v[46:47], v[12:13], s[48:49] op_sel_hi:[1,1,0]
	v_exp_f32_e32 v15, v15
	v_and_b32_e32 v51, 0xffff0000, v9
	v_pk_fma_f32 v[12:13], v[46:47], v[12:13], s[50:51] op_sel_hi:[1,1,0]
	v_pk_fma_f32 v[12:13], v[46:47], v[12:13], s[56:57] op_sel_hi:[1,1,0]
	v_fma_f32 v8, |v50|, s40, 1.0
	v_fma_f32 v9, |v51|, s40, 1.0
	v_pk_mul_f32 v[12:13], v[46:47], v[12:13]
	v_rcp_f32_e32 v52, v8
	v_rcp_f32_e32 v53, v9
	v_pk_mul_f32 v[12:13], v[14:15], v[12:13]
	v_cmp_gt_f32_e64 s[0:1], 0, v48
	v_pk_mul_f32 v[14:15], v[48:49], v[12:13]
	v_pk_fma_f32 v[12:13], v[48:49], v[12:13], v[48:49] neg_lo:[1,0,0] neg_hi:[1,0,0]
	v_lshlrev_b32_e32 v60, 16, v10
	v_cndmask_b32_e64 v47, v12, v14, s[0:1]
	v_cmp_gt_f32_e64 s[0:1], 0, v49
	v_and_b32_e32 v61, 0xffff0000, v10
	v_lshlrev_b32_e32 v10, 16, v11
	v_cndmask_b32_e64 v9, v13, v15, s[0:1]
	v_pk_fma_f32 v[12:13], v[52:53], s[42:43], v[22:23] op_sel_hi:[1,0,0]
	v_pk_mul_f32 v[14:15], v[50:51], v[50:51]
	v_pk_fma_f32 v[12:13], v[52:53], v[12:13], s[48:49] op_sel_hi:[1,1,0]
	v_pk_mul_f32 v[14:15], v[14:15], s[64:65] op_sel_hi:[1,0]
	v_pk_fma_f32 v[12:13], v[52:53], v[12:13], s[50:51] op_sel_hi:[1,1,0]
	v_exp_f32_e32 v14, v14
	v_exp_f32_e32 v15, v15
	v_pk_fma_f32 v[12:13], v[52:53], v[12:13], s[56:57] op_sel_hi:[1,1,0]
	v_cmp_gt_f32_e64 s[0:1], 0, v50
	v_pk_mul_f32 v[12:13], v[52:53], v[12:13]
	v_fma_f32 v52, |v60|, s40, 1.0
	v_fma_f32 v53, |v61|, s40, 1.0
	v_pk_mul_f32 v[12:13], v[14:15], v[12:13]
	v_rcp_f32_e32 v52, v52
	v_rcp_f32_e32 v53, v53
	v_pk_mul_f32 v[14:15], v[50:51], v[12:13]
	v_pk_fma_f32 v[12:13], v[50:51], v[12:13], v[50:51] neg_lo:[1,0,0] neg_hi:[1,0,0]
	v_and_b32_e32 v11, 0xffff0000, v11
	v_cndmask_b32_e64 v49, v12, v14, s[0:1]
	v_cmp_gt_f32_e64 s[0:1], 0, v51
	v_cndmask_b32_e64 v51, v13, v15, s[0:1]
	v_pk_mul_f32 v[14:15], v[60:61], v[60:61]
	v_pk_fma_f32 v[12:13], v[52:53], s[42:43], v[22:23] op_sel_hi:[1,0,0]
	v_pk_mul_f32 v[14:15], v[14:15], s[64:65] op_sel_hi:[1,0]
	v_pk_fma_f32 v[12:13], v[52:53], v[12:13], s[48:49] op_sel_hi:[1,1,0]
	v_exp_f32_e32 v14, v14
	v_exp_f32_e32 v15, v15
	v_pk_fma_f32 v[12:13], v[52:53], v[12:13], s[50:51] op_sel_hi:[1,1,0]
	v_fma_f32 v62, |v10|, s40, 1.0
	v_fma_f32 v63, |v11|, s40, 1.0
	v_pk_fma_f32 v[12:13], v[52:53], v[12:13], s[56:57] op_sel_hi:[1,1,0]
	v_rcp_f32_e32 v62, v62
	v_pk_mul_f32 v[12:13], v[52:53], v[12:13]
	v_rcp_f32_e32 v63, v63
	v_pk_mul_f32 v[12:13], v[14:15], v[12:13]
	v_cmp_gt_f32_e64 s[0:1], 0, v60
	v_pk_mul_f32 v[14:15], v[60:61], v[12:13]
	v_pk_fma_f32 v[12:13], v[60:61], v[12:13], v[60:61] neg_lo:[1,0,0] neg_hi:[1,0,0]
	v_mul_f32_e32 v42, v43, v43
	v_cndmask_b32_e64 v53, v12, v14, s[0:1]
	v_cmp_gt_f32_e64 s[0:1], 0, v61
	s_waitcnt vmcnt(0)
	v_lshlrev_b32_e32 v64, 16, v4
	v_and_b32_e32 v65, 0xffff0000, v4
	v_cndmask_b32_e64 v61, v13, v15, s[0:1]
	v_pk_mul_f32 v[14:15], v[10:11], v[10:11]
	v_pk_fma_f32 v[12:13], v[62:63], s[42:43], v[22:23] op_sel_hi:[1,0,0]
	v_pk_mul_f32 v[14:15], v[14:15], s[64:65] op_sel_hi:[1,0]
	v_pk_fma_f32 v[12:13], v[62:63], v[12:13], s[48:49] op_sel_hi:[1,1,0]
	v_exp_f32_e32 v14, v14
	v_exp_f32_e32 v15, v15
	v_pk_fma_f32 v[12:13], v[62:63], v[12:13], s[50:51] op_sel_hi:[1,1,0]
	v_pk_fma_f32 v[12:13], v[62:63], v[12:13], s[56:57] op_sel_hi:[1,1,0]
	v_pk_mul_f32 v[12:13], v[62:63], v[12:13]
	v_fma_f32 v66, |v64|, s40, 1.0
	v_fma_f32 v67, |v65|, s40, 1.0
	v_pk_mul_f32 v[12:13], v[14:15], v[12:13]
	v_rcp_f32_e32 v66, v66
	v_rcp_f32_e32 v67, v67
	v_max_f32_e32 v80, 0, v10
	v_fma_f32 v63, -|v10|, v12, v80
	v_max_f32_e32 v81, 0, v11
	v_fma_f32 v11, -|v11|, v13, v81
	v_lshlrev_b32_e32 v4, 16, v5
	v_and_b32_e32 v5, 0xffff0000, v5
	v_pk_mul_f32 v[14:15], v[64:65], v[64:65]
	v_pk_fma_f32 v[12:13], v[66:67], s[42:43], v[22:23] op_sel_hi:[1,0,0]
	v_pk_mul_f32 v[14:15], v[14:15], s[64:65] op_sel_hi:[1,0]
	v_pk_fma_f32 v[12:13], v[66:67], v[12:13], s[48:49] op_sel_hi:[1,1,0]
	v_exp_f32_e32 v14, v14
	v_exp_f32_e32 v15, v15
	v_pk_fma_f32 v[12:13], v[66:67], v[12:13], s[50:51] op_sel_hi:[1,1,0]
	v_fma_f32 v68, |v4|, s40, 1.0
	v_fma_f32 v69, |v5|, s40, 1.0
	v_pk_fma_f32 v[12:13], v[66:67], v[12:13], s[56:57] op_sel_hi:[1,1,0]
	v_rcp_f32_e32 v68, v68
	v_pk_mul_f32 v[12:13], v[66:67], v[12:13]
	v_rcp_f32_e32 v69, v69
	v_pk_mul_f32 v[12:13], v[14:15], v[12:13]
	v_cmp_gt_f32_e64 s[0:1], 0, v64
	v_pk_mul_f32 v[14:15], v[64:65], v[12:13]
	v_pk_fma_f32 v[12:13], v[64:65], v[12:13], v[64:65] neg_lo:[1,0,0] neg_hi:[1,0,0]
	v_mul_f32_e32 v44, v45, v45
	v_cndmask_b32_e64 v67, v12, v14, s[0:1]
	v_cmp_gt_f32_e64 s[0:1], 0, v65
	v_pk_add_f32 v[26:27], v[28:29], v[26:27]
	v_pk_add_f32 v[28:29], v[38:39], v[40:41]
	v_cndmask_b32_e64 v65, v13, v15, s[0:1]
	v_pk_fma_f32 v[12:13], v[68:69], s[42:43], v[22:23] op_sel_hi:[1,0,0]
	v_pk_mul_f32 v[14:15], v[4:5], v[4:5]
	v_pk_fma_f32 v[12:13], v[68:69], v[12:13], s[48:49] op_sel_hi:[1,1,0]
	v_pk_mul_f32 v[14:15], v[14:15], s[64:65] op_sel_hi:[1,0]
	v_pk_fma_f32 v[12:13], v[68:69], v[12:13], s[50:51] op_sel_hi:[1,1,0]
	v_exp_f32_e32 v70, v14
	v_exp_f32_e32 v71, v15
	v_pk_fma_f32 v[72:73], v[68:69], v[12:13], s[56:57] op_sel_hi:[1,1,0]
	global_load_dwordx4 v[12:15], v[24:25], off offset:1024
	v_mul_f32_e32 v46, v47, v47
	v_mul_f32_e32 v8, v9, v9
	v_pk_add_f32 v[26:27], v[28:29], v[26:27]
	v_pk_add_f32 v[28:29], v[42:43], v[44:45]
	v_mul_f32_e32 v48, v49, v49
	v_mul_f32_e32 v50, v51, v51
	v_pk_add_f32 v[26:27], v[28:29], v[26:27]
	v_pk_add_f32 v[8:9], v[46:47], v[8:9]
	v_mul_f32_e32 v52, v53, v53
	v_mul_f32_e32 v60, v61, v61
	v_pk_mul_f32 v[68:69], v[68:69], v[72:73]
	v_pk_add_f32 v[8:9], v[8:9], v[26:27]
	v_pk_add_f32 v[26:27], v[48:49], v[50:51]
	v_pk_mul_f32 v[68:69], v[70:71], v[68:69]
	v_pk_add_f32 v[8:9], v[26:27], v[8:9]
	v_pk_add_f32 v[26:27], v[52:53], v[60:61]
	v_lshlrev_b32_e32 v28, 16, v6
	v_and_b32_e32 v29, 0xffff0000, v6
	v_max_f32_e32 v82, 0, v4
	v_fma_f32 v73, -|v4|, v68, v82
	v_max_f32_e32 v83, 0, v5
	v_fma_f32 v5, -|v5|, v69, v83
	v_pk_add_f32 v[8:9], v[26:27], v[8:9]
	v_mul_f32_e32 v62, v63, v63
	v_mul_f32_e32 v10, v11, v11
	v_fma_f32 v26, |v28|, s40, 1.0
	v_fma_f32 v27, |v29|, s40, 1.0
	v_mul_f32_e32 v66, v67, v67
	v_mul_f32_e32 v64, v65, v65
	v_pk_add_f32 v[10:11], v[62:63], v[10:11]
	v_rcp_f32_e32 v30, v26
	v_rcp_f32_e32 v31, v27
	v_mul_f32_e32 v72, v73, v73
	v_mul_f32_e32 v4, v5, v5
	v_pk_add_f32 v[8:9], v[10:11], v[8:9]
	v_pk_add_f32 v[10:11], v[66:67], v[64:65]
	v_pk_add_f32 v[4:5], v[72:73], v[4:5]
	v_pk_add_f32 v[8:9], v[10:11], v[8:9]
	v_cmp_gt_f32_e64 s[0:1], 0, v28
	v_pk_add_f32 v[26:27], v[4:5], v[8:9]
	v_pk_mul_f32 v[8:9], v[28:29], v[28:29]
	v_pk_fma_f32 v[4:5], v[30:31], s[42:43], v[22:23] op_sel_hi:[1,0,0]
	v_pk_mul_f32 v[8:9], v[8:9], s[64:65] op_sel_hi:[1,0]
	v_pk_fma_f32 v[4:5], v[30:31], v[4:5], s[48:49] op_sel_hi:[1,1,0]
	v_exp_f32_e32 v8, v8
	v_exp_f32_e32 v9, v9
	v_pk_fma_f32 v[4:5], v[30:31], v[4:5], s[50:51] op_sel_hi:[1,1,0]
	v_lshlrev_b32_e32 v6, 16, v7
	v_pk_fma_f32 v[4:5], v[30:31], v[4:5], s[56:57] op_sel_hi:[1,1,0]
	v_and_b32_e32 v7, 0xffff0000, v7
	v_pk_mul_f32 v[4:5], v[30:31], v[4:5]
	s_nop 0
	v_pk_mul_f32 v[4:5], v[8:9], v[4:5]
	s_nop 0
	v_pk_mul_f32 v[8:9], v[28:29], v[4:5]
	v_pk_fma_f32 v[4:5], v[28:29], v[4:5], v[28:29] neg_lo:[1,0,0] neg_hi:[1,0,0]
	s_nop 0
	v_cndmask_b32_e64 v11, v4, v8, s[0:1]
	v_cmp_gt_f32_e64 s[0:1], 0, v29
	v_and_b32_e32 v8, 0x7fffffff, v6
	v_mul_f32_e32 v10, v11, v11
	v_cndmask_b32_e64 v5, v5, v9, s[0:1]
	v_and_b32_e32 v9, 0x7fffffff, v7
	v_pk_fma_f32 v[8:9], v[8:9], s[40:41], 1.0 op_sel_hi:[1,0,0]
	v_mul_f32_e32 v4, v5, v5
	v_rcp_f32_e32 v8, v8
	v_rcp_f32_e32 v9, v9
	v_pk_add_f32 v[28:29], v[10:11], v[4:5]
	v_pk_mul_f32 v[10:11], v[6:7], v[6:7]
	v_cmp_gt_f32_e64 s[0:1], 0, v6
	v_pk_fma_f32 v[4:5], v[8:9], s[42:43], v[22:23] op_sel_hi:[1,0,0]
	v_pk_mul_f32 v[10:11], v[10:11], s[64:65] op_sel_hi:[1,0]
	v_pk_fma_f32 v[4:5], v[8:9], v[4:5], s[48:49] op_sel_hi:[1,1,0]
	v_exp_f32_e32 v10, v10
	v_exp_f32_e32 v11, v11
	v_pk_fma_f32 v[4:5], v[8:9], v[4:5], s[50:51] op_sel_hi:[1,1,0]
	v_pk_add_f32 v[26:27], v[28:29], v[26:27]
	v_pk_fma_f32 v[4:5], v[8:9], v[4:5], s[56:57] op_sel_hi:[1,1,0]
	s_nop 0
	v_pk_mul_f32 v[4:5], v[8:9], v[4:5]
	s_nop 0
	v_pk_mul_f32 v[4:5], v[10:11], v[4:5]
	global_load_dwordx4 v[8:11], v[24:25], off offset:1280
	s_waitcnt vmcnt(1)
	v_lshlrev_b32_e32 v36, 16, v12
	v_and_b32_e32 v37, 0xffff0000, v12
	v_fma_f32 v34, |v36|, s40, 1.0
	v_fma_f32 v35, |v37|, s40, 1.0
	v_pk_mul_f32 v[32:33], v[6:7], v[4:5]
	v_rcp_f32_e32 v34, v34
	v_rcp_f32_e32 v35, v35
	v_pk_fma_f32 v[4:5], v[6:7], v[4:5], v[6:7] neg_lo:[1,0,0] neg_hi:[1,0,0]
	v_lshlrev_b32_e32 v38, 16, v13
	v_cndmask_b32_e64 v31, v4, v32, s[0:1]
	v_cmp_gt_f32_e64 s[0:1], 0, v7
	v_pk_mul_f32 v[6:7], v[36:37], v[36:37]
	v_and_b32_e32 v39, 0xffff0000, v13
	v_cndmask_b32_e64 v33, v5, v33, s[0:1]
	v_pk_fma_f32 v[4:5], v[34:35], s[42:43], v[22:23] op_sel_hi:[1,0,0]
	v_pk_mul_f32 v[6:7], v[6:7], s[64:65] op_sel_hi:[1,0]
	v_pk_fma_f32 v[4:5], v[34:35], v[4:5], s[48:49] op_sel_hi:[1,1,0]
	v_exp_f32_e32 v6, v6
	v_exp_f32_e32 v7, v7
	v_pk_fma_f32 v[4:5], v[34:35], v[4:5], s[50:51] op_sel_hi:[1,1,0]
	v_pk_fma_f32 v[4:5], v[34:35], v[4:5], s[56:57] op_sel_hi:[1,1,0]
	v_fma_f32 v12, |v38|, s40, 1.0
	v_fma_f32 v13, |v39|, s40, 1.0
	v_pk_mul_f32 v[4:5], v[34:35], v[4:5]
	v_rcp_f32_e32 v40, v12
	v_rcp_f32_e32 v41, v13
	v_pk_mul_f32 v[4:5], v[6:7], v[4:5]
	v_cmp_gt_f32_e64 s[0:1], 0, v36
	v_pk_mul_f32 v[6:7], v[36:37], v[4:5]
	v_pk_fma_f32 v[4:5], v[36:37], v[4:5], v[36:37] neg_lo:[1,0,0] neg_hi:[1,0,0]
	v_lshlrev_b32_e32 v42, 16, v14
	v_cndmask_b32_e64 v35, v4, v6, s[0:1]
	v_cmp_gt_f32_e64 s[0:1], 0, v37
	v_and_b32_e32 v43, 0xffff0000, v14
	v_lshlrev_b32_e32 v44, 16, v15
	v_cndmask_b32_e64 v13, v5, v7, s[0:1]
	v_pk_fma_f32 v[4:5], v[40:41], s[42:43], v[22:23] op_sel_hi:[1,0,0]
	v_pk_mul_f32 v[6:7], v[38:39], v[38:39]
	v_pk_fma_f32 v[4:5], v[40:41], v[4:5], s[48:49] op_sel_hi:[1,1,0]
	v_pk_mul_f32 v[6:7], v[6:7], s[64:65] op_sel_hi:[1,0]
	v_pk_fma_f32 v[4:5], v[40:41], v[4:5], s[50:51] op_sel_hi:[1,1,0]
	v_exp_f32_e32 v6, v6
	v_exp_f32_e32 v7, v7
	v_pk_fma_f32 v[4:5], v[40:41], v[4:5], s[56:57] op_sel_hi:[1,1,0]
	v_cmp_gt_f32_e64 s[0:1], 0, v38
	v_pk_mul_f32 v[4:5], v[40:41], v[4:5]
	v_fma_f32 v40, |v42|, s40, 1.0
	v_fma_f32 v41, |v43|, s40, 1.0
	v_pk_mul_f32 v[4:5], v[6:7], v[4:5]
	v_rcp_f32_e32 v40, v40
	v_rcp_f32_e32 v41, v41
	v_pk_mul_f32 v[6:7], v[38:39], v[4:5]
	v_pk_fma_f32 v[4:5], v[38:39], v[4:5], v[38:39] neg_lo:[1,0,0] neg_hi:[1,0,0]
	v_and_b32_e32 v45, 0xffff0000, v15
	v_cndmask_b32_e64 v37, v4, v6, s[0:1]
	v_cmp_gt_f32_e64 s[0:1], 0, v39
	v_cndmask_b32_e64 v39, v5, v7, s[0:1]
	v_pk_mul_f32 v[6:7], v[42:43], v[42:43]
	v_pk_fma_f32 v[4:5], v[40:41], s[42:43], v[22:23] op_sel_hi:[1,0,0]
	v_pk_mul_f32 v[6:7], v[6:7], s[64:65] op_sel_hi:[1,0]
	v_pk_fma_f32 v[4:5], v[40:41], v[4:5], s[48:49] op_sel_hi:[1,1,0]
	v_exp_f32_e32 v6, v6
	v_exp_f32_e32 v7, v7
	v_pk_fma_f32 v[4:5], v[40:41], v[4:5], s[50:51] op_sel_hi:[1,1,0]
	v_fma_f32 v14, |v44|, s40, 1.0
	v_fma_f32 v15, |v45|, s40, 1.0
	v_pk_fma_f32 v[4:5], v[40:41], v[4:5], s[56:57] op_sel_hi:[1,1,0]
	v_rcp_f32_e32 v46, v14
	v_pk_mul_f32 v[4:5], v[40:41], v[4:5]
	v_rcp_f32_e32 v47, v15
	v_pk_mul_f32 v[4:5], v[6:7], v[4:5]
	v_cmp_gt_f32_e64 s[0:1], 0, v42
	v_pk_mul_f32 v[6:7], v[42:43], v[4:5]
	v_pk_fma_f32 v[4:5], v[42:43], v[4:5], v[42:43] neg_lo:[1,0,0] neg_hi:[1,0,0]
	v_mul_f32_e32 v30, v31, v31
	v_cndmask_b32_e64 v41, v4, v6, s[0:1]
	v_cmp_gt_f32_e64 s[0:1], 0, v43
	s_waitcnt vmcnt(0)
	v_lshlrev_b32_e32 v48, 16, v8
	v_and_b32_e32 v49, 0xffff0000, v8
	v_cndmask_b32_e64 v15, v5, v7, s[0:1]
	v_pk_fma_f32 v[4:5], v[46:47], s[42:43], v[22:23] op_sel_hi:[1,0,0]
	v_pk_mul_f32 v[6:7], v[44:45], v[44:45]
	v_pk_fma_f32 v[4:5], v[46:47], v[4:5], s[48:49] op_sel_hi:[1,1,0]
	v_pk_mul_f32 v[6:7], v[6:7], s[64:65] op_sel_hi:[1,0]
	v_pk_fma_f32 v[4:5], v[46:47], v[4:5], s[50:51] op_sel_hi:[1,1,0]
	v_exp_f32_e32 v6, v6
	v_exp_f32_e32 v7, v7
	v_pk_fma_f32 v[4:5], v[46:47], v[4:5], s[56:57] op_sel_hi:[1,1,0]
	v_cmp_gt_f32_e64 s[0:1], 0, v44
	v_pk_mul_f32 v[4:5], v[46:47], v[4:5]
	v_fma_f32 v46, |v48|, s40, 1.0
	v_fma_f32 v47, |v49|, s40, 1.0
	v_pk_mul_f32 v[4:5], v[6:7], v[4:5]
	v_rcp_f32_e32 v46, v46
	v_rcp_f32_e32 v47, v47
	v_pk_mul_f32 v[6:7], v[44:45], v[4:5]
	v_pk_fma_f32 v[4:5], v[44:45], v[4:5], v[44:45] neg_lo:[1,0,0] neg_hi:[1,0,0]
	v_lshlrev_b32_e32 v60, 16, v9
	v_cndmask_b32_e64 v43, v4, v6, s[0:1]
	v_cmp_gt_f32_e64 s[0:1], 0, v45
	v_and_b32_e32 v61, 0xffff0000, v9
	v_cndmask_b32_e64 v45, v5, v7, s[0:1]
	v_pk_mul_f32 v[6:7], v[48:49], v[48:49]
	v_pk_fma_f32 v[4:5], v[46:47], s[42:43], v[22:23] op_sel_hi:[1,0,0]
	v_pk_mul_f32 v[6:7], v[6:7], s[64:65] op_sel_hi:[1,0]
	v_pk_fma_f32 v[4:5], v[46:47], v[4:5], s[48:49] op_sel_hi:[1,1,0]
	v_exp_f32_e32 v6, v6
	v_exp_f32_e32 v7, v7
	v_pk_fma_f32 v[4:5], v[46:47], v[4:5], s[50:51] op_sel_hi:[1,1,0]
	v_pk_fma_f32 v[4:5], v[46:47], v[4:5], s[56:57] op_sel_hi:[1,1,0]
	v_fma_f32 v8, |v60|, s40, 1.0
	v_fma_f32 v9, |v61|, s40, 1.0
	v_pk_mul_f32 v[4:5], v[46:47], v[4:5]
	v_rcp_f32_e32 v62, v8
	v_pk_mul_f32 v[46:47], v[6:7], v[4:5]
	global_load_dwordx4 v[4:7], v[24:25], off offset:1536
	v_rcp_f32_e32 v63, v9
	v_max_f32_e32 v85, 0, v49
	v_fma_f32 v9, -|v49|, v47, v85
	v_max_f32_e32 v84, 0, v48
	v_fma_f32 v47, -|v48|, v46, v84
	v_lshlrev_b32_e32 v66, 16, v11
	v_and_b32_e32 v67, 0xffff0000, v11
	v_pk_fma_f32 v[48:49], v[62:63], s[42:43], v[22:23] op_sel_hi:[1,0,0]
	v_and_b32_e32 v11, 0x7fffffff, v67
	v_pk_fma_f32 v[48:49], v[62:63], v[48:49], s[48:49] op_sel_hi:[1,1,0]
	v_pk_mul_f32 v[50:51], v[60:61], v[60:61]
	v_pk_fma_f32 v[48:49], v[62:63], v[48:49], s[50:51] op_sel_hi:[1,1,0]
	v_pk_mul_f32 v[50:51], v[50:51], s[64:65] op_sel_hi:[1,0]
	v_pk_fma_f32 v[48:49], v[62:63], v[48:49], s[56:57] op_sel_hi:[1,1,0]
	v_exp_f32_e32 v50, v50
	v_exp_f32_e32 v51, v51
	v_pk_mul_f32 v[48:49], v[62:63], v[48:49]
	v_lshlrev_b32_e32 v62, 16, v10
	v_and_b32_e32 v63, 0xffff0000, v10
	v_fma_f32 v64, |v62|, s40, 1.0
	v_fma_f32 v65, |v63|, s40, 1.0
	v_pk_mul_f32 v[48:49], v[50:51], v[48:49]
	v_rcp_f32_e32 v64, v64
	v_rcp_f32_e32 v65, v65
	v_max_f32_e32 v90, 0, v61
	v_fma_f32 v51, -|v61|, v49, v90
	v_max_f32_e32 v86, 0, v60
	v_fma_f32 v49, -|v60|, v48, v86
	v_and_b32_e32 v10, 0x7fffffff, v66
	v_pk_fma_f32 v[10:11], v[10:11], s[40:41], 1.0 op_sel_hi:[1,0,0]
	v_pk_mul_f32 v[60:61], v[62:63], v[62:63]
	v_rcp_f32_e32 v68, v10
	v_pk_fma_f32 v[52:53], v[64:65], s[42:43], v[22:23] op_sel_hi:[1,0,0]
	v_pk_mul_f32 v[60:61], v[60:61], s[64:65] op_sel_hi:[1,0]
	v_pk_fma_f32 v[52:53], v[64:65], v[52:53], s[48:49] op_sel_hi:[1,1,0]
	v_exp_f32_e32 v60, v60
	v_exp_f32_e32 v61, v61
	v_pk_fma_f32 v[52:53], v[64:65], v[52:53], s[50:51] op_sel_hi:[1,1,0]
	v_rcp_f32_e32 v69, v11
	v_pk_fma_f32 v[52:53], v[64:65], v[52:53], s[56:57] op_sel_hi:[1,1,0]
	v_cmp_gt_f32_e64 s[0:1], 0, v62
	v_pk_mul_f32 v[52:53], v[64:65], v[52:53]
	v_mul_f32_e32 v32, v33, v33
	v_pk_mul_f32 v[52:53], v[60:61], v[52:53]
	v_mul_f32_e32 v34, v35, v35
	v_pk_mul_f32 v[60:61], v[62:63], v[52:53]
	v_pk_fma_f32 v[64:65], v[62:63], v[52:53], v[62:63] neg_lo:[1,0,0] neg_hi:[1,0,0]
	v_mul_f32_e32 v12, v13, v13
	v_cndmask_b32_e64 v53, v64, v60, s[0:1]
	v_cmp_gt_f32_e64 s[0:1], 0, v63
	v_pk_mul_f32 v[62:63], v[66:67], v[66:67]
	v_pk_add_f32 v[28:29], v[30:31], v[32:33]
	v_cndmask_b32_e64 v11, v65, v61, s[0:1]
	v_pk_fma_f32 v[60:61], v[68:69], s[42:43], v[22:23] op_sel_hi:[1,0,0]
	v_pk_mul_f32 v[62:63], v[62:63], s[64:65] op_sel_hi:[1,0]
	v_pk_fma_f32 v[60:61], v[68:69], v[60:61], s[48:49] op_sel_hi:[1,1,0]
	v_exp_f32_e32 v62, v62
	v_exp_f32_e32 v63, v63
	v_pk_fma_f32 v[60:61], v[68:69], v[60:61], s[50:51] op_sel_hi:[1,1,0]
	v_cmp_gt_f32_e64 s[0:1], 0, v66
	v_pk_fma_f32 v[60:61], v[68:69], v[60:61], s[56:57] op_sel_hi:[1,1,0]
	v_mul_f32_e32 v36, v37, v37
	v_pk_mul_f32 v[60:61], v[68:69], v[60:61]
	v_mul_f32_e32 v38, v39, v39
	v_pk_mul_f32 v[60:61], v[62:63], v[60:61]
	v_pk_add_f32 v[26:27], v[28:29], v[26:27]
	v_pk_mul_f32 v[64:65], v[66:67], v[60:61]
	v_pk_fma_f32 v[68:69], v[66:67], v[60:61], v[66:67] neg_lo:[1,0,0] neg_hi:[1,0,0]
	global_load_dwordx4 v[60:63], v[24:25], off offset:1792
	v_cndmask_b32_e64 v71, v68, v64, s[0:1]
	v_cmp_gt_f32_e64 s[0:1], 0, v67
	v_pk_add_f32 v[12:13], v[34:35], v[12:13]
	v_mul_f32_e32 v40, v41, v41
	v_cndmask_b32_e64 v65, v69, v65, s[0:1]
	s_waitcnt vmcnt(1)
	v_lshlrev_b32_e32 v24, 16, v4
	v_and_b32_e32 v25, 0xffff0000, v4
	v_fma_f32 v72, |v24|, s40, 1.0
	v_fma_f32 v73, |v25|, s40, 1.0
	v_pk_mul_f32 v[68:69], v[24:25], v[24:25]
	v_rcp_f32_e32 v72, v72
	v_rcp_f32_e32 v73, v73
	v_mul_f32_e32 v14, v15, v15
	v_pk_mul_f32 v[68:69], v[68:69], s[64:65] op_sel_hi:[1,0]
	v_pk_add_f32 v[12:13], v[12:13], v[26:27]
	v_pk_fma_f32 v[66:67], v[72:73], s[42:43], v[22:23] op_sel_hi:[1,0,0]
	v_pk_add_f32 v[26:27], v[36:37], v[38:39]
	v_mul_f32_e32 v42, v43, v43
	v_mul_f32_e32 v44, v45, v45
	v_pk_fma_f32 v[66:67], v[72:73], v[66:67], s[48:49] op_sel_hi:[1,1,0]
	v_exp_f32_e32 v68, v68
	v_exp_f32_e32 v69, v69
	v_pk_add_f32 v[12:13], v[26:27], v[12:13]
	v_pk_add_f32 v[14:15], v[40:41], v[14:15]
	v_mul_f32_e32 v46, v47, v47
	v_mul_f32_e32 v8, v9, v9
	v_pk_fma_f32 v[66:67], v[72:73], v[66:67], s[50:51] op_sel_hi:[1,1,0]
	v_pk_add_f32 v[12:13], v[14:15], v[12:13]
	v_pk_add_f32 v[14:15], v[42:43], v[44:45]
	v_mul_f32_e32 v48, v49, v49
	v_mul_f32_e32 v50, v51, v51
	v_pk_fma_f32 v[66:67], v[72:73], v[66:67], s[56:57] op_sel_hi:[1,1,0]
	v_pk_add_f32 v[12:13], v[14:15], v[12:13]
	v_pk_add_f32 v[8:9], v[46:47], v[8:9]
	v_pk_mul_f32 v[66:67], v[72:73], v[66:67]
	v_pk_add_f32 v[8:9], v[8:9], v[12:13]
	v_pk_add_f32 v[12:13], v[48:49], v[50:51]
	v_lshlrev_b32_e32 v4, 16, v5
	v_and_b32_e32 v5, 0xffff0000, v5
	v_pk_mul_f32 v[66:67], v[68:69], v[66:67]
	v_pk_add_f32 v[8:9], v[12:13], v[8:9]
	v_max_f32_e32 v91, 0, v24
	v_fma_f32 v73, -|v24|, v66, v91
	v_max_f32_e32 v92, 0, v25
	v_fma_f32 v25, -|v25|, v67, v92
	v_fma_f32 v12, |v4|, s40, 1.0
	v_fma_f32 v13, |v5|, s40, 1.0
	v_mul_f32_e32 v52, v53, v53
	v_mul_f32_e32 v10, v11, v11
	v_rcp_f32_e32 v12, v12
	v_rcp_f32_e32 v13, v13
	v_mul_f32_e32 v70, v71, v71
	v_mul_f32_e32 v64, v65, v65
	v_pk_add_f32 v[10:11], v[52:53], v[10:11]
	v_mul_f32_e32 v72, v73, v73
	v_mul_f32_e32 v24, v25, v25
	v_pk_add_f32 v[8:9], v[10:11], v[8:9]
	v_pk_add_f32 v[10:11], v[70:71], v[64:65]
	v_pk_mul_f32 v[14:15], v[4:5], v[4:5]
	v_pk_add_f32 v[8:9], v[10:11], v[8:9]
	v_pk_add_f32 v[10:11], v[72:73], v[24:25]
	v_pk_mul_f32 v[14:15], v[14:15], s[64:65] op_sel_hi:[1,0]
	v_pk_add_f32 v[8:9], v[10:11], v[8:9]
	v_pk_fma_f32 v[10:11], v[12:13], s[42:43], v[22:23] op_sel_hi:[1,0,0]
	v_exp_f32_e32 v14, v14
	v_pk_fma_f32 v[10:11], v[12:13], v[10:11], s[48:49] op_sel_hi:[1,1,0]
	v_exp_f32_e32 v15, v15
	v_pk_fma_f32 v[10:11], v[12:13], v[10:11], s[50:51] op_sel_hi:[1,1,0]
	v_cmp_gt_f32_e64 s[0:1], 0, v4
	v_pk_fma_f32 v[10:11], v[12:13], v[10:11], s[56:57] op_sel_hi:[1,1,0]
	s_waitcnt vmcnt(0)
	v_lshlrev_b32_e32 v28, 16, v60
	v_pk_mul_f32 v[10:11], v[12:13], v[10:11]
	v_and_b32_e32 v29, 0xffff0000, v60
	v_pk_mul_f32 v[10:11], v[14:15], v[10:11]
	v_and_b32_e32 v31, 0x7fffffff, v29
	v_pk_mul_f32 v[12:13], v[4:5], v[10:11]
	v_pk_fma_f32 v[10:11], v[4:5], v[10:11], v[4:5] neg_lo:[1,0,0] neg_hi:[1,0,0]
	v_and_b32_e32 v30, 0x7fffffff, v28
	v_cndmask_b32_e64 v15, v10, v12, s[0:1]
	v_cmp_gt_f32_e64 s[0:1], 0, v5
	v_lshlrev_b32_e32 v10, 16, v6
	v_and_b32_e32 v12, 0x7fffffff, v10
	v_cndmask_b32_e64 v5, v11, v13, s[0:1]
	v_and_b32_e32 v11, 0xffff0000, v6
	v_and_b32_e32 v13, 0x7fffffff, v11
	v_pk_fma_f32 v[12:13], v[12:13], s[40:41], 1.0 op_sel_hi:[1,0,0]
	v_mul_f32_e32 v14, v15, v15
	v_rcp_f32_e32 v12, v12
	v_rcp_f32_e32 v13, v13
	v_mul_f32_e32 v4, v5, v5
	v_pk_mul_f32 v[24:25], v[10:11], v[10:11]
	v_pk_add_f32 v[4:5], v[14:15], v[4:5]
	v_pk_fma_f32 v[14:15], v[12:13], s[42:43], v[22:23] op_sel_hi:[1,0,0]
	v_pk_mul_f32 v[24:25], v[24:25], s[64:65] op_sel_hi:[1,0]
	v_pk_fma_f32 v[14:15], v[12:13], v[14:15], s[48:49] op_sel_hi:[1,1,0]
	v_exp_f32_e32 v24, v24
	v_exp_f32_e32 v25, v25
	v_pk_fma_f32 v[14:15], v[12:13], v[14:15], s[50:51] op_sel_hi:[1,1,0]
	v_lshlrev_b32_e32 v6, 16, v7
	v_and_b32_e32 v7, 0xffff0000, v7
	v_pk_fma_f32 v[14:15], v[12:13], v[14:15], s[56:57] op_sel_hi:[1,1,0]
	v_pk_mul_f32 v[12:13], v[12:13], v[14:15]
	v_fma_f32 v26, |v6|, s40, 1.0
	v_fma_f32 v27, |v7|, s40, 1.0
	v_pk_mul_f32 v[12:13], v[24:25], v[12:13]
	v_rcp_f32_e32 v26, v26
	v_rcp_f32_e32 v27, v27
	v_max_f32_e32 v93, 0, v10
	v_fma_f32 v25, -|v10|, v12, v93
	v_max_f32_e32 v94, 0, v11
	v_fma_f32 v11, -|v11|, v13, v94
	v_pk_fma_f32 v[30:31], v[30:31], s[40:41], 1.0 op_sel_hi:[1,0,0]
	v_lshlrev_b32_e32 v32, 16, v61
	v_rcp_f32_e32 v30, v30
	v_rcp_f32_e32 v31, v31
	v_pk_mul_f32 v[14:15], v[6:7], v[6:7]
	v_pk_fma_f32 v[12:13], v[26:27], s[42:43], v[22:23] op_sel_hi:[1,0,0]
	v_pk_mul_f32 v[14:15], v[14:15], s[64:65] op_sel_hi:[1,0]
	v_pk_fma_f32 v[12:13], v[26:27], v[12:13], s[48:49] op_sel_hi:[1,1,0]
	v_exp_f32_e32 v14, v14
	v_exp_f32_e32 v15, v15
	v_pk_fma_f32 v[12:13], v[26:27], v[12:13], s[50:51] op_sel_hi:[1,1,0]
	v_cmp_gt_f32_e64 s[0:1], 0, v6
	v_pk_fma_f32 v[12:13], v[26:27], v[12:13], s[56:57] op_sel_hi:[1,1,0]
	v_and_b32_e32 v33, 0xffff0000, v61
	v_pk_mul_f32 v[12:13], v[26:27], v[12:13]
	v_pk_mul_f32 v[12:13], v[14:15], v[12:13]
	v_pk_mul_f32 v[14:15], v[6:7], v[12:13]
	v_pk_fma_f32 v[12:13], v[6:7], v[12:13], v[6:7] neg_lo:[1,0,0] neg_hi:[1,0,0]
	v_fma_f32 v34, |v32|, s40, 1.0
	v_fma_f32 v35, |v33|, s40, 1.0
	v_cndmask_b32_e64 v27, v12, v14, s[0:1]
	v_cmp_gt_f32_e64 s[0:1], 0, v7
	v_rcp_f32_e32 v34, v34
	v_rcp_f32_e32 v35, v35
	v_cndmask_b32_e64 v7, v13, v15, s[0:1]
	v_pk_mul_f32 v[14:15], v[28:29], v[28:29]
	v_pk_fma_f32 v[12:13], v[30:31], s[42:43], v[22:23] op_sel_hi:[1,0,0]
	v_pk_mul_f32 v[14:15], v[14:15], s[64:65] op_sel_hi:[1,0]
	v_pk_fma_f32 v[12:13], v[30:31], v[12:13], s[48:49] op_sel_hi:[1,1,0]
	v_exp_f32_e32 v14, v14
	v_exp_f32_e32 v15, v15
	v_pk_fma_f32 v[12:13], v[30:31], v[12:13], s[50:51] op_sel_hi:[1,1,0]
	v_cmp_gt_f32_e64 s[0:1], 0, v28
	v_pk_fma_f32 v[12:13], v[30:31], v[12:13], s[56:57] op_sel_hi:[1,1,0]
	v_lshlrev_b32_e32 v36, 16, v62
	v_pk_mul_f32 v[12:13], v[30:31], v[12:13]
	v_and_b32_e32 v37, 0xffff0000, v62
	v_pk_mul_f32 v[12:13], v[14:15], v[12:13]
	v_pk_mul_f32 v[14:15], v[28:29], v[12:13]
	v_pk_fma_f32 v[12:13], v[28:29], v[12:13], v[28:29] neg_lo:[1,0,0] neg_hi:[1,0,0]
	v_cndmask_b32_e64 v31, v12, v14, s[0:1]
	v_cmp_gt_f32_e64 s[0:1], 0, v29
	v_pk_mul_f32 v[28:29], v[32:33], v[32:33]
	v_fma_f32 v38, |v36|, s40, 1.0
	v_fma_f32 v39, |v37|, s40, 1.0
	v_cndmask_b32_e64 v13, v13, v15, s[0:1]
	v_pk_fma_f32 v[14:15], v[34:35], s[42:43], v[22:23] op_sel_hi:[1,0,0]
	v_pk_mul_f32 v[28:29], v[28:29], s[64:65] op_sel_hi:[1,0]
	v_pk_fma_f32 v[14:15], v[34:35], v[14:15], s[48:49] op_sel_hi:[1,1,0]
	v_exp_f32_e32 v28, v28
	v_exp_f32_e32 v29, v29
	v_pk_fma_f32 v[14:15], v[34:35], v[14:15], s[50:51] op_sel_hi:[1,1,0]
	v_rcp_f32_e32 v38, v38
	v_pk_fma_f32 v[14:15], v[34:35], v[14:15], s[56:57] op_sel_hi:[1,1,0]
	v_rcp_f32_e32 v39, v39
	v_pk_mul_f32 v[14:15], v[34:35], v[14:15]
	v_cmp_gt_f32_e64 s[0:1], 0, v32
	v_pk_mul_f32 v[14:15], v[28:29], v[14:15]
	v_lshlrev_b32_e32 v40, 16, v63
	v_pk_mul_f32 v[28:29], v[32:33], v[14:15]
	v_pk_fma_f32 v[14:15], v[32:33], v[14:15], v[32:33] neg_lo:[1,0,0] neg_hi:[1,0,0]
	v_and_b32_e32 v41, 0xffff0000, v63
	v_cndmask_b32_e64 v35, v14, v28, s[0:1]
	v_cmp_gt_f32_e64 s[0:1], 0, v33
	v_pk_mul_f32 v[32:33], v[36:37], v[36:37]
	v_cndmask_b32_e64 v15, v15, v29, s[0:1]
	v_pk_fma_f32 v[28:29], v[38:39], s[42:43], v[22:23] op_sel_hi:[1,0,0]
	v_pk_mul_f32 v[32:33], v[32:33], s[64:65] op_sel_hi:[1,0]
	v_pk_fma_f32 v[28:29], v[38:39], v[28:29], s[48:49] op_sel_hi:[1,1,0]
	v_exp_f32_e32 v32, v32
	v_exp_f32_e32 v33, v33
	v_pk_fma_f32 v[28:29], v[38:39], v[28:29], s[50:51] op_sel_hi:[1,1,0]
	v_pk_fma_f32 v[28:29], v[38:39], v[28:29], s[56:57] op_sel_hi:[1,1,0]
	v_fma_f32 v42, |v40|, s40, 1.0
	v_fma_f32 v43, |v41|, s40, 1.0
	v_pk_mul_f32 v[28:29], v[38:39], v[28:29]
	v_rcp_f32_e32 v42, v42
	v_pk_mul_f32 v[28:29], v[32:33], v[28:29]
	v_rcp_f32_e32 v43, v43
	v_max_f32_e32 v95, 0, v36
	v_fma_f32 v39, -|v36|, v28, v95
	v_max_f32_e32 v96, 0, v37
	v_fma_f32 v29, -|v37|, v29, v96
	v_pk_fma_f32 v[22:23], v[42:43], s[42:43], v[22:23] op_sel_hi:[1,0,0]
	v_mul_f32_e32 v24, v25, v25
	v_pk_fma_f32 v[22:23], v[42:43], v[22:23], s[48:49] op_sel_hi:[1,1,0]
	v_mul_f32_e32 v10, v11, v11
	v_pk_mul_f32 v[32:33], v[40:41], v[40:41]
	v_pk_fma_f32 v[22:23], v[42:43], v[22:23], s[50:51] op_sel_hi:[1,1,0]
	v_pk_mul_f32 v[32:33], v[32:33], s[64:65] op_sel_hi:[1,0]
	v_pk_fma_f32 v[22:23], v[42:43], v[22:23], s[56:57] op_sel_hi:[1,1,0]
	v_exp_f32_e32 v32, v32
	v_exp_f32_e32 v33, v33
	v_pk_mul_f32 v[22:23], v[42:43], v[22:23]
	v_mul_f32_e32 v26, v27, v27
	v_mul_f32_e32 v6, v7, v7
	v_pk_mul_f32 v[22:23], v[32:33], v[22:23]
	v_pk_add_f32 v[4:5], v[4:5], v[8:9]
	v_pk_add_f32 v[8:9], v[24:25], v[10:11]
	v_mul_f32_e32 v30, v31, v31
	v_mul_f32_e32 v12, v13, v13
	v_max_f32_e32 v97, 0, v40
	v_fma_f32 v37, -|v40|, v22, v97
	v_max_f32_e32 v98, 0, v41
	v_fma_f32 v23, -|v41|, v23, v98
	v_pk_add_f32 v[4:5], v[8:9], v[4:5]
	v_pk_add_f32 v[6:7], v[26:27], v[6:7]
	v_mul_f32_e32 v34, v35, v35
	v_mul_f32_e32 v14, v15, v15
	v_pk_add_f32 v[4:5], v[6:7], v[4:5]
	v_pk_add_f32 v[6:7], v[30:31], v[12:13]
	v_mul_f32_e32 v38, v39, v39
	v_mul_f32_e32 v28, v29, v29
	v_pk_add_f32 v[4:5], v[6:7], v[4:5]
	v_pk_add_f32 v[6:7], v[34:35], v[14:15]
	v_mul_f32_e32 v36, v37, v37
	v_mul_f32_e32 v22, v23, v23
	v_pk_add_f32 v[4:5], v[6:7], v[4:5]
	v_pk_add_f32 v[6:7], v[38:39], v[28:29]
	s_nop 0
	v_pk_add_f32 v[4:5], v[6:7], v[4:5]
	v_pk_add_f32 v[6:7], v[36:37], v[22:23]
	s_nop 0
	v_pk_add_f32 v[4:5], v[6:7], v[4:5]
	ds_bpermute_b32 v7, v56, v5
	ds_bpermute_b32 v6, v56, v4
	s_waitcnt lgkmcnt(0)
	v_pk_add_f32 v[4:5], v[4:5], v[6:7]
	ds_bpermute_b32 v7, v57, v5
	ds_bpermute_b32 v6, v57, v4
	s_waitcnt lgkmcnt(0)
	v_pk_add_f32 v[4:5], v[4:5], v[6:7]
	ds_bpermute_b32 v7, v58, v5
	ds_bpermute_b32 v6, v58, v4
	s_waitcnt lgkmcnt(0)
	v_pk_add_f32 v[4:5], v[4:5], v[6:7]
	ds_bpermute_b32 v7, v59, v5
	ds_bpermute_b32 v6, v59, v4
	s_and_saveexec_b64 s[8:9], vcc
	s_cbranch_execz .LBB0_447
	s_waitcnt lgkmcnt(0)
	v_pk_add_f32 v[4:5], v[4:5], v[6:7]
	s_nop 0
	v_pk_mul_f32 v[4:5], v[4:5], s[66:67] op_sel_hi:[1,0]
	s_nop 0
	v_fma_f32 v4, -v5, v5, v4
	v_max_f32_e32 v4, 0, v4
	v_add_f32_e32 v4, 0x358637bd, v4
	v_mul_f32_e32 v6, 0x4b800000, v4
	v_cmp_gt_f32_e64 s[0:1], s36, v4
	s_nop 1
	v_cndmask_b32_e64 v4, v4, v6, s[0:1]
	v_rsq_f32_e32 v4, v4
	v_lshl_add_u32 v6, v20, 2, 0
	v_add_u32_e32 v7, 0x11000, v6
	ds_write_b32 v7, v5
	v_mul_f32_e32 v5, 0x45800000, v4
	v_cndmask_b32_e64 v4, v4, v5, s[0:1]
	v_add_u32_e32 v5, 0x11200, v6
	ds_write_b32 v5, v4
.LBB0_447:
	s_or_b64 exec, exec, s[8:9]
	v_or_b32_e32 v20, 8, v16
	v_ashrrev_i32_e32 v21, 31, v20
	v_lshl_add_u64 v[4:5], s[6:7], 0, v[20:21]
	v_lshlrev_b64 v[4:5], 11, v[4:5]
	v_lshl_add_u64 v[4:5], s[4:5], 0, v[4:5]
	v_lshl_add_u64 v[24:25], v[4:5], 0, v[18:19]
	global_load_dwordx4 v[8:11], v[24:25], off
	s_waitcnt lgkmcnt(0)
	global_load_dwordx4 v[4:7], v[24:25], off offset:256
	v_mov_b64_e32 v[22:23], s[44:45]
	v_mov_b32_e32 v13, v2
	s_waitcnt vmcnt(1)
	v_lshlrev_b32_e32 v28, 16, v10
	v_and_b32_e32 v29, 0xffff0000, v10
	v_and_b32_e32 v15, 0xffff0000, v8
	v_and_b32_e32 v27, 0xffff0000, v9
	v_lshlrev_b32_e32 v26, 16, v9
	v_lshlrev_b32_e32 v14, 16, v8
	v_lshlrev_b32_e32 v8, 16, v11
	v_and_b32_e32 v9, 0xffff0000, v11
	v_fma_f32 v10, |v28|, s40, 1.0
	v_fma_f32 v11, |v29|, s40, 1.0
	v_fma_f32 v32, |v14|, s40, 1.0
	v_fma_f32 v33, |v15|, s40, 1.0
	v_rcp_f32_e32 v10, v10
	v_rcp_f32_e32 v11, v11
	v_fma_f32 v36, |v26|, s40, 1.0
	v_fma_f32 v37, |v27|, s40, 1.0
	v_rcp_f32_e32 v32, v32
	v_rcp_f32_e32 v33, v33
	v_rcp_f32_e32 v36, v36
	v_rcp_f32_e32 v37, v37
	v_pk_mul_f32 v[30:31], v[28:29], v[28:29]
	v_pk_mul_f32 v[34:35], v[14:15], v[14:15]
	v_pk_mul_f32 v[30:31], v[30:31], s[64:65] op_sel_hi:[1,0]
	v_pk_fma_f32 v[44:45], v[10:11], s[42:43], v[22:23] op_sel_hi:[1,0,0]
	v_pk_mul_f32 v[38:39], v[26:27], v[26:27]
	v_pk_mul_f32 v[34:35], v[34:35], s[64:65] op_sel_hi:[1,0]
	v_exp_f32_e32 v30, v30
	v_exp_f32_e32 v31, v31
	v_pk_fma_f32 v[46:47], v[32:33], s[42:43], v[22:23] op_sel_hi:[1,0,0]
	v_pk_fma_f32 v[44:45], v[10:11], v[44:45], s[48:49] op_sel_hi:[1,1,0]
	v_pk_mul_f32 v[38:39], v[38:39], s[64:65] op_sel_hi:[1,0]
	v_exp_f32_e32 v34, v34
	v_exp_f32_e32 v35, v35
	v_pk_fma_f32 v[48:49], v[36:37], s[42:43], v[22:23] op_sel_hi:[1,0,0]
	v_pk_fma_f32 v[46:47], v[32:33], v[46:47], s[48:49] op_sel_hi:[1,1,0]
	v_pk_fma_f32 v[44:45], v[10:11], v[44:45], s[50:51] op_sel_hi:[1,1,0]
	v_exp_f32_e32 v38, v38
	v_exp_f32_e32 v39, v39
	v_pk_fma_f32 v[48:49], v[36:37], v[48:49], s[48:49] op_sel_hi:[1,1,0]
	v_pk_fma_f32 v[46:47], v[32:33], v[46:47], s[50:51] op_sel_hi:[1,1,0]
	v_pk_fma_f32 v[44:45], v[10:11], v[44:45], s[56:57] op_sel_hi:[1,1,0]
	v_pk_fma_f32 v[48:49], v[36:37], v[48:49], s[50:51] op_sel_hi:[1,1,0]
	v_pk_fma_f32 v[46:47], v[32:33], v[46:47], s[56:57] op_sel_hi:[1,1,0]
	v_pk_mul_f32 v[10:11], v[10:11], v[44:45]
	v_pk_fma_f32 v[48:49], v[36:37], v[48:49], s[56:57] op_sel_hi:[1,1,0]
	v_pk_mul_f32 v[32:33], v[32:33], v[46:47]
	v_pk_mul_f32 v[10:11], v[30:31], v[10:11]
	v_pk_mul_f32 v[36:37], v[36:37], v[48:49]
	v_pk_mul_f32 v[30:31], v[34:35], v[32:33]
	v_max_f32_e32 v99, 0, v28
	v_fma_f32 v45, -|v28|, v10, v99
	v_max_f32_e32 v100, 0, v29
	v_fma_f32 v11, -|v29|, v11, v100
	v_pk_mul_f32 v[32:33], v[38:39], v[36:37]
	v_max_f32_e32 v104, 0, v26
	v_fma_f32 v29, -|v26|, v32, v104
	v_max_f32_e32 v105, 0, v27
	v_fma_f32 v27, -|v27|, v33, v105
	v_pk_mul_f32 v[36:37], v[30:31], v[14:15]
	v_pk_fma_f32 v[30:31], v[30:31], v[14:15], v[14:15] neg_lo:[1,0,0] neg_hi:[1,0,0]
	v_cmp_gt_f32_e64 s[0:1], 0, v14
	v_fma_f32 v40, |v8|, s40, 1.0
	v_fma_f32 v41, |v9|, s40, 1.0
	v_mov_b32_e32 v14, v29
	v_cndmask_b32_e64 v28, v30, v36, s[0:1]
	v_cmp_gt_f32_e64 s[0:1], 0, v15
	v_rcp_f32_e32 v40, v40
	v_rcp_f32_e32 v41, v41
	v_cndmask_b32_e64 v15, v31, v37, s[0:1]
	v_mul_f32_e32 v30, v28, v28
	v_mov_b32_e32 v31, v29
	v_mul_f32_e32 v26, v15, v15
	v_mul_f32_e32 v12, v27, v27
	v_pk_add_f32 v[26:27], v[30:31], v[26:27]
	v_pk_mul_f32 v[30:31], v[28:29], v[14:15] op_sel:[1,0] op_sel_hi:[0,1]
	v_pk_add_f32 v[14:15], v[28:29], v[14:15] op_sel:[1,0] op_sel_hi:[0,1]
	v_pk_mul_f32 v[42:43], v[8:9], v[8:9]
	v_mov_b32_e32 v31, v15
	v_pk_mul_f32 v[42:43], v[42:43], s[64:65] op_sel_hi:[1,0]
	v_pk_fma_f32 v[50:51], v[40:41], s[42:43], v[22:23] op_sel_hi:[1,0,0]
	v_mul_f32_e32 v44, v45, v45
	v_mul_f32_e32 v10, v11, v11
	v_pk_add_f32 v[12:13], v[30:31], v[12:13]
	v_exp_f32_e32 v42, v42
	v_exp_f32_e32 v43, v43
	v_pk_fma_f32 v[50:51], v[40:41], v[50:51], s[48:49] op_sel_hi:[1,1,0]
	v_pk_add_f32 v[10:11], v[44:45], v[10:11]
	v_pk_add_f32 v[12:13], v[26:27], v[12:13]
	v_cmp_gt_f32_e64 s[0:1], 0, v8
	v_pk_add_f32 v[26:27], v[10:11], v[12:13]
	v_pk_fma_f32 v[10:11], v[40:41], v[50:51], s[50:51] op_sel_hi:[1,1,0]
	s_nop 0
	v_pk_fma_f32 v[10:11], v[40:41], v[10:11], s[56:57] op_sel_hi:[1,1,0]
	s_nop 0
	v_pk_mul_f32 v[10:11], v[40:41], v[10:11]
	s_waitcnt vmcnt(0)
	v_lshlrev_b32_e32 v40, 16, v6
	v_pk_mul_f32 v[10:11], v[42:43], v[10:11]
	v_and_b32_e32 v41, 0xffff0000, v6
	v_pk_mul_f32 v[12:13], v[8:9], v[10:11]
	v_pk_fma_f32 v[10:11], v[8:9], v[10:11], v[8:9] neg_lo:[1,0,0] neg_hi:[1,0,0]
	v_and_b32_e32 v37, 0x7fffffff, v41
	v_cndmask_b32_e64 v15, v10, v12, s[0:1]
	v_cmp_gt_f32_e64 s[0:1], 0, v9
	v_lshlrev_b32_e32 v12, 16, v4
	v_and_b32_e32 v10, 0x7fffffff, v12
	v_cndmask_b32_e64 v9, v11, v13, s[0:1]
	v_and_b32_e32 v13, 0xffff0000, v4
	v_and_b32_e32 v11, 0x7fffffff, v13
	v_pk_fma_f32 v[10:11], v[10:11], s[40:41], 1.0 op_sel_hi:[1,0,0]
	v_mul_f32_e32 v14, v15, v15
	v_rcp_f32_e32 v10, v10
	v_rcp_f32_e32 v11, v11
	v_mul_f32_e32 v8, v9, v9
	v_pk_add_f32 v[28:29], v[14:15], v[8:9]
	v_pk_mul_f32 v[14:15], v[12:13], v[12:13]
	v_pk_fma_f32 v[8:9], v[10:11], s[42:43], v[22:23] op_sel_hi:[1,0,0]
	v_pk_mul_f32 v[14:15], v[14:15], s[64:65] op_sel_hi:[1,0]
	v_pk_fma_f32 v[8:9], v[10:11], v[8:9], s[48:49] op_sel_hi:[1,1,0]
	v_exp_f32_e32 v14, v14
	v_exp_f32_e32 v15, v15
	v_pk_fma_f32 v[8:9], v[10:11], v[8:9], s[50:51] op_sel_hi:[1,1,0]
	v_lshlrev_b32_e32 v4, 16, v5
	v_pk_fma_f32 v[8:9], v[10:11], v[8:9], s[56:57] op_sel_hi:[1,1,0]
	v_and_b32_e32 v5, 0xffff0000, v5
	v_pk_mul_f32 v[8:9], v[10:11], v[8:9]
	v_pk_mul_f32 v[14:15], v[14:15], v[8:9]
	global_load_dwordx4 v[8:11], v[24:25], off offset:512
	v_fma_f32 v34, |v4|, s40, 1.0
	v_fma_f32 v35, |v5|, s40, 1.0
	v_rcp_f32_e32 v34, v34
	v_rcp_f32_e32 v35, v35
	v_max_f32_e32 v106, 0, v12
	v_fma_f32 v31, -|v12|, v14, v106
	v_max_f32_e32 v107, 0, v13
	v_fma_f32 v33, -|v13|, v15, v107
	v_and_b32_e32 v36, 0x7fffffff, v40
	v_pk_fma_f32 v[36:37], v[36:37], s[40:41], 1.0 op_sel_hi:[1,0,0]
	v_pk_fma_f32 v[12:13], v[34:35], s[42:43], v[22:23] op_sel_hi:[1,0,0]
	v_rcp_f32_e32 v38, v36
	v_pk_mul_f32 v[14:15], v[4:5], v[4:5]
	v_pk_fma_f32 v[12:13], v[34:35], v[12:13], s[48:49] op_sel_hi:[1,1,0]
	v_pk_mul_f32 v[14:15], v[14:15], s[64:65] op_sel_hi:[1,0]
	v_pk_fma_f32 v[12:13], v[34:35], v[12:13], s[50:51] op_sel_hi:[1,1,0]
	v_exp_f32_e32 v14, v14
	v_exp_f32_e32 v15, v15
	v_pk_fma_f32 v[12:13], v[34:35], v[12:13], s[56:57] op_sel_hi:[1,1,0]
	v_rcp_f32_e32 v39, v37
	v_pk_mul_f32 v[12:13], v[34:35], v[12:13]
	v_cmp_gt_f32_e64 s[0:1], 0, v4
	v_pk_mul_f32 v[12:13], v[14:15], v[12:13]
	v_mul_f32_e32 v30, v31, v31
	v_pk_mul_f32 v[14:15], v[4:5], v[12:13]
	v_pk_fma_f32 v[12:13], v[4:5], v[12:13], v[4:5] neg_lo:[1,0,0] neg_hi:[1,0,0]
	v_mul_f32_e32 v32, v33, v33
	v_cndmask_b32_e64 v35, v12, v14, s[0:1]
	v_cmp_gt_f32_e64 s[0:1], 0, v5
	v_pk_fma_f32 v[4:5], v[38:39], s[42:43], v[22:23] op_sel_hi:[1,0,0]
	v_lshlrev_b32_e32 v14, 16, v7
	v_cndmask_b32_e64 v37, v13, v15, s[0:1]
	v_pk_mul_f32 v[12:13], v[40:41], v[40:41]
	v_pk_fma_f32 v[4:5], v[38:39], v[4:5], s[48:49] op_sel_hi:[1,1,0]
	v_pk_mul_f32 v[12:13], v[12:13], s[64:65] op_sel_hi:[1,0]
	v_pk_fma_f32 v[4:5], v[38:39], v[4:5], s[50:51] op_sel_hi:[1,1,0]
	v_exp_f32_e32 v12, v12
	v_exp_f32_e32 v13, v13
	v_and_b32_e32 v15, 0xffff0000, v7
	v_pk_fma_f32 v[4:5], v[38:39], v[4:5], s[56:57] op_sel_hi:[1,1,0]
	v_pk_mul_f32 v[4:5], v[38:39], v[4:5]
	v_fma_f32 v6, |v14|, s40, 1.0
	v_fma_f32 v7, |v15|, s40, 1.0
	v_pk_mul_f32 v[4:5], v[12:13], v[4:5]
	v_rcp_f32_e32 v6, v6
	v_rcp_f32_e32 v7, v7
	v_max_f32_e32 v108, 0, v40
	v_fma_f32 v39, -|v40|, v4, v108
	v_max_f32_e32 v109, 0, v41
	v_fma_f32 v41, -|v41|, v5, v109
	v_mul_f32_e32 v34, v35, v35
	v_mul_f32_e32 v36, v37, v37
	v_pk_add_f32 v[26:27], v[28:29], v[26:27]
	v_pk_add_f32 v[28:29], v[30:31], v[32:33]
	v_pk_mul_f32 v[12:13], v[14:15], v[14:15]
	v_pk_fma_f32 v[4:5], v[6:7], s[42:43], v[22:23] op_sel_hi:[1,0,0]
	v_pk_mul_f32 v[12:13], v[12:13], s[64:65] op_sel_hi:[1,0]
	v_pk_fma_f32 v[4:5], v[6:7], v[4:5], s[48:49] op_sel_hi:[1,1,0]
	v_exp_f32_e32 v12, v12
	v_exp_f32_e32 v13, v13
	v_pk_fma_f32 v[4:5], v[6:7], v[4:5], s[50:51] op_sel_hi:[1,1,0]
	v_cmp_gt_f32_e64 s[0:1], 0, v14
	v_pk_fma_f32 v[4:5], v[6:7], v[4:5], s[56:57] op_sel_hi:[1,1,0]
	v_mul_f32_e32 v38, v39, v39
	v_pk_mul_f32 v[4:5], v[6:7], v[4:5]
	v_mul_f32_e32 v40, v41, v41
	v_pk_mul_f32 v[4:5], v[12:13], v[4:5]
	v_pk_add_f32 v[26:27], v[28:29], v[26:27]
	v_pk_mul_f32 v[12:13], v[14:15], v[4:5]
	v_pk_fma_f32 v[44:45], v[14:15], v[4:5], v[14:15] neg_lo:[1,0,0] neg_hi:[1,0,0]
	global_load_dwordx4 v[4:7], v[24:25], off offset:768
	v_cndmask_b32_e64 v43, v44, v12, s[0:1]
	v_cmp_gt_f32_e64 s[0:1], 0, v15
	v_pk_add_f32 v[28:29], v[34:35], v[36:37]
	s_waitcnt vmcnt(1)
	v_lshlrev_b32_e32 v48, 16, v8
	v_and_b32_e32 v49, 0xffff0000, v8
	v_fma_f32 v46, |v48|, s40, 1.0
	v_fma_f32 v47, |v49|, s40, 1.0
	v_pk_mul_f32 v[14:15], v[48:49], v[48:49]
	v_rcp_f32_e32 v46, v46
	v_rcp_f32_e32 v47, v47
	v_cndmask_b32_e64 v45, v45, v13, s[0:1]
	v_pk_mul_f32 v[14:15], v[14:15], s[64:65] op_sel_hi:[1,0]
	v_lshlrev_b32_e32 v50, 16, v9
	v_pk_fma_f32 v[12:13], v[46:47], s[42:43], v[22:23] op_sel_hi:[1,0,0]
	v_exp_f32_e32 v14, v14
	v_pk_fma_f32 v[12:13], v[46:47], v[12:13], s[48:49] op_sel_hi:[1,1,0]
	v_exp_f32_e32 v15, v15
	v_and_b32_e32 v51, 0xffff0000, v9
	v_pk_fma_f32 v[12:13], v[46:47], v[12:13], s[50:51] op_sel_hi:[1,1,0]
	v_pk_fma_f32 v[12:13], v[46:47], v[12:13], s[56:57] op_sel_hi:[1,1,0]
	v_fma_f32 v8, |v50|, s40, 1.0
	v_fma_f32 v9, |v51|, s40, 1.0
	v_pk_mul_f32 v[12:13], v[46:47], v[12:13]
	v_rcp_f32_e32 v52, v8
	v_rcp_f32_e32 v53, v9
	v_pk_mul_f32 v[12:13], v[14:15], v[12:13]
	v_cmp_gt_f32_e64 s[0:1], 0, v48
	v_pk_mul_f32 v[14:15], v[48:49], v[12:13]
	v_pk_fma_f32 v[12:13], v[48:49], v[12:13], v[48:49] neg_lo:[1,0,0] neg_hi:[1,0,0]
	v_lshlrev_b32_e32 v60, 16, v10
	v_cndmask_b32_e64 v47, v12, v14, s[0:1]
	v_cmp_gt_f32_e64 s[0:1], 0, v49
	v_and_b32_e32 v61, 0xffff0000, v10
	v_lshlrev_b32_e32 v10, 16, v11
	v_cndmask_b32_e64 v9, v13, v15, s[0:1]
	v_pk_fma_f32 v[12:13], v[52:53], s[42:43], v[22:23] op_sel_hi:[1,0,0]
	v_pk_mul_f32 v[14:15], v[50:51], v[50:51]
	v_pk_fma_f32 v[12:13], v[52:53], v[12:13], s[48:49] op_sel_hi:[1,1,0]
	v_pk_mul_f32 v[14:15], v[14:15], s[64:65] op_sel_hi:[1,0]
	v_pk_fma_f32 v[12:13], v[52:53], v[12:13], s[50:51] op_sel_hi:[1,1,0]
	v_exp_f32_e32 v14, v14
	v_exp_f32_e32 v15, v15
	v_pk_fma_f32 v[12:13], v[52:53], v[12:13], s[56:57] op_sel_hi:[1,1,0]
	v_cmp_gt_f32_e64 s[0:1], 0, v50
	v_pk_mul_f32 v[12:13], v[52:53], v[12:13]
	v_fma_f32 v52, |v60|, s40, 1.0
	v_fma_f32 v53, |v61|, s40, 1.0
	v_pk_mul_f32 v[12:13], v[14:15], v[12:13]
	v_rcp_f32_e32 v52, v52
	v_rcp_f32_e32 v53, v53
	v_pk_mul_f32 v[14:15], v[50:51], v[12:13]
	v_pk_fma_f32 v[12:13], v[50:51], v[12:13], v[50:51] neg_lo:[1,0,0] neg_hi:[1,0,0]
	v_and_b32_e32 v11, 0xffff0000, v11
	v_cndmask_b32_e64 v49, v12, v14, s[0:1]
	v_cmp_gt_f32_e64 s[0:1], 0, v51
	v_cndmask_b32_e64 v51, v13, v15, s[0:1]
	v_pk_mul_f32 v[14:15], v[60:61], v[60:61]
	v_pk_fma_f32 v[12:13], v[52:53], s[42:43], v[22:23] op_sel_hi:[1,0,0]
	v_pk_mul_f32 v[14:15], v[14:15], s[64:65] op_sel_hi:[1,0]
	v_pk_fma_f32 v[12:13], v[52:53], v[12:13], s[48:49] op_sel_hi:[1,1,0]
	v_exp_f32_e32 v14, v14
	v_exp_f32_e32 v15, v15
	v_pk_fma_f32 v[12:13], v[52:53], v[12:13], s[50:51] op_sel_hi:[1,1,0]
	v_fma_f32 v62, |v10|, s40, 1.0
	v_fma_f32 v63, |v11|, s40, 1.0
	v_pk_fma_f32 v[12:13], v[52:53], v[12:13], s[56:57] op_sel_hi:[1,1,0]
	v_rcp_f32_e32 v62, v62
	v_pk_mul_f32 v[12:13], v[52:53], v[12:13]
	v_rcp_f32_e32 v63, v63
	v_pk_mul_f32 v[12:13], v[14:15], v[12:13]
	v_cmp_gt_f32_e64 s[0:1], 0, v60
	v_pk_mul_f32 v[14:15], v[60:61], v[12:13]
	v_pk_fma_f32 v[12:13], v[60:61], v[12:13], v[60:61] neg_lo:[1,0,0] neg_hi:[1,0,0]
	v_mul_f32_e32 v42, v43, v43
	v_cndmask_b32_e64 v53, v12, v14, s[0:1]
	v_cmp_gt_f32_e64 s[0:1], 0, v61
	s_waitcnt vmcnt(0)
	v_lshlrev_b32_e32 v64, 16, v4
	v_and_b32_e32 v65, 0xffff0000, v4
	v_cndmask_b32_e64 v61, v13, v15, s[0:1]
	v_pk_mul_f32 v[14:15], v[10:11], v[10:11]
	v_pk_fma_f32 v[12:13], v[62:63], s[42:43], v[22:23] op_sel_hi:[1,0,0]
	v_pk_mul_f32 v[14:15], v[14:15], s[64:65] op_sel_hi:[1,0]
	v_pk_fma_f32 v[12:13], v[62:63], v[12:13], s[48:49] op_sel_hi:[1,1,0]
	v_exp_f32_e32 v14, v14
	v_exp_f32_e32 v15, v15
	v_pk_fma_f32 v[12:13], v[62:63], v[12:13], s[50:51] op_sel_hi:[1,1,0]
	v_pk_fma_f32 v[12:13], v[62:63], v[12:13], s[56:57] op_sel_hi:[1,1,0]
	v_pk_mul_f32 v[12:13], v[62:63], v[12:13]
	v_fma_f32 v66, |v64|, s40, 1.0
	v_fma_f32 v67, |v65|, s40, 1.0
	v_pk_mul_f32 v[12:13], v[14:15], v[12:13]
	v_rcp_f32_e32 v66, v66
	v_rcp_f32_e32 v67, v67
	v_max_f32_e32 v110, 0, v10
	v_fma_f32 v63, -|v10|, v12, v110
	v_max_f32_e32 v111, 0, v11
	v_fma_f32 v11, -|v11|, v13, v111
	v_lshlrev_b32_e32 v4, 16, v5
	v_and_b32_e32 v5, 0xffff0000, v5
	v_pk_mul_f32 v[14:15], v[64:65], v[64:65]
	v_pk_fma_f32 v[12:13], v[66:67], s[42:43], v[22:23] op_sel_hi:[1,0,0]
	v_pk_mul_f32 v[14:15], v[14:15], s[64:65] op_sel_hi:[1,0]
	v_pk_fma_f32 v[12:13], v[66:67], v[12:13], s[48:49] op_sel_hi:[1,1,0]
	v_exp_f32_e32 v14, v14
	v_exp_f32_e32 v15, v15
	v_pk_fma_f32 v[12:13], v[66:67], v[12:13], s[50:51] op_sel_hi:[1,1,0]
	v_fma_f32 v68, |v4|, s40, 1.0
	v_fma_f32 v69, |v5|, s40, 1.0
	v_pk_fma_f32 v[12:13], v[66:67], v[12:13], s[56:57] op_sel_hi:[1,1,0]
	v_rcp_f32_e32 v68, v68
	v_pk_mul_f32 v[12:13], v[66:67], v[12:13]
	v_rcp_f32_e32 v69, v69
	v_pk_mul_f32 v[12:13], v[14:15], v[12:13]
	v_cmp_gt_f32_e64 s[0:1], 0, v64
	v_pk_mul_f32 v[14:15], v[64:65], v[12:13]
	v_pk_fma_f32 v[12:13], v[64:65], v[12:13], v[64:65] neg_lo:[1,0,0] neg_hi:[1,0,0]
	v_mul_f32_e32 v44, v45, v45
	v_cndmask_b32_e64 v67, v12, v14, s[0:1]
	v_cmp_gt_f32_e64 s[0:1], 0, v65
	v_pk_add_f32 v[26:27], v[28:29], v[26:27]
	v_pk_add_f32 v[28:29], v[38:39], v[40:41]
	v_cndmask_b32_e64 v65, v13, v15, s[0:1]
	v_pk_fma_f32 v[12:13], v[68:69], s[42:43], v[22:23] op_sel_hi:[1,0,0]
	v_pk_mul_f32 v[14:15], v[4:5], v[4:5]
	v_pk_fma_f32 v[12:13], v[68:69], v[12:13], s[48:49] op_sel_hi:[1,1,0]
	v_pk_mul_f32 v[14:15], v[14:15], s[64:65] op_sel_hi:[1,0]
	v_pk_fma_f32 v[12:13], v[68:69], v[12:13], s[50:51] op_sel_hi:[1,1,0]
	v_exp_f32_e32 v70, v14
	v_exp_f32_e32 v71, v15
	v_pk_fma_f32 v[72:73], v[68:69], v[12:13], s[56:57] op_sel_hi:[1,1,0]
	global_load_dwordx4 v[12:15], v[24:25], off offset:1024
	v_mul_f32_e32 v46, v47, v47
	v_mul_f32_e32 v8, v9, v9
	v_pk_add_f32 v[26:27], v[28:29], v[26:27]
	v_pk_add_f32 v[28:29], v[42:43], v[44:45]
	v_mul_f32_e32 v48, v49, v49
	v_mul_f32_e32 v50, v51, v51
	v_pk_add_f32 v[26:27], v[28:29], v[26:27]
	v_pk_add_f32 v[8:9], v[46:47], v[8:9]
	v_mul_f32_e32 v52, v53, v53
	v_mul_f32_e32 v60, v61, v61
	v_pk_mul_f32 v[68:69], v[68:69], v[72:73]
	v_pk_add_f32 v[8:9], v[8:9], v[26:27]
	v_pk_add_f32 v[26:27], v[48:49], v[50:51]
	v_pk_mul_f32 v[68:69], v[70:71], v[68:69]
	v_pk_add_f32 v[8:9], v[26:27], v[8:9]
	v_pk_add_f32 v[26:27], v[52:53], v[60:61]
	v_lshlrev_b32_e32 v28, 16, v6
	v_and_b32_e32 v29, 0xffff0000, v6
	v_max_f32_e32 v112, 0, v4
	v_fma_f32 v73, -|v4|, v68, v112
	v_max_f32_e32 v113, 0, v5
	v_fma_f32 v5, -|v5|, v69, v113
	v_pk_add_f32 v[8:9], v[26:27], v[8:9]
	v_mul_f32_e32 v62, v63, v63
	v_mul_f32_e32 v10, v11, v11
	v_fma_f32 v26, |v28|, s40, 1.0
	v_fma_f32 v27, |v29|, s40, 1.0
	v_mul_f32_e32 v66, v67, v67
	v_mul_f32_e32 v64, v65, v65
	v_pk_add_f32 v[10:11], v[62:63], v[10:11]
	v_rcp_f32_e32 v30, v26
	v_rcp_f32_e32 v31, v27
	v_mul_f32_e32 v72, v73, v73
	v_mul_f32_e32 v4, v5, v5
	v_pk_add_f32 v[8:9], v[10:11], v[8:9]
	v_pk_add_f32 v[10:11], v[66:67], v[64:65]
	v_pk_add_f32 v[4:5], v[72:73], v[4:5]
	v_pk_add_f32 v[8:9], v[10:11], v[8:9]
	v_cmp_gt_f32_e64 s[0:1], 0, v28
	v_pk_add_f32 v[26:27], v[4:5], v[8:9]
	v_pk_mul_f32 v[8:9], v[28:29], v[28:29]
	v_pk_fma_f32 v[4:5], v[30:31], s[42:43], v[22:23] op_sel_hi:[1,0,0]
	v_pk_mul_f32 v[8:9], v[8:9], s[64:65] op_sel_hi:[1,0]
	v_pk_fma_f32 v[4:5], v[30:31], v[4:5], s[48:49] op_sel_hi:[1,1,0]
	v_exp_f32_e32 v8, v8
	v_exp_f32_e32 v9, v9
	v_pk_fma_f32 v[4:5], v[30:31], v[4:5], s[50:51] op_sel_hi:[1,1,0]
	v_lshlrev_b32_e32 v6, 16, v7
	v_pk_fma_f32 v[4:5], v[30:31], v[4:5], s[56:57] op_sel_hi:[1,1,0]
	v_and_b32_e32 v7, 0xffff0000, v7
	v_pk_mul_f32 v[4:5], v[30:31], v[4:5]
	s_nop 0
	v_pk_mul_f32 v[4:5], v[8:9], v[4:5]
	s_nop 0
	v_pk_mul_f32 v[8:9], v[28:29], v[4:5]
	v_pk_fma_f32 v[4:5], v[28:29], v[4:5], v[28:29] neg_lo:[1,0,0] neg_hi:[1,0,0]
	s_nop 0
	v_cndmask_b32_e64 v11, v4, v8, s[0:1]
	v_cmp_gt_f32_e64 s[0:1], 0, v29
	v_and_b32_e32 v8, 0x7fffffff, v6
	v_mul_f32_e32 v10, v11, v11
	v_cndmask_b32_e64 v5, v5, v9, s[0:1]
	v_and_b32_e32 v9, 0x7fffffff, v7
	v_pk_fma_f32 v[8:9], v[8:9], s[40:41], 1.0 op_sel_hi:[1,0,0]
	v_mul_f32_e32 v4, v5, v5
	v_rcp_f32_e32 v8, v8
	v_rcp_f32_e32 v9, v9
	v_pk_add_f32 v[28:29], v[10:11], v[4:5]
	v_pk_mul_f32 v[10:11], v[6:7], v[6:7]
	v_cmp_gt_f32_e64 s[0:1], 0, v6
	v_pk_fma_f32 v[4:5], v[8:9], s[42:43], v[22:23] op_sel_hi:[1,0,0]
	v_pk_mul_f32 v[10:11], v[10:11], s[64:65] op_sel_hi:[1,0]
	v_pk_fma_f32 v[4:5], v[8:9], v[4:5], s[48:49] op_sel_hi:[1,1,0]
	v_exp_f32_e32 v10, v10
	v_exp_f32_e32 v11, v11
	v_pk_fma_f32 v[4:5], v[8:9], v[4:5], s[50:51] op_sel_hi:[1,1,0]
	v_pk_add_f32 v[26:27], v[28:29], v[26:27]
	v_pk_fma_f32 v[4:5], v[8:9], v[4:5], s[56:57] op_sel_hi:[1,1,0]
	s_nop 0
	v_pk_mul_f32 v[4:5], v[8:9], v[4:5]
	s_nop 0
	v_pk_mul_f32 v[4:5], v[10:11], v[4:5]
	global_load_dwordx4 v[8:11], v[24:25], off offset:1280
	s_waitcnt vmcnt(1)
	v_lshlrev_b32_e32 v36, 16, v12
	v_and_b32_e32 v37, 0xffff0000, v12
	v_fma_f32 v34, |v36|, s40, 1.0
	v_fma_f32 v35, |v37|, s40, 1.0
	v_pk_mul_f32 v[32:33], v[6:7], v[4:5]
	v_rcp_f32_e32 v34, v34
	v_rcp_f32_e32 v35, v35
	v_pk_fma_f32 v[4:5], v[6:7], v[4:5], v[6:7] neg_lo:[1,0,0] neg_hi:[1,0,0]
	v_lshlrev_b32_e32 v38, 16, v13
	v_cndmask_b32_e64 v31, v4, v32, s[0:1]
	v_cmp_gt_f32_e64 s[0:1], 0, v7
	v_pk_mul_f32 v[6:7], v[36:37], v[36:37]
	v_and_b32_e32 v39, 0xffff0000, v13
	v_cndmask_b32_e64 v33, v5, v33, s[0:1]
	v_pk_fma_f32 v[4:5], v[34:35], s[42:43], v[22:23] op_sel_hi:[1,0,0]
	v_pk_mul_f32 v[6:7], v[6:7], s[64:65] op_sel_hi:[1,0]
	v_pk_fma_f32 v[4:5], v[34:35], v[4:5], s[48:49] op_sel_hi:[1,1,0]
	v_exp_f32_e32 v6, v6
	v_exp_f32_e32 v7, v7
	v_pk_fma_f32 v[4:5], v[34:35], v[4:5], s[50:51] op_sel_hi:[1,1,0]
	v_pk_fma_f32 v[4:5], v[34:35], v[4:5], s[56:57] op_sel_hi:[1,1,0]
	v_fma_f32 v12, |v38|, s40, 1.0
	v_fma_f32 v13, |v39|, s40, 1.0
	v_pk_mul_f32 v[4:5], v[34:35], v[4:5]
	v_rcp_f32_e32 v40, v12
	v_rcp_f32_e32 v41, v13
	v_pk_mul_f32 v[4:5], v[6:7], v[4:5]
	v_cmp_gt_f32_e64 s[0:1], 0, v36
	v_pk_mul_f32 v[6:7], v[36:37], v[4:5]
	v_pk_fma_f32 v[4:5], v[36:37], v[4:5], v[36:37] neg_lo:[1,0,0] neg_hi:[1,0,0]
	v_lshlrev_b32_e32 v42, 16, v14
	v_cndmask_b32_e64 v35, v4, v6, s[0:1]
	v_cmp_gt_f32_e64 s[0:1], 0, v37
	v_and_b32_e32 v43, 0xffff0000, v14
	v_lshlrev_b32_e32 v44, 16, v15
	v_cndmask_b32_e64 v13, v5, v7, s[0:1]
	v_pk_fma_f32 v[4:5], v[40:41], s[42:43], v[22:23] op_sel_hi:[1,0,0]
	v_pk_mul_f32 v[6:7], v[38:39], v[38:39]
	v_pk_fma_f32 v[4:5], v[40:41], v[4:5], s[48:49] op_sel_hi:[1,1,0]
	v_pk_mul_f32 v[6:7], v[6:7], s[64:65] op_sel_hi:[1,0]
	v_pk_fma_f32 v[4:5], v[40:41], v[4:5], s[50:51] op_sel_hi:[1,1,0]
	v_exp_f32_e32 v6, v6
	v_exp_f32_e32 v7, v7
	v_pk_fma_f32 v[4:5], v[40:41], v[4:5], s[56:57] op_sel_hi:[1,1,0]
	v_cmp_gt_f32_e64 s[0:1], 0, v38
	v_pk_mul_f32 v[4:5], v[40:41], v[4:5]
	v_fma_f32 v40, |v42|, s40, 1.0
	v_fma_f32 v41, |v43|, s40, 1.0
	v_pk_mul_f32 v[4:5], v[6:7], v[4:5]
	v_rcp_f32_e32 v40, v40
	v_rcp_f32_e32 v41, v41
	v_pk_mul_f32 v[6:7], v[38:39], v[4:5]
	v_pk_fma_f32 v[4:5], v[38:39], v[4:5], v[38:39] neg_lo:[1,0,0] neg_hi:[1,0,0]
	v_and_b32_e32 v45, 0xffff0000, v15
	v_cndmask_b32_e64 v37, v4, v6, s[0:1]
	v_cmp_gt_f32_e64 s[0:1], 0, v39
	v_cndmask_b32_e64 v39, v5, v7, s[0:1]
	v_pk_mul_f32 v[6:7], v[42:43], v[42:43]
	v_pk_fma_f32 v[4:5], v[40:41], s[42:43], v[22:23] op_sel_hi:[1,0,0]
	v_pk_mul_f32 v[6:7], v[6:7], s[64:65] op_sel_hi:[1,0]
	v_pk_fma_f32 v[4:5], v[40:41], v[4:5], s[48:49] op_sel_hi:[1,1,0]
	v_exp_f32_e32 v6, v6
	v_exp_f32_e32 v7, v7
	v_pk_fma_f32 v[4:5], v[40:41], v[4:5], s[50:51] op_sel_hi:[1,1,0]
	v_fma_f32 v14, |v44|, s40, 1.0
	v_fma_f32 v15, |v45|, s40, 1.0
	v_pk_fma_f32 v[4:5], v[40:41], v[4:5], s[56:57] op_sel_hi:[1,1,0]
	v_rcp_f32_e32 v46, v14
	v_pk_mul_f32 v[4:5], v[40:41], v[4:5]
	v_rcp_f32_e32 v47, v15
	v_pk_mul_f32 v[4:5], v[6:7], v[4:5]
	v_cmp_gt_f32_e64 s[0:1], 0, v42
	v_pk_mul_f32 v[6:7], v[42:43], v[4:5]
	v_pk_fma_f32 v[4:5], v[42:43], v[4:5], v[42:43] neg_lo:[1,0,0] neg_hi:[1,0,0]
	v_mul_f32_e32 v30, v31, v31
	v_cndmask_b32_e64 v41, v4, v6, s[0:1]
	v_cmp_gt_f32_e64 s[0:1], 0, v43
	s_waitcnt vmcnt(0)
	v_lshlrev_b32_e32 v48, 16, v8
	v_and_b32_e32 v49, 0xffff0000, v8
	v_cndmask_b32_e64 v15, v5, v7, s[0:1]
	v_pk_fma_f32 v[4:5], v[46:47], s[42:43], v[22:23] op_sel_hi:[1,0,0]
	v_pk_mul_f32 v[6:7], v[44:45], v[44:45]
	v_pk_fma_f32 v[4:5], v[46:47], v[4:5], s[48:49] op_sel_hi:[1,1,0]
	v_pk_mul_f32 v[6:7], v[6:7], s[64:65] op_sel_hi:[1,0]
	v_pk_fma_f32 v[4:5], v[46:47], v[4:5], s[50:51] op_sel_hi:[1,1,0]
	v_exp_f32_e32 v6, v6
	v_exp_f32_e32 v7, v7
	v_pk_fma_f32 v[4:5], v[46:47], v[4:5], s[56:57] op_sel_hi:[1,1,0]
	v_cmp_gt_f32_e64 s[0:1], 0, v44
	v_pk_mul_f32 v[4:5], v[46:47], v[4:5]
	v_fma_f32 v46, |v48|, s40, 1.0
	v_fma_f32 v47, |v49|, s40, 1.0
	v_pk_mul_f32 v[4:5], v[6:7], v[4:5]
	v_rcp_f32_e32 v46, v46
	v_rcp_f32_e32 v47, v47
	v_pk_mul_f32 v[6:7], v[44:45], v[4:5]
	v_pk_fma_f32 v[4:5], v[44:45], v[4:5], v[44:45] neg_lo:[1,0,0] neg_hi:[1,0,0]
	v_lshlrev_b32_e32 v60, 16, v9
	v_cndmask_b32_e64 v43, v4, v6, s[0:1]
	v_cmp_gt_f32_e64 s[0:1], 0, v45
	v_and_b32_e32 v61, 0xffff0000, v9
	v_cndmask_b32_e64 v45, v5, v7, s[0:1]
	v_pk_mul_f32 v[6:7], v[48:49], v[48:49]
	v_pk_fma_f32 v[4:5], v[46:47], s[42:43], v[22:23] op_sel_hi:[1,0,0]
	v_pk_mul_f32 v[6:7], v[6:7], s[64:65] op_sel_hi:[1,0]
	v_pk_fma_f32 v[4:5], v[46:47], v[4:5], s[48:49] op_sel_hi:[1,1,0]
	v_exp_f32_e32 v6, v6
	v_exp_f32_e32 v7, v7
	v_pk_fma_f32 v[4:5], v[46:47], v[4:5], s[50:51] op_sel_hi:[1,1,0]
	v_pk_fma_f32 v[4:5], v[46:47], v[4:5], s[56:57] op_sel_hi:[1,1,0]
	v_fma_f32 v8, |v60|, s40, 1.0
	v_fma_f32 v9, |v61|, s40, 1.0
	v_pk_mul_f32 v[4:5], v[46:47], v[4:5]
	v_rcp_f32_e32 v62, v8
	v_pk_mul_f32 v[46:47], v[6:7], v[4:5]
	global_load_dwordx4 v[4:7], v[24:25], off offset:1536
	v_rcp_f32_e32 v63, v9
	v_max_f32_e32 v115, 0, v49
	v_fma_f32 v9, -|v49|, v47, v115
	v_max_f32_e32 v114, 0, v48
	v_fma_f32 v47, -|v48|, v46, v114
	v_lshlrev_b32_e32 v66, 16, v11
	v_and_b32_e32 v67, 0xffff0000, v11
	v_pk_fma_f32 v[48:49], v[62:63], s[42:43], v[22:23] op_sel_hi:[1,0,0]
	v_and_b32_e32 v11, 0x7fffffff, v67
	v_pk_fma_f32 v[48:49], v[62:63], v[48:49], s[48:49] op_sel_hi:[1,1,0]
	v_pk_mul_f32 v[50:51], v[60:61], v[60:61]
	v_pk_fma_f32 v[48:49], v[62:63], v[48:49], s[50:51] op_sel_hi:[1,1,0]
	v_pk_mul_f32 v[50:51], v[50:51], s[64:65] op_sel_hi:[1,0]
	v_pk_fma_f32 v[48:49], v[62:63], v[48:49], s[56:57] op_sel_hi:[1,1,0]
	v_exp_f32_e32 v50, v50
	v_exp_f32_e32 v51, v51
	v_pk_mul_f32 v[48:49], v[62:63], v[48:49]
	v_lshlrev_b32_e32 v62, 16, v10
	v_and_b32_e32 v63, 0xffff0000, v10
	v_fma_f32 v64, |v62|, s40, 1.0
	v_fma_f32 v65, |v63|, s40, 1.0
	v_pk_mul_f32 v[48:49], v[50:51], v[48:49]
	v_rcp_f32_e32 v64, v64
	v_rcp_f32_e32 v65, v65
	v_max_f32_e32 v117, 0, v61
	v_fma_f32 v51, -|v61|, v49, v117
	v_max_f32_e32 v116, 0, v60
	v_fma_f32 v49, -|v60|, v48, v116
	v_and_b32_e32 v10, 0x7fffffff, v66
	v_pk_fma_f32 v[10:11], v[10:11], s[40:41], 1.0 op_sel_hi:[1,0,0]
	v_pk_mul_f32 v[60:61], v[62:63], v[62:63]
	v_rcp_f32_e32 v68, v10
	v_pk_fma_f32 v[52:53], v[64:65], s[42:43], v[22:23] op_sel_hi:[1,0,0]
	v_pk_mul_f32 v[60:61], v[60:61], s[64:65] op_sel_hi:[1,0]
	v_pk_fma_f32 v[52:53], v[64:65], v[52:53], s[48:49] op_sel_hi:[1,1,0]
	v_exp_f32_e32 v60, v60
	v_exp_f32_e32 v61, v61
	v_pk_fma_f32 v[52:53], v[64:65], v[52:53], s[50:51] op_sel_hi:[1,1,0]
	v_rcp_f32_e32 v69, v11
	v_pk_fma_f32 v[52:53], v[64:65], v[52:53], s[56:57] op_sel_hi:[1,1,0]
	v_cmp_gt_f32_e64 s[0:1], 0, v62
	v_pk_mul_f32 v[52:53], v[64:65], v[52:53]
	v_mul_f32_e32 v32, v33, v33
	v_pk_mul_f32 v[52:53], v[60:61], v[52:53]
	v_mul_f32_e32 v34, v35, v35
	v_pk_mul_f32 v[60:61], v[62:63], v[52:53]
	v_pk_fma_f32 v[64:65], v[62:63], v[52:53], v[62:63] neg_lo:[1,0,0] neg_hi:[1,0,0]
	v_mul_f32_e32 v12, v13, v13
	v_cndmask_b32_e64 v53, v64, v60, s[0:1]
	v_cmp_gt_f32_e64 s[0:1], 0, v63
	v_pk_mul_f32 v[62:63], v[66:67], v[66:67]
	v_pk_add_f32 v[28:29], v[30:31], v[32:33]
	v_cndmask_b32_e64 v11, v65, v61, s[0:1]
	v_pk_fma_f32 v[60:61], v[68:69], s[42:43], v[22:23] op_sel_hi:[1,0,0]
	v_pk_mul_f32 v[62:63], v[62:63], s[64:65] op_sel_hi:[1,0]
	v_pk_fma_f32 v[60:61], v[68:69], v[60:61], s[48:49] op_sel_hi:[1,1,0]
	v_exp_f32_e32 v62, v62
	v_exp_f32_e32 v63, v63
	v_pk_fma_f32 v[60:61], v[68:69], v[60:61], s[50:51] op_sel_hi:[1,1,0]
	v_cmp_gt_f32_e64 s[0:1], 0, v66
	v_pk_fma_f32 v[60:61], v[68:69], v[60:61], s[56:57] op_sel_hi:[1,1,0]
	v_mul_f32_e32 v36, v37, v37
	v_pk_mul_f32 v[60:61], v[68:69], v[60:61]
	v_mul_f32_e32 v38, v39, v39
	v_pk_mul_f32 v[60:61], v[62:63], v[60:61]
	v_pk_add_f32 v[26:27], v[28:29], v[26:27]
	v_pk_mul_f32 v[64:65], v[66:67], v[60:61]
	v_pk_fma_f32 v[68:69], v[66:67], v[60:61], v[66:67] neg_lo:[1,0,0] neg_hi:[1,0,0]
	global_load_dwordx4 v[60:63], v[24:25], off offset:1792
	v_cndmask_b32_e64 v71, v68, v64, s[0:1]
	v_cmp_gt_f32_e64 s[0:1], 0, v67
	v_pk_add_f32 v[12:13], v[34:35], v[12:13]
	v_mul_f32_e32 v40, v41, v41
	v_cndmask_b32_e64 v65, v69, v65, s[0:1]
	s_waitcnt vmcnt(1)
	v_lshlrev_b32_e32 v24, 16, v4
	v_and_b32_e32 v25, 0xffff0000, v4
	v_fma_f32 v72, |v24|, s40, 1.0
	v_fma_f32 v73, |v25|, s40, 1.0
	v_pk_mul_f32 v[68:69], v[24:25], v[24:25]
	v_rcp_f32_e32 v72, v72
	v_rcp_f32_e32 v73, v73
	v_mul_f32_e32 v14, v15, v15
	v_pk_mul_f32 v[68:69], v[68:69], s[64:65] op_sel_hi:[1,0]
	v_pk_add_f32 v[12:13], v[12:13], v[26:27]
	v_pk_fma_f32 v[66:67], v[72:73], s[42:43], v[22:23] op_sel_hi:[1,0,0]
	v_pk_add_f32 v[26:27], v[36:37], v[38:39]
	v_mul_f32_e32 v42, v43, v43
	v_mul_f32_e32 v44, v45, v45
	v_pk_fma_f32 v[66:67], v[72:73], v[66:67], s[48:49] op_sel_hi:[1,1,0]
	v_exp_f32_e32 v68, v68
	v_exp_f32_e32 v69, v69
	v_pk_add_f32 v[12:13], v[26:27], v[12:13]
	v_pk_add_f32 v[14:15], v[40:41], v[14:15]
	v_mul_f32_e32 v46, v47, v47
	v_mul_f32_e32 v8, v9, v9
	v_pk_fma_f32 v[66:67], v[72:73], v[66:67], s[50:51] op_sel_hi:[1,1,0]
	v_pk_add_f32 v[12:13], v[14:15], v[12:13]
	v_pk_add_f32 v[14:15], v[42:43], v[44:45]
	v_mul_f32_e32 v48, v49, v49
	v_mul_f32_e32 v50, v51, v51
	v_pk_fma_f32 v[66:67], v[72:73], v[66:67], s[56:57] op_sel_hi:[1,1,0]
	v_pk_add_f32 v[12:13], v[14:15], v[12:13]
	v_pk_add_f32 v[8:9], v[46:47], v[8:9]
	v_pk_mul_f32 v[66:67], v[72:73], v[66:67]
	v_pk_add_f32 v[8:9], v[8:9], v[12:13]
	v_pk_add_f32 v[12:13], v[48:49], v[50:51]
	v_lshlrev_b32_e32 v4, 16, v5
	v_and_b32_e32 v5, 0xffff0000, v5
	v_pk_mul_f32 v[66:67], v[68:69], v[66:67]
	v_pk_add_f32 v[8:9], v[12:13], v[8:9]
	v_max_f32_e32 v80, 0, v24
	v_fma_f32 v73, -|v24|, v66, v80
	v_max_f32_e32 v81, 0, v25
	v_fma_f32 v25, -|v25|, v67, v81
	v_fma_f32 v12, |v4|, s40, 1.0
	v_fma_f32 v13, |v5|, s40, 1.0
	v_mul_f32_e32 v52, v53, v53
	v_mul_f32_e32 v10, v11, v11
	v_rcp_f32_e32 v12, v12
	v_rcp_f32_e32 v13, v13
	v_mul_f32_e32 v70, v71, v71
	v_mul_f32_e32 v64, v65, v65
	v_pk_add_f32 v[10:11], v[52:53], v[10:11]
	v_mul_f32_e32 v72, v73, v73
	v_mul_f32_e32 v24, v25, v25
	v_pk_add_f32 v[8:9], v[10:11], v[8:9]
	v_pk_add_f32 v[10:11], v[70:71], v[64:65]
	v_pk_mul_f32 v[14:15], v[4:5], v[4:5]
	v_pk_add_f32 v[8:9], v[10:11], v[8:9]
	v_pk_add_f32 v[10:11], v[72:73], v[24:25]
	v_pk_mul_f32 v[14:15], v[14:15], s[64:65] op_sel_hi:[1,0]
	v_pk_add_f32 v[8:9], v[10:11], v[8:9]
	v_pk_fma_f32 v[10:11], v[12:13], s[42:43], v[22:23] op_sel_hi:[1,0,0]
	v_exp_f32_e32 v14, v14
	v_pk_fma_f32 v[10:11], v[12:13], v[10:11], s[48:49] op_sel_hi:[1,1,0]
	v_exp_f32_e32 v15, v15
	v_pk_fma_f32 v[10:11], v[12:13], v[10:11], s[50:51] op_sel_hi:[1,1,0]
	v_cmp_gt_f32_e64 s[0:1], 0, v4
	v_pk_fma_f32 v[10:11], v[12:13], v[10:11], s[56:57] op_sel_hi:[1,1,0]
	s_waitcnt vmcnt(0)
	v_lshlrev_b32_e32 v28, 16, v60
	v_pk_mul_f32 v[10:11], v[12:13], v[10:11]
	v_and_b32_e32 v29, 0xffff0000, v60
	v_pk_mul_f32 v[10:11], v[14:15], v[10:11]
	v_and_b32_e32 v31, 0x7fffffff, v29
	v_pk_mul_f32 v[12:13], v[4:5], v[10:11]
	v_pk_fma_f32 v[10:11], v[4:5], v[10:11], v[4:5] neg_lo:[1,0,0] neg_hi:[1,0,0]
	v_and_b32_e32 v30, 0x7fffffff, v28
	v_cndmask_b32_e64 v15, v10, v12, s[0:1]
	v_cmp_gt_f32_e64 s[0:1], 0, v5
	v_lshlrev_b32_e32 v10, 16, v6
	v_and_b32_e32 v12, 0x7fffffff, v10
	v_cndmask_b32_e64 v5, v11, v13, s[0:1]
	v_and_b32_e32 v11, 0xffff0000, v6
	v_and_b32_e32 v13, 0x7fffffff, v11
	v_pk_fma_f32 v[12:13], v[12:13], s[40:41], 1.0 op_sel_hi:[1,0,0]
	v_mul_f32_e32 v14, v15, v15
	v_rcp_f32_e32 v12, v12
	v_rcp_f32_e32 v13, v13
	v_mul_f32_e32 v4, v5, v5
	v_pk_mul_f32 v[24:25], v[10:11], v[10:11]
	v_pk_add_f32 v[4:5], v[14:15], v[4:5]
	v_pk_fma_f32 v[14:15], v[12:13], s[42:43], v[22:23] op_sel_hi:[1,0,0]
	v_pk_mul_f32 v[24:25], v[24:25], s[64:65] op_sel_hi:[1,0]
	v_pk_fma_f32 v[14:15], v[12:13], v[14:15], s[48:49] op_sel_hi:[1,1,0]
	v_exp_f32_e32 v24, v24
	v_exp_f32_e32 v25, v25
	v_pk_fma_f32 v[14:15], v[12:13], v[14:15], s[50:51] op_sel_hi:[1,1,0]
	v_lshlrev_b32_e32 v6, 16, v7
	v_and_b32_e32 v7, 0xffff0000, v7
	v_pk_fma_f32 v[14:15], v[12:13], v[14:15], s[56:57] op_sel_hi:[1,1,0]
	v_pk_mul_f32 v[12:13], v[12:13], v[14:15]
	v_fma_f32 v26, |v6|, s40, 1.0
	v_fma_f32 v27, |v7|, s40, 1.0
	v_pk_mul_f32 v[12:13], v[24:25], v[12:13]
	v_rcp_f32_e32 v26, v26
	v_rcp_f32_e32 v27, v27
	v_max_f32_e32 v82, 0, v10
	v_fma_f32 v25, -|v10|, v12, v82
	v_max_f32_e32 v83, 0, v11
	v_fma_f32 v11, -|v11|, v13, v83
	v_pk_fma_f32 v[30:31], v[30:31], s[40:41], 1.0 op_sel_hi:[1,0,0]
	v_lshlrev_b32_e32 v32, 16, v61
	v_rcp_f32_e32 v30, v30
	v_rcp_f32_e32 v31, v31
	v_pk_mul_f32 v[14:15], v[6:7], v[6:7]
	v_pk_fma_f32 v[12:13], v[26:27], s[42:43], v[22:23] op_sel_hi:[1,0,0]
	v_pk_mul_f32 v[14:15], v[14:15], s[64:65] op_sel_hi:[1,0]
	v_pk_fma_f32 v[12:13], v[26:27], v[12:13], s[48:49] op_sel_hi:[1,1,0]
	v_exp_f32_e32 v14, v14
	v_exp_f32_e32 v15, v15
	v_pk_fma_f32 v[12:13], v[26:27], v[12:13], s[50:51] op_sel_hi:[1,1,0]
	v_cmp_gt_f32_e64 s[0:1], 0, v6
	v_pk_fma_f32 v[12:13], v[26:27], v[12:13], s[56:57] op_sel_hi:[1,1,0]
	v_and_b32_e32 v33, 0xffff0000, v61
	v_pk_mul_f32 v[12:13], v[26:27], v[12:13]
	v_pk_mul_f32 v[12:13], v[14:15], v[12:13]
	v_pk_mul_f32 v[14:15], v[6:7], v[12:13]
	v_pk_fma_f32 v[12:13], v[6:7], v[12:13], v[6:7] neg_lo:[1,0,0] neg_hi:[1,0,0]
	v_fma_f32 v34, |v32|, s40, 1.0
	v_fma_f32 v35, |v33|, s40, 1.0
	v_cndmask_b32_e64 v27, v12, v14, s[0:1]
	v_cmp_gt_f32_e64 s[0:1], 0, v7
	v_rcp_f32_e32 v34, v34
	v_rcp_f32_e32 v35, v35
	v_cndmask_b32_e64 v7, v13, v15, s[0:1]
	v_pk_mul_f32 v[14:15], v[28:29], v[28:29]
	v_pk_fma_f32 v[12:13], v[30:31], s[42:43], v[22:23] op_sel_hi:[1,0,0]
	v_pk_mul_f32 v[14:15], v[14:15], s[64:65] op_sel_hi:[1,0]
	v_pk_fma_f32 v[12:13], v[30:31], v[12:13], s[48:49] op_sel_hi:[1,1,0]
	v_exp_f32_e32 v14, v14
	v_exp_f32_e32 v15, v15
	v_pk_fma_f32 v[12:13], v[30:31], v[12:13], s[50:51] op_sel_hi:[1,1,0]
	v_cmp_gt_f32_e64 s[0:1], 0, v28
	v_pk_fma_f32 v[12:13], v[30:31], v[12:13], s[56:57] op_sel_hi:[1,1,0]
	v_lshlrev_b32_e32 v36, 16, v62
	v_pk_mul_f32 v[12:13], v[30:31], v[12:13]
	v_and_b32_e32 v37, 0xffff0000, v62
	v_pk_mul_f32 v[12:13], v[14:15], v[12:13]
	v_pk_mul_f32 v[14:15], v[28:29], v[12:13]
	v_pk_fma_f32 v[12:13], v[28:29], v[12:13], v[28:29] neg_lo:[1,0,0] neg_hi:[1,0,0]
	v_cndmask_b32_e64 v31, v12, v14, s[0:1]
	v_cmp_gt_f32_e64 s[0:1], 0, v29
	v_pk_mul_f32 v[28:29], v[32:33], v[32:33]
	v_fma_f32 v38, |v36|, s40, 1.0
	v_fma_f32 v39, |v37|, s40, 1.0
	v_cndmask_b32_e64 v13, v13, v15, s[0:1]
	v_pk_fma_f32 v[14:15], v[34:35], s[42:43], v[22:23] op_sel_hi:[1,0,0]
	v_pk_mul_f32 v[28:29], v[28:29], s[64:65] op_sel_hi:[1,0]
	v_pk_fma_f32 v[14:15], v[34:35], v[14:15], s[48:49] op_sel_hi:[1,1,0]
	v_exp_f32_e32 v28, v28
	v_exp_f32_e32 v29, v29
	v_pk_fma_f32 v[14:15], v[34:35], v[14:15], s[50:51] op_sel_hi:[1,1,0]
	v_rcp_f32_e32 v38, v38
	v_pk_fma_f32 v[14:15], v[34:35], v[14:15], s[56:57] op_sel_hi:[1,1,0]
	v_rcp_f32_e32 v39, v39
	v_pk_mul_f32 v[14:15], v[34:35], v[14:15]
	v_cmp_gt_f32_e64 s[0:1], 0, v32
	v_pk_mul_f32 v[14:15], v[28:29], v[14:15]
	v_lshlrev_b32_e32 v40, 16, v63
	v_pk_mul_f32 v[28:29], v[32:33], v[14:15]
	v_pk_fma_f32 v[14:15], v[32:33], v[14:15], v[32:33] neg_lo:[1,0,0] neg_hi:[1,0,0]
	v_and_b32_e32 v41, 0xffff0000, v63
	v_cndmask_b32_e64 v35, v14, v28, s[0:1]
	v_cmp_gt_f32_e64 s[0:1], 0, v33
	v_pk_mul_f32 v[32:33], v[36:37], v[36:37]
	v_cndmask_b32_e64 v15, v15, v29, s[0:1]
	v_pk_fma_f32 v[28:29], v[38:39], s[42:43], v[22:23] op_sel_hi:[1,0,0]
	v_pk_mul_f32 v[32:33], v[32:33], s[64:65] op_sel_hi:[1,0]
	v_pk_fma_f32 v[28:29], v[38:39], v[28:29], s[48:49] op_sel_hi:[1,1,0]
	v_exp_f32_e32 v32, v32
	v_exp_f32_e32 v33, v33
	v_pk_fma_f32 v[28:29], v[38:39], v[28:29], s[50:51] op_sel_hi:[1,1,0]
	v_pk_fma_f32 v[28:29], v[38:39], v[28:29], s[56:57] op_sel_hi:[1,1,0]
	v_fma_f32 v42, |v40|, s40, 1.0
	v_fma_f32 v43, |v41|, s40, 1.0
	v_pk_mul_f32 v[28:29], v[38:39], v[28:29]
	v_rcp_f32_e32 v42, v42
	v_pk_mul_f32 v[28:29], v[32:33], v[28:29]
	v_rcp_f32_e32 v43, v43
	v_max_f32_e32 v84, 0, v36
	v_fma_f32 v39, -|v36|, v28, v84
	v_max_f32_e32 v85, 0, v37
	v_fma_f32 v29, -|v37|, v29, v85
	v_pk_fma_f32 v[22:23], v[42:43], s[42:43], v[22:23] op_sel_hi:[1,0,0]
	v_mul_f32_e32 v24, v25, v25
	v_pk_fma_f32 v[22:23], v[42:43], v[22:23], s[48:49] op_sel_hi:[1,1,0]
	v_mul_f32_e32 v10, v11, v11
	v_pk_mul_f32 v[32:33], v[40:41], v[40:41]
	v_pk_fma_f32 v[22:23], v[42:43], v[22:23], s[50:51] op_sel_hi:[1,1,0]
	v_pk_mul_f32 v[32:33], v[32:33], s[64:65] op_sel_hi:[1,0]
	v_pk_fma_f32 v[22:23], v[42:43], v[22:23], s[56:57] op_sel_hi:[1,1,0]
	v_exp_f32_e32 v32, v32
	v_exp_f32_e32 v33, v33
	v_pk_mul_f32 v[22:23], v[42:43], v[22:23]
	v_mul_f32_e32 v26, v27, v27
	v_mul_f32_e32 v6, v7, v7
	v_pk_mul_f32 v[22:23], v[32:33], v[22:23]
	v_pk_add_f32 v[4:5], v[4:5], v[8:9]
	v_pk_add_f32 v[8:9], v[24:25], v[10:11]
	v_mul_f32_e32 v30, v31, v31
	v_mul_f32_e32 v12, v13, v13
	v_max_f32_e32 v86, 0, v40
	v_fma_f32 v37, -|v40|, v22, v86
	v_max_f32_e32 v90, 0, v41
	v_fma_f32 v23, -|v41|, v23, v90
	v_pk_add_f32 v[4:5], v[8:9], v[4:5]
	v_pk_add_f32 v[6:7], v[26:27], v[6:7]
	v_mul_f32_e32 v34, v35, v35
	v_mul_f32_e32 v14, v15, v15
	v_pk_add_f32 v[4:5], v[6:7], v[4:5]
	v_pk_add_f32 v[6:7], v[30:31], v[12:13]
	v_mul_f32_e32 v38, v39, v39
	v_mul_f32_e32 v28, v29, v29
	v_pk_add_f32 v[4:5], v[6:7], v[4:5]
	v_pk_add_f32 v[6:7], v[34:35], v[14:15]
	v_mul_f32_e32 v36, v37, v37
	v_mul_f32_e32 v22, v23, v23
	v_pk_add_f32 v[4:5], v[6:7], v[4:5]
	v_pk_add_f32 v[6:7], v[38:39], v[28:29]
	s_nop 0
	v_pk_add_f32 v[4:5], v[6:7], v[4:5]
	v_pk_add_f32 v[6:7], v[36:37], v[22:23]
	s_nop 0
	v_pk_add_f32 v[4:5], v[6:7], v[4:5]
	ds_bpermute_b32 v7, v56, v5
	ds_bpermute_b32 v6, v56, v4
	s_waitcnt lgkmcnt(0)
	v_pk_add_f32 v[4:5], v[4:5], v[6:7]
	ds_bpermute_b32 v7, v57, v5
	ds_bpermute_b32 v6, v57, v4
	s_waitcnt lgkmcnt(0)
	v_pk_add_f32 v[4:5], v[4:5], v[6:7]
	ds_bpermute_b32 v7, v58, v5
	ds_bpermute_b32 v6, v58, v4
	s_waitcnt lgkmcnt(0)
	v_pk_add_f32 v[4:5], v[4:5], v[6:7]
	ds_bpermute_b32 v7, v59, v5
	ds_bpermute_b32 v6, v59, v4
	s_and_saveexec_b64 s[8:9], vcc
	s_cbranch_execz .LBB0_449
	s_waitcnt lgkmcnt(0)
	v_pk_add_f32 v[4:5], v[4:5], v[6:7]
	s_nop 0
	v_pk_mul_f32 v[4:5], v[4:5], s[66:67] op_sel_hi:[1,0]
	s_nop 0
	v_fma_f32 v4, -v5, v5, v4
	v_max_f32_e32 v4, 0, v4
	v_add_f32_e32 v4, 0x358637bd, v4
	v_mul_f32_e32 v6, 0x4b800000, v4
	v_cmp_gt_f32_e64 s[0:1], s36, v4
	s_nop 1
	v_cndmask_b32_e64 v4, v4, v6, s[0:1]
	v_rsq_f32_e32 v4, v4
	v_lshl_add_u32 v6, v20, 2, 0
	v_add_u32_e32 v7, 0x11000, v6
	ds_write_b32 v7, v5
	v_mul_f32_e32 v5, 0x45800000, v4
	v_cndmask_b32_e64 v4, v4, v5, s[0:1]
	v_add_u32_e32 v5, 0x11200, v6
	ds_write_b32 v5, v4
.LBB0_449:
	s_or_b64 exec, exec, s[8:9]
	v_or_b32_e32 v16, 12, v16
	v_ashrrev_i32_e32 v17, 31, v16
	v_lshl_add_u64 v[4:5], s[6:7], 0, v[16:17]
	v_lshlrev_b64 v[4:5], 11, v[4:5]
	v_lshl_add_u64 v[4:5], s[4:5], 0, v[4:5]
	v_mov_b32_e32 v19, v2
	v_lshl_add_u64 v[20:21], v[4:5], 0, v[18:19]
	global_load_dwordx4 v[8:11], v[20:21], off
	s_waitcnt lgkmcnt(0)
	global_load_dwordx4 v[4:7], v[20:21], off offset:256
	v_mov_b64_e32 v[18:19], s[44:45]
	v_mov_b32_e32 v13, v2
	s_waitcnt vmcnt(1)
	v_lshlrev_b32_e32 v24, 16, v10
	v_and_b32_e32 v25, 0xffff0000, v10
	v_and_b32_e32 v15, 0xffff0000, v8
	v_and_b32_e32 v23, 0xffff0000, v9
	v_lshlrev_b32_e32 v22, 16, v9
	v_lshlrev_b32_e32 v14, 16, v8
	v_lshlrev_b32_e32 v8, 16, v11
	v_and_b32_e32 v9, 0xffff0000, v11
	v_fma_f32 v10, |v24|, s40, 1.0
	v_fma_f32 v11, |v25|, s40, 1.0
	v_fma_f32 v28, |v14|, s40, 1.0
	v_fma_f32 v29, |v15|, s40, 1.0
	v_rcp_f32_e32 v10, v10
	v_rcp_f32_e32 v11, v11
	v_fma_f32 v32, |v22|, s40, 1.0
	v_fma_f32 v33, |v23|, s40, 1.0
	v_rcp_f32_e32 v28, v28
	v_rcp_f32_e32 v29, v29
	v_rcp_f32_e32 v32, v32
	v_rcp_f32_e32 v33, v33
	v_pk_mul_f32 v[26:27], v[24:25], v[24:25]
	v_pk_mul_f32 v[30:31], v[14:15], v[14:15]
	v_pk_mul_f32 v[26:27], v[26:27], s[64:65] op_sel_hi:[1,0]
	v_pk_fma_f32 v[40:41], v[10:11], s[42:43], v[18:19] op_sel_hi:[1,0,0]
	v_pk_mul_f32 v[34:35], v[22:23], v[22:23]
	v_pk_mul_f32 v[30:31], v[30:31], s[64:65] op_sel_hi:[1,0]
	v_exp_f32_e32 v26, v26
	v_exp_f32_e32 v27, v27
	v_pk_fma_f32 v[42:43], v[28:29], s[42:43], v[18:19] op_sel_hi:[1,0,0]
	v_pk_fma_f32 v[40:41], v[10:11], v[40:41], s[48:49] op_sel_hi:[1,1,0]
	v_pk_mul_f32 v[34:35], v[34:35], s[64:65] op_sel_hi:[1,0]
	v_exp_f32_e32 v30, v30
	v_exp_f32_e32 v31, v31
	v_pk_fma_f32 v[44:45], v[32:33], s[42:43], v[18:19] op_sel_hi:[1,0,0]
	v_pk_fma_f32 v[42:43], v[28:29], v[42:43], s[48:49] op_sel_hi:[1,1,0]
	v_pk_fma_f32 v[40:41], v[10:11], v[40:41], s[50:51] op_sel_hi:[1,1,0]
	v_exp_f32_e32 v34, v34
	v_exp_f32_e32 v35, v35
	v_pk_fma_f32 v[44:45], v[32:33], v[44:45], s[48:49] op_sel_hi:[1,1,0]
	v_pk_fma_f32 v[42:43], v[28:29], v[42:43], s[50:51] op_sel_hi:[1,1,0]
	v_pk_fma_f32 v[40:41], v[10:11], v[40:41], s[56:57] op_sel_hi:[1,1,0]
	v_pk_fma_f32 v[44:45], v[32:33], v[44:45], s[50:51] op_sel_hi:[1,1,0]
	v_pk_fma_f32 v[42:43], v[28:29], v[42:43], s[56:57] op_sel_hi:[1,1,0]
	v_pk_mul_f32 v[10:11], v[10:11], v[40:41]
	v_pk_fma_f32 v[44:45], v[32:33], v[44:45], s[56:57] op_sel_hi:[1,1,0]
	v_pk_mul_f32 v[28:29], v[28:29], v[42:43]
	v_pk_mul_f32 v[10:11], v[26:27], v[10:11]
	v_pk_mul_f32 v[32:33], v[32:33], v[44:45]
	v_pk_mul_f32 v[26:27], v[30:31], v[28:29]
	v_max_f32_e32 v91, 0, v24
	v_fma_f32 v41, -|v24|, v10, v91
	v_max_f32_e32 v92, 0, v25
	v_fma_f32 v11, -|v25|, v11, v92
	v_pk_mul_f32 v[28:29], v[34:35], v[32:33]
	v_max_f32_e32 v93, 0, v22
	v_fma_f32 v25, -|v22|, v28, v93
	v_max_f32_e32 v94, 0, v23
	v_fma_f32 v23, -|v23|, v29, v94
	v_pk_mul_f32 v[32:33], v[26:27], v[14:15]
	v_pk_fma_f32 v[26:27], v[26:27], v[14:15], v[14:15] neg_lo:[1,0,0] neg_hi:[1,0,0]
	v_cmp_gt_f32_e64 s[0:1], 0, v14
	v_fma_f32 v36, |v8|, s40, 1.0
	v_fma_f32 v37, |v9|, s40, 1.0
	v_mov_b32_e32 v14, v25
	v_cndmask_b32_e64 v24, v26, v32, s[0:1]
	v_cmp_gt_f32_e64 s[0:1], 0, v15
	v_rcp_f32_e32 v36, v36
	v_rcp_f32_e32 v37, v37
	v_cndmask_b32_e64 v15, v27, v33, s[0:1]
	v_mul_f32_e32 v26, v24, v24
	v_mov_b32_e32 v27, v25
	v_mul_f32_e32 v22, v15, v15
	v_mul_f32_e32 v12, v23, v23
	v_pk_add_f32 v[22:23], v[26:27], v[22:23]
	v_pk_mul_f32 v[26:27], v[24:25], v[14:15] op_sel:[1,0] op_sel_hi:[0,1]
	v_pk_add_f32 v[14:15], v[24:25], v[14:15] op_sel:[1,0] op_sel_hi:[0,1]
	v_pk_mul_f32 v[38:39], v[8:9], v[8:9]
	v_mov_b32_e32 v27, v15
	v_pk_mul_f32 v[38:39], v[38:39], s[64:65] op_sel_hi:[1,0]
	v_pk_fma_f32 v[46:47], v[36:37], s[42:43], v[18:19] op_sel_hi:[1,0,0]
	v_mul_f32_e32 v40, v41, v41
	v_mul_f32_e32 v10, v11, v11
	v_pk_add_f32 v[12:13], v[26:27], v[12:13]
	v_exp_f32_e32 v38, v38
	v_pk_fma_f32 v[46:47], v[36:37], v[46:47], s[48:49] op_sel_hi:[1,1,0]
	v_pk_add_f32 v[10:11], v[40:41], v[10:11]
	v_pk_add_f32 v[12:13], v[22:23], v[12:13]
	v_exp_f32_e32 v39, v39
	v_pk_add_f32 v[22:23], v[10:11], v[12:13]
	v_pk_fma_f32 v[10:11], v[36:37], v[46:47], s[50:51] op_sel_hi:[1,1,0]
	v_cmp_gt_f32_e64 s[0:1], 0, v8
	v_pk_fma_f32 v[10:11], v[36:37], v[10:11], s[56:57] op_sel_hi:[1,1,0]
	s_nop 0
	v_pk_mul_f32 v[10:11], v[36:37], v[10:11]
	s_waitcnt vmcnt(0)
	v_lshlrev_b32_e32 v36, 16, v6
	v_pk_mul_f32 v[10:11], v[38:39], v[10:11]
	v_and_b32_e32 v37, 0xffff0000, v6
	v_pk_mul_f32 v[12:13], v[8:9], v[10:11]
	v_pk_fma_f32 v[10:11], v[8:9], v[10:11], v[8:9] neg_lo:[1,0,0] neg_hi:[1,0,0]
	v_and_b32_e32 v33, 0x7fffffff, v37
	v_cndmask_b32_e64 v15, v10, v12, s[0:1]
	v_cmp_gt_f32_e64 s[0:1], 0, v9
	v_lshlrev_b32_e32 v12, 16, v4
	v_and_b32_e32 v10, 0x7fffffff, v12
	v_cndmask_b32_e64 v9, v11, v13, s[0:1]
	v_and_b32_e32 v13, 0xffff0000, v4
	v_and_b32_e32 v11, 0x7fffffff, v13
	v_pk_fma_f32 v[10:11], v[10:11], s[40:41], 1.0 op_sel_hi:[1,0,0]
	v_mul_f32_e32 v14, v15, v15
	v_rcp_f32_e32 v10, v10
	v_rcp_f32_e32 v11, v11
	v_mul_f32_e32 v8, v9, v9
	v_pk_add_f32 v[24:25], v[14:15], v[8:9]
	v_pk_mul_f32 v[14:15], v[12:13], v[12:13]
	v_pk_fma_f32 v[8:9], v[10:11], s[42:43], v[18:19] op_sel_hi:[1,0,0]
	v_pk_mul_f32 v[14:15], v[14:15], s[64:65] op_sel_hi:[1,0]
	v_pk_fma_f32 v[8:9], v[10:11], v[8:9], s[48:49] op_sel_hi:[1,1,0]
	v_exp_f32_e32 v14, v14
	v_exp_f32_e32 v15, v15
	v_pk_fma_f32 v[8:9], v[10:11], v[8:9], s[50:51] op_sel_hi:[1,1,0]
	v_lshlrev_b32_e32 v4, 16, v5
	v_pk_fma_f32 v[8:9], v[10:11], v[8:9], s[56:57] op_sel_hi:[1,1,0]
	v_and_b32_e32 v5, 0xffff0000, v5
	v_pk_mul_f32 v[8:9], v[10:11], v[8:9]
	v_pk_mul_f32 v[14:15], v[14:15], v[8:9]
	global_load_dwordx4 v[8:11], v[20:21], off offset:512
	v_fma_f32 v30, |v4|, s40, 1.0
	v_fma_f32 v31, |v5|, s40, 1.0
	v_rcp_f32_e32 v30, v30
	v_rcp_f32_e32 v31, v31
	v_max_f32_e32 v95, 0, v12
	v_fma_f32 v27, -|v12|, v14, v95
	v_max_f32_e32 v96, 0, v13
	v_fma_f32 v29, -|v13|, v15, v96
	v_and_b32_e32 v32, 0x7fffffff, v36
	v_pk_fma_f32 v[32:33], v[32:33], s[40:41], 1.0 op_sel_hi:[1,0,0]
	v_pk_fma_f32 v[12:13], v[30:31], s[42:43], v[18:19] op_sel_hi:[1,0,0]
	v_rcp_f32_e32 v34, v32
	v_pk_mul_f32 v[14:15], v[4:5], v[4:5]
	v_pk_fma_f32 v[12:13], v[30:31], v[12:13], s[48:49] op_sel_hi:[1,1,0]
	v_pk_mul_f32 v[14:15], v[14:15], s[64:65] op_sel_hi:[1,0]
	v_pk_fma_f32 v[12:13], v[30:31], v[12:13], s[50:51] op_sel_hi:[1,1,0]
	v_exp_f32_e32 v14, v14
	v_exp_f32_e32 v15, v15
	v_pk_fma_f32 v[12:13], v[30:31], v[12:13], s[56:57] op_sel_hi:[1,1,0]
	v_rcp_f32_e32 v35, v33
	v_pk_mul_f32 v[12:13], v[30:31], v[12:13]
	v_cmp_gt_f32_e64 s[0:1], 0, v4
	v_pk_mul_f32 v[12:13], v[14:15], v[12:13]
	v_mul_f32_e32 v26, v27, v27
	v_pk_mul_f32 v[14:15], v[4:5], v[12:13]
	v_pk_fma_f32 v[12:13], v[4:5], v[12:13], v[4:5] neg_lo:[1,0,0] neg_hi:[1,0,0]
	v_mul_f32_e32 v28, v29, v29
	v_cndmask_b32_e64 v31, v12, v14, s[0:1]
	v_cmp_gt_f32_e64 s[0:1], 0, v5
	v_pk_fma_f32 v[4:5], v[34:35], s[42:43], v[18:19] op_sel_hi:[1,0,0]
	v_lshlrev_b32_e32 v14, 16, v7
	v_cndmask_b32_e64 v33, v13, v15, s[0:1]
	v_pk_mul_f32 v[12:13], v[36:37], v[36:37]
	v_pk_fma_f32 v[4:5], v[34:35], v[4:5], s[48:49] op_sel_hi:[1,1,0]
	v_pk_mul_f32 v[12:13], v[12:13], s[64:65] op_sel_hi:[1,0]
	v_pk_fma_f32 v[4:5], v[34:35], v[4:5], s[50:51] op_sel_hi:[1,1,0]
	v_exp_f32_e32 v12, v12
	v_exp_f32_e32 v13, v13
	v_and_b32_e32 v15, 0xffff0000, v7
	v_pk_fma_f32 v[4:5], v[34:35], v[4:5], s[56:57] op_sel_hi:[1,1,0]
	v_pk_mul_f32 v[4:5], v[34:35], v[4:5]
	v_fma_f32 v6, |v14|, s40, 1.0
	v_fma_f32 v7, |v15|, s40, 1.0
	v_pk_mul_f32 v[4:5], v[12:13], v[4:5]
	v_rcp_f32_e32 v6, v6
	v_rcp_f32_e32 v7, v7
	v_max_f32_e32 v97, 0, v36
	v_fma_f32 v35, -|v36|, v4, v97
	v_max_f32_e32 v98, 0, v37
	v_fma_f32 v37, -|v37|, v5, v98
	v_mul_f32_e32 v30, v31, v31
	v_mul_f32_e32 v32, v33, v33
	v_pk_add_f32 v[22:23], v[24:25], v[22:23]
	v_pk_add_f32 v[24:25], v[26:27], v[28:29]
	v_pk_mul_f32 v[12:13], v[14:15], v[14:15]
	v_pk_fma_f32 v[4:5], v[6:7], s[42:43], v[18:19] op_sel_hi:[1,0,0]
	v_pk_mul_f32 v[12:13], v[12:13], s[64:65] op_sel_hi:[1,0]
	v_pk_fma_f32 v[4:5], v[6:7], v[4:5], s[48:49] op_sel_hi:[1,1,0]
	v_exp_f32_e32 v12, v12
	v_exp_f32_e32 v13, v13
	v_pk_fma_f32 v[4:5], v[6:7], v[4:5], s[50:51] op_sel_hi:[1,1,0]
	v_cmp_gt_f32_e64 s[0:1], 0, v14
	v_pk_fma_f32 v[4:5], v[6:7], v[4:5], s[56:57] op_sel_hi:[1,1,0]
	v_mul_f32_e32 v34, v35, v35
	v_pk_mul_f32 v[4:5], v[6:7], v[4:5]
	v_mul_f32_e32 v36, v37, v37
	v_pk_mul_f32 v[4:5], v[12:13], v[4:5]
	v_pk_add_f32 v[22:23], v[24:25], v[22:23]
	v_pk_mul_f32 v[12:13], v[14:15], v[4:5]
	v_pk_fma_f32 v[40:41], v[14:15], v[4:5], v[14:15] neg_lo:[1,0,0] neg_hi:[1,0,0]
	global_load_dwordx4 v[4:7], v[20:21], off offset:768
	v_cndmask_b32_e64 v39, v40, v12, s[0:1]
	v_cmp_gt_f32_e64 s[0:1], 0, v15
	v_pk_add_f32 v[24:25], v[30:31], v[32:33]
	s_waitcnt vmcnt(1)
	v_lshlrev_b32_e32 v44, 16, v8
	v_and_b32_e32 v45, 0xffff0000, v8
	v_fma_f32 v42, |v44|, s40, 1.0
	v_fma_f32 v43, |v45|, s40, 1.0
	v_pk_mul_f32 v[14:15], v[44:45], v[44:45]
	v_rcp_f32_e32 v42, v42
	v_rcp_f32_e32 v43, v43
	v_cndmask_b32_e64 v41, v41, v13, s[0:1]
	v_pk_mul_f32 v[14:15], v[14:15], s[64:65] op_sel_hi:[1,0]
	v_lshlrev_b32_e32 v46, 16, v9
	v_pk_fma_f32 v[12:13], v[42:43], s[42:43], v[18:19] op_sel_hi:[1,0,0]
	v_exp_f32_e32 v14, v14
	v_pk_fma_f32 v[12:13], v[42:43], v[12:13], s[48:49] op_sel_hi:[1,1,0]
	v_exp_f32_e32 v15, v15
	v_and_b32_e32 v47, 0xffff0000, v9
	v_pk_fma_f32 v[12:13], v[42:43], v[12:13], s[50:51] op_sel_hi:[1,1,0]
	v_pk_fma_f32 v[12:13], v[42:43], v[12:13], s[56:57] op_sel_hi:[1,1,0]
	v_fma_f32 v8, |v46|, s40, 1.0
	v_fma_f32 v9, |v47|, s40, 1.0
	v_pk_mul_f32 v[12:13], v[42:43], v[12:13]
	v_rcp_f32_e32 v48, v8
	v_rcp_f32_e32 v49, v9
	v_pk_mul_f32 v[12:13], v[14:15], v[12:13]
	v_cmp_gt_f32_e64 s[0:1], 0, v44
	v_pk_mul_f32 v[14:15], v[44:45], v[12:13]
	v_pk_fma_f32 v[12:13], v[44:45], v[12:13], v[44:45] neg_lo:[1,0,0] neg_hi:[1,0,0]
	v_lshlrev_b32_e32 v50, 16, v10
	v_cndmask_b32_e64 v43, v12, v14, s[0:1]
	v_cmp_gt_f32_e64 s[0:1], 0, v45
	v_and_b32_e32 v51, 0xffff0000, v10
	v_lshlrev_b32_e32 v10, 16, v11
	v_cndmask_b32_e64 v9, v13, v15, s[0:1]
	v_pk_fma_f32 v[12:13], v[48:49], s[42:43], v[18:19] op_sel_hi:[1,0,0]
	v_pk_mul_f32 v[14:15], v[46:47], v[46:47]
	v_pk_fma_f32 v[12:13], v[48:49], v[12:13], s[48:49] op_sel_hi:[1,1,0]
	v_pk_mul_f32 v[14:15], v[14:15], s[64:65] op_sel_hi:[1,0]
	v_pk_fma_f32 v[12:13], v[48:49], v[12:13], s[50:51] op_sel_hi:[1,1,0]
	v_exp_f32_e32 v14, v14
	v_exp_f32_e32 v15, v15
	v_pk_fma_f32 v[12:13], v[48:49], v[12:13], s[56:57] op_sel_hi:[1,1,0]
	v_cmp_gt_f32_e64 s[0:1], 0, v46
	v_pk_mul_f32 v[12:13], v[48:49], v[12:13]
	v_fma_f32 v48, |v50|, s40, 1.0
	v_fma_f32 v49, |v51|, s40, 1.0
	v_pk_mul_f32 v[12:13], v[14:15], v[12:13]
	v_rcp_f32_e32 v48, v48
	v_rcp_f32_e32 v49, v49
	v_pk_mul_f32 v[14:15], v[46:47], v[12:13]
	v_pk_fma_f32 v[12:13], v[46:47], v[12:13], v[46:47] neg_lo:[1,0,0] neg_hi:[1,0,0]
	v_and_b32_e32 v11, 0xffff0000, v11
	v_cndmask_b32_e64 v45, v12, v14, s[0:1]
	v_cmp_gt_f32_e64 s[0:1], 0, v47
	v_cndmask_b32_e64 v47, v13, v15, s[0:1]
	v_pk_mul_f32 v[14:15], v[50:51], v[50:51]
	v_pk_fma_f32 v[12:13], v[48:49], s[42:43], v[18:19] op_sel_hi:[1,0,0]
	v_pk_mul_f32 v[14:15], v[14:15], s[64:65] op_sel_hi:[1,0]
	v_pk_fma_f32 v[12:13], v[48:49], v[12:13], s[48:49] op_sel_hi:[1,1,0]
	v_exp_f32_e32 v14, v14
	v_exp_f32_e32 v15, v15
	v_pk_fma_f32 v[12:13], v[48:49], v[12:13], s[50:51] op_sel_hi:[1,1,0]
	v_fma_f32 v52, |v10|, s40, 1.0
	v_fma_f32 v53, |v11|, s40, 1.0
	v_pk_fma_f32 v[12:13], v[48:49], v[12:13], s[56:57] op_sel_hi:[1,1,0]
	v_rcp_f32_e32 v52, v52
	v_pk_mul_f32 v[12:13], v[48:49], v[12:13]
	v_rcp_f32_e32 v53, v53
	v_pk_mul_f32 v[12:13], v[14:15], v[12:13]
	v_cmp_gt_f32_e64 s[0:1], 0, v50
	v_pk_mul_f32 v[14:15], v[50:51], v[12:13]
	v_pk_fma_f32 v[12:13], v[50:51], v[12:13], v[50:51] neg_lo:[1,0,0] neg_hi:[1,0,0]
	v_mul_f32_e32 v38, v39, v39
	v_cndmask_b32_e64 v49, v12, v14, s[0:1]
	v_cmp_gt_f32_e64 s[0:1], 0, v51
	s_waitcnt vmcnt(0)
	v_lshlrev_b32_e32 v60, 16, v4
	v_and_b32_e32 v61, 0xffff0000, v4
	v_cndmask_b32_e64 v51, v13, v15, s[0:1]
	v_pk_mul_f32 v[14:15], v[10:11], v[10:11]
	v_pk_fma_f32 v[12:13], v[52:53], s[42:43], v[18:19] op_sel_hi:[1,0,0]
	v_pk_mul_f32 v[14:15], v[14:15], s[64:65] op_sel_hi:[1,0]
	v_pk_fma_f32 v[12:13], v[52:53], v[12:13], s[48:49] op_sel_hi:[1,1,0]
	v_exp_f32_e32 v14, v14
	v_exp_f32_e32 v15, v15
	v_pk_fma_f32 v[12:13], v[52:53], v[12:13], s[50:51] op_sel_hi:[1,1,0]
	v_pk_fma_f32 v[12:13], v[52:53], v[12:13], s[56:57] op_sel_hi:[1,1,0]
	v_pk_mul_f32 v[12:13], v[52:53], v[12:13]
	v_fma_f32 v62, |v60|, s40, 1.0
	v_fma_f32 v63, |v61|, s40, 1.0
	v_pk_mul_f32 v[12:13], v[14:15], v[12:13]
	v_rcp_f32_e32 v62, v62
	v_rcp_f32_e32 v63, v63
	v_max_f32_e32 v99, 0, v10
	v_fma_f32 v53, -|v10|, v12, v99
	v_max_f32_e32 v100, 0, v11
	v_fma_f32 v11, -|v11|, v13, v100
	v_lshlrev_b32_e32 v4, 16, v5
	v_and_b32_e32 v5, 0xffff0000, v5
	v_pk_mul_f32 v[14:15], v[60:61], v[60:61]
	v_pk_fma_f32 v[12:13], v[62:63], s[42:43], v[18:19] op_sel_hi:[1,0,0]
	v_pk_mul_f32 v[14:15], v[14:15], s[64:65] op_sel_hi:[1,0]
	v_pk_fma_f32 v[12:13], v[62:63], v[12:13], s[48:49] op_sel_hi:[1,1,0]
	v_exp_f32_e32 v14, v14
	v_exp_f32_e32 v15, v15
	v_pk_fma_f32 v[12:13], v[62:63], v[12:13], s[50:51] op_sel_hi:[1,1,0]
	v_fma_f32 v64, |v4|, s40, 1.0
	v_fma_f32 v65, |v5|, s40, 1.0
	v_pk_fma_f32 v[12:13], v[62:63], v[12:13], s[56:57] op_sel_hi:[1,1,0]
	v_rcp_f32_e32 v64, v64
	v_pk_mul_f32 v[12:13], v[62:63], v[12:13]
	v_rcp_f32_e32 v65, v65
	v_pk_mul_f32 v[12:13], v[14:15], v[12:13]
	v_cmp_gt_f32_e64 s[0:1], 0, v60
	v_pk_mul_f32 v[14:15], v[60:61], v[12:13]
	v_pk_fma_f32 v[12:13], v[60:61], v[12:13], v[60:61] neg_lo:[1,0,0] neg_hi:[1,0,0]
	v_mul_f32_e32 v40, v41, v41
	v_cndmask_b32_e64 v63, v12, v14, s[0:1]
	v_cmp_gt_f32_e64 s[0:1], 0, v61
	v_pk_add_f32 v[22:23], v[24:25], v[22:23]
	v_pk_add_f32 v[24:25], v[34:35], v[36:37]
	v_cndmask_b32_e64 v61, v13, v15, s[0:1]
	v_pk_fma_f32 v[12:13], v[64:65], s[42:43], v[18:19] op_sel_hi:[1,0,0]
	v_pk_mul_f32 v[14:15], v[4:5], v[4:5]
	v_pk_fma_f32 v[12:13], v[64:65], v[12:13], s[48:49] op_sel_hi:[1,1,0]
	v_pk_mul_f32 v[14:15], v[14:15], s[64:65] op_sel_hi:[1,0]
	v_pk_fma_f32 v[12:13], v[64:65], v[12:13], s[50:51] op_sel_hi:[1,1,0]
	v_exp_f32_e32 v66, v14
	v_exp_f32_e32 v67, v15
	v_pk_fma_f32 v[68:69], v[64:65], v[12:13], s[56:57] op_sel_hi:[1,1,0]
	global_load_dwordx4 v[12:15], v[20:21], off offset:1024
	v_mul_f32_e32 v42, v43, v43
	v_mul_f32_e32 v8, v9, v9
	v_pk_add_f32 v[22:23], v[24:25], v[22:23]
	v_pk_add_f32 v[24:25], v[38:39], v[40:41]
	v_mul_f32_e32 v44, v45, v45
	v_mul_f32_e32 v46, v47, v47
	v_pk_add_f32 v[22:23], v[24:25], v[22:23]
	v_pk_add_f32 v[8:9], v[42:43], v[8:9]
	v_mul_f32_e32 v48, v49, v49
	v_mul_f32_e32 v50, v51, v51
	v_pk_mul_f32 v[64:65], v[64:65], v[68:69]
	v_pk_add_f32 v[8:9], v[8:9], v[22:23]
	v_pk_add_f32 v[22:23], v[44:45], v[46:47]
	v_pk_mul_f32 v[64:65], v[66:67], v[64:65]
	v_pk_add_f32 v[8:9], v[22:23], v[8:9]
	v_pk_add_f32 v[22:23], v[48:49], v[50:51]
	v_lshlrev_b32_e32 v24, 16, v6
	v_and_b32_e32 v25, 0xffff0000, v6
	v_max_f32_e32 v104, 0, v4
	v_fma_f32 v69, -|v4|, v64, v104
	v_max_f32_e32 v105, 0, v5
	v_fma_f32 v5, -|v5|, v65, v105
	v_pk_add_f32 v[8:9], v[22:23], v[8:9]
	v_mul_f32_e32 v52, v53, v53
	v_mul_f32_e32 v10, v11, v11
	v_fma_f32 v22, |v24|, s40, 1.0
	v_fma_f32 v23, |v25|, s40, 1.0
	v_mul_f32_e32 v62, v63, v63
	v_mul_f32_e32 v60, v61, v61
	v_pk_add_f32 v[10:11], v[52:53], v[10:11]
	v_rcp_f32_e32 v26, v22
	v_rcp_f32_e32 v27, v23
	v_mul_f32_e32 v68, v69, v69
	v_mul_f32_e32 v4, v5, v5
	v_pk_add_f32 v[8:9], v[10:11], v[8:9]
	v_pk_add_f32 v[10:11], v[62:63], v[60:61]
	v_pk_add_f32 v[4:5], v[68:69], v[4:5]
	v_pk_add_f32 v[8:9], v[10:11], v[8:9]
	v_cmp_gt_f32_e64 s[0:1], 0, v24
	v_pk_add_f32 v[22:23], v[4:5], v[8:9]
	v_pk_mul_f32 v[8:9], v[24:25], v[24:25]
	v_pk_fma_f32 v[4:5], v[26:27], s[42:43], v[18:19] op_sel_hi:[1,0,0]
	v_pk_mul_f32 v[8:9], v[8:9], s[64:65] op_sel_hi:[1,0]
	v_pk_fma_f32 v[4:5], v[26:27], v[4:5], s[48:49] op_sel_hi:[1,1,0]
	v_exp_f32_e32 v8, v8
	v_exp_f32_e32 v9, v9
	v_pk_fma_f32 v[4:5], v[26:27], v[4:5], s[50:51] op_sel_hi:[1,1,0]
	v_lshlrev_b32_e32 v6, 16, v7
	v_pk_fma_f32 v[4:5], v[26:27], v[4:5], s[56:57] op_sel_hi:[1,1,0]
	v_and_b32_e32 v7, 0xffff0000, v7
	v_pk_mul_f32 v[4:5], v[26:27], v[4:5]
	s_nop 0
	v_pk_mul_f32 v[4:5], v[8:9], v[4:5]
	s_nop 0
	v_pk_mul_f32 v[8:9], v[24:25], v[4:5]
	v_pk_fma_f32 v[4:5], v[24:25], v[4:5], v[24:25] neg_lo:[1,0,0] neg_hi:[1,0,0]
	s_nop 0
	v_cndmask_b32_e64 v11, v4, v8, s[0:1]
	v_cmp_gt_f32_e64 s[0:1], 0, v25
	v_and_b32_e32 v8, 0x7fffffff, v6
	v_mul_f32_e32 v10, v11, v11
	v_cndmask_b32_e64 v5, v5, v9, s[0:1]
	v_and_b32_e32 v9, 0x7fffffff, v7
	v_pk_fma_f32 v[8:9], v[8:9], s[40:41], 1.0 op_sel_hi:[1,0,0]
	v_mul_f32_e32 v4, v5, v5
	v_rcp_f32_e32 v8, v8
	v_rcp_f32_e32 v9, v9
	v_pk_add_f32 v[24:25], v[10:11], v[4:5]
	v_pk_mul_f32 v[10:11], v[6:7], v[6:7]
	v_cmp_gt_f32_e64 s[0:1], 0, v6
	v_pk_fma_f32 v[4:5], v[8:9], s[42:43], v[18:19] op_sel_hi:[1,0,0]
	v_pk_mul_f32 v[10:11], v[10:11], s[64:65] op_sel_hi:[1,0]
	v_pk_fma_f32 v[4:5], v[8:9], v[4:5], s[48:49] op_sel_hi:[1,1,0]
	v_exp_f32_e32 v10, v10
	v_exp_f32_e32 v11, v11
	v_pk_fma_f32 v[4:5], v[8:9], v[4:5], s[50:51] op_sel_hi:[1,1,0]
	v_pk_add_f32 v[22:23], v[24:25], v[22:23]
	v_pk_fma_f32 v[4:5], v[8:9], v[4:5], s[56:57] op_sel_hi:[1,1,0]
	s_nop 0
	v_pk_mul_f32 v[4:5], v[8:9], v[4:5]
	s_nop 0
	v_pk_mul_f32 v[4:5], v[10:11], v[4:5]
	global_load_dwordx4 v[8:11], v[20:21], off offset:1280
	s_waitcnt vmcnt(1)
	v_lshlrev_b32_e32 v32, 16, v12
	v_and_b32_e32 v33, 0xffff0000, v12
	v_fma_f32 v30, |v32|, s40, 1.0
	v_fma_f32 v31, |v33|, s40, 1.0
	v_pk_mul_f32 v[28:29], v[6:7], v[4:5]
	v_rcp_f32_e32 v30, v30
	v_rcp_f32_e32 v31, v31
	v_pk_fma_f32 v[4:5], v[6:7], v[4:5], v[6:7] neg_lo:[1,0,0] neg_hi:[1,0,0]
	v_lshlrev_b32_e32 v34, 16, v13
	v_cndmask_b32_e64 v27, v4, v28, s[0:1]
	v_cmp_gt_f32_e64 s[0:1], 0, v7
	v_pk_mul_f32 v[6:7], v[32:33], v[32:33]
	v_and_b32_e32 v35, 0xffff0000, v13
	v_cndmask_b32_e64 v29, v5, v29, s[0:1]
	v_pk_fma_f32 v[4:5], v[30:31], s[42:43], v[18:19] op_sel_hi:[1,0,0]
	v_pk_mul_f32 v[6:7], v[6:7], s[64:65] op_sel_hi:[1,0]
	v_pk_fma_f32 v[4:5], v[30:31], v[4:5], s[48:49] op_sel_hi:[1,1,0]
	v_exp_f32_e32 v6, v6
	v_exp_f32_e32 v7, v7
	v_pk_fma_f32 v[4:5], v[30:31], v[4:5], s[50:51] op_sel_hi:[1,1,0]
	v_pk_fma_f32 v[4:5], v[30:31], v[4:5], s[56:57] op_sel_hi:[1,1,0]
	v_fma_f32 v12, |v34|, s40, 1.0
	v_fma_f32 v13, |v35|, s40, 1.0
	v_pk_mul_f32 v[4:5], v[30:31], v[4:5]
	v_rcp_f32_e32 v36, v12
	v_rcp_f32_e32 v37, v13
	v_pk_mul_f32 v[4:5], v[6:7], v[4:5]
	v_cmp_gt_f32_e64 s[0:1], 0, v32
	v_pk_mul_f32 v[6:7], v[32:33], v[4:5]
	v_pk_fma_f32 v[4:5], v[32:33], v[4:5], v[32:33] neg_lo:[1,0,0] neg_hi:[1,0,0]
	v_lshlrev_b32_e32 v38, 16, v14
	v_cndmask_b32_e64 v31, v4, v6, s[0:1]
	v_cmp_gt_f32_e64 s[0:1], 0, v33
	v_and_b32_e32 v39, 0xffff0000, v14
	v_lshlrev_b32_e32 v40, 16, v15
	v_cndmask_b32_e64 v13, v5, v7, s[0:1]
	v_pk_fma_f32 v[4:5], v[36:37], s[42:43], v[18:19] op_sel_hi:[1,0,0]
	v_pk_mul_f32 v[6:7], v[34:35], v[34:35]
	v_pk_fma_f32 v[4:5], v[36:37], v[4:5], s[48:49] op_sel_hi:[1,1,0]
	v_pk_mul_f32 v[6:7], v[6:7], s[64:65] op_sel_hi:[1,0]
	v_pk_fma_f32 v[4:5], v[36:37], v[4:5], s[50:51] op_sel_hi:[1,1,0]
	v_exp_f32_e32 v6, v6
	v_exp_f32_e32 v7, v7
	v_pk_fma_f32 v[4:5], v[36:37], v[4:5], s[56:57] op_sel_hi:[1,1,0]
	v_cmp_gt_f32_e64 s[0:1], 0, v34
	v_pk_mul_f32 v[4:5], v[36:37], v[4:5]
	v_fma_f32 v36, |v38|, s40, 1.0
	v_fma_f32 v37, |v39|, s40, 1.0
	v_pk_mul_f32 v[4:5], v[6:7], v[4:5]
	v_rcp_f32_e32 v36, v36
	v_rcp_f32_e32 v37, v37
	v_pk_mul_f32 v[6:7], v[34:35], v[4:5]
	v_pk_fma_f32 v[4:5], v[34:35], v[4:5], v[34:35] neg_lo:[1,0,0] neg_hi:[1,0,0]
	v_and_b32_e32 v41, 0xffff0000, v15
	v_cndmask_b32_e64 v33, v4, v6, s[0:1]
	v_cmp_gt_f32_e64 s[0:1], 0, v35
	v_cndmask_b32_e64 v35, v5, v7, s[0:1]
	v_pk_mul_f32 v[6:7], v[38:39], v[38:39]
	v_pk_fma_f32 v[4:5], v[36:37], s[42:43], v[18:19] op_sel_hi:[1,0,0]
	v_pk_mul_f32 v[6:7], v[6:7], s[64:65] op_sel_hi:[1,0]
	v_pk_fma_f32 v[4:5], v[36:37], v[4:5], s[48:49] op_sel_hi:[1,1,0]
	v_exp_f32_e32 v6, v6
	v_exp_f32_e32 v7, v7
	v_pk_fma_f32 v[4:5], v[36:37], v[4:5], s[50:51] op_sel_hi:[1,1,0]
	v_fma_f32 v14, |v40|, s40, 1.0
	v_fma_f32 v15, |v41|, s40, 1.0
	v_pk_fma_f32 v[4:5], v[36:37], v[4:5], s[56:57] op_sel_hi:[1,1,0]
	v_rcp_f32_e32 v42, v14
	v_pk_mul_f32 v[4:5], v[36:37], v[4:5]
	v_rcp_f32_e32 v43, v15
	v_pk_mul_f32 v[4:5], v[6:7], v[4:5]
	v_cmp_gt_f32_e64 s[0:1], 0, v38
	v_pk_mul_f32 v[6:7], v[38:39], v[4:5]
	v_pk_fma_f32 v[4:5], v[38:39], v[4:5], v[38:39] neg_lo:[1,0,0] neg_hi:[1,0,0]
	v_mul_f32_e32 v26, v27, v27
	v_cndmask_b32_e64 v37, v4, v6, s[0:1]
	v_cmp_gt_f32_e64 s[0:1], 0, v39
	s_waitcnt vmcnt(0)
	v_lshlrev_b32_e32 v44, 16, v8
	v_and_b32_e32 v45, 0xffff0000, v8
	v_cndmask_b32_e64 v15, v5, v7, s[0:1]
	v_pk_fma_f32 v[4:5], v[42:43], s[42:43], v[18:19] op_sel_hi:[1,0,0]
	v_pk_mul_f32 v[6:7], v[40:41], v[40:41]
	v_pk_fma_f32 v[4:5], v[42:43], v[4:5], s[48:49] op_sel_hi:[1,1,0]
	v_pk_mul_f32 v[6:7], v[6:7], s[64:65] op_sel_hi:[1,0]
	v_pk_fma_f32 v[4:5], v[42:43], v[4:5], s[50:51] op_sel_hi:[1,1,0]
	v_exp_f32_e32 v6, v6
	v_exp_f32_e32 v7, v7
	v_pk_fma_f32 v[4:5], v[42:43], v[4:5], s[56:57] op_sel_hi:[1,1,0]
	v_cmp_gt_f32_e64 s[0:1], 0, v40
	v_pk_mul_f32 v[4:5], v[42:43], v[4:5]
	v_fma_f32 v42, |v44|, s40, 1.0
	v_fma_f32 v43, |v45|, s40, 1.0
	v_pk_mul_f32 v[4:5], v[6:7], v[4:5]
	v_rcp_f32_e32 v42, v42
	v_rcp_f32_e32 v43, v43
	v_pk_mul_f32 v[6:7], v[40:41], v[4:5]
	v_pk_fma_f32 v[4:5], v[40:41], v[4:5], v[40:41] neg_lo:[1,0,0] neg_hi:[1,0,0]
	v_lshlrev_b32_e32 v50, 16, v9
	v_cndmask_b32_e64 v39, v4, v6, s[0:1]
	v_cmp_gt_f32_e64 s[0:1], 0, v41
	v_and_b32_e32 v51, 0xffff0000, v9
	v_cndmask_b32_e64 v41, v5, v7, s[0:1]
	v_pk_mul_f32 v[6:7], v[44:45], v[44:45]
	v_pk_fma_f32 v[4:5], v[42:43], s[42:43], v[18:19] op_sel_hi:[1,0,0]
	v_pk_mul_f32 v[6:7], v[6:7], s[64:65] op_sel_hi:[1,0]
	v_pk_fma_f32 v[4:5], v[42:43], v[4:5], s[48:49] op_sel_hi:[1,1,0]
	v_exp_f32_e32 v6, v6
	v_exp_f32_e32 v7, v7
	v_pk_fma_f32 v[4:5], v[42:43], v[4:5], s[50:51] op_sel_hi:[1,1,0]
	v_pk_fma_f32 v[4:5], v[42:43], v[4:5], s[56:57] op_sel_hi:[1,1,0]
	v_fma_f32 v8, |v50|, s40, 1.0
	v_fma_f32 v9, |v51|, s40, 1.0
	v_pk_mul_f32 v[4:5], v[42:43], v[4:5]
	v_rcp_f32_e32 v52, v8
	v_pk_mul_f32 v[42:43], v[6:7], v[4:5]
	global_load_dwordx4 v[4:7], v[20:21], off offset:1536
	v_rcp_f32_e32 v53, v9
	v_max_f32_e32 v107, 0, v45
	v_fma_f32 v9, -|v45|, v43, v107
	v_max_f32_e32 v106, 0, v44
	v_fma_f32 v43, -|v44|, v42, v106
	v_lshlrev_b32_e32 v62, 16, v11
	v_and_b32_e32 v63, 0xffff0000, v11
	v_pk_fma_f32 v[44:45], v[52:53], s[42:43], v[18:19] op_sel_hi:[1,0,0]
	v_and_b32_e32 v11, 0x7fffffff, v63
	v_pk_fma_f32 v[44:45], v[52:53], v[44:45], s[48:49] op_sel_hi:[1,1,0]
	v_pk_mul_f32 v[46:47], v[50:51], v[50:51]
	v_pk_fma_f32 v[44:45], v[52:53], v[44:45], s[50:51] op_sel_hi:[1,1,0]
	v_pk_mul_f32 v[46:47], v[46:47], s[64:65] op_sel_hi:[1,0]
	v_pk_fma_f32 v[44:45], v[52:53], v[44:45], s[56:57] op_sel_hi:[1,1,0]
	v_exp_f32_e32 v46, v46
	v_exp_f32_e32 v47, v47
	v_pk_mul_f32 v[44:45], v[52:53], v[44:45]
	v_lshlrev_b32_e32 v52, 16, v10
	v_and_b32_e32 v53, 0xffff0000, v10
	v_fma_f32 v60, |v52|, s40, 1.0
	v_fma_f32 v61, |v53|, s40, 1.0
	v_pk_mul_f32 v[44:45], v[46:47], v[44:45]
	v_rcp_f32_e32 v60, v60
	v_rcp_f32_e32 v61, v61
	v_max_f32_e32 v109, 0, v51
	v_fma_f32 v47, -|v51|, v45, v109
	v_max_f32_e32 v108, 0, v50
	v_fma_f32 v45, -|v50|, v44, v108
	v_and_b32_e32 v10, 0x7fffffff, v62
	v_pk_fma_f32 v[10:11], v[10:11], s[40:41], 1.0 op_sel_hi:[1,0,0]
	v_pk_mul_f32 v[50:51], v[52:53], v[52:53]
	v_rcp_f32_e32 v64, v10
	v_pk_fma_f32 v[48:49], v[60:61], s[42:43], v[18:19] op_sel_hi:[1,0,0]
	v_pk_mul_f32 v[50:51], v[50:51], s[64:65] op_sel_hi:[1,0]
	v_pk_fma_f32 v[48:49], v[60:61], v[48:49], s[48:49] op_sel_hi:[1,1,0]
	v_exp_f32_e32 v50, v50
	v_exp_f32_e32 v51, v51
	v_pk_fma_f32 v[48:49], v[60:61], v[48:49], s[50:51] op_sel_hi:[1,1,0]
	v_rcp_f32_e32 v65, v11
	v_pk_fma_f32 v[48:49], v[60:61], v[48:49], s[56:57] op_sel_hi:[1,1,0]
	v_cmp_gt_f32_e64 s[0:1], 0, v52
	v_pk_mul_f32 v[48:49], v[60:61], v[48:49]
	v_mul_f32_e32 v28, v29, v29
	v_pk_mul_f32 v[48:49], v[50:51], v[48:49]
	v_mul_f32_e32 v30, v31, v31
	v_pk_mul_f32 v[50:51], v[52:53], v[48:49]
	v_pk_fma_f32 v[60:61], v[52:53], v[48:49], v[52:53] neg_lo:[1,0,0] neg_hi:[1,0,0]
	v_mul_f32_e32 v12, v13, v13
	v_cndmask_b32_e64 v49, v60, v50, s[0:1]
	v_cmp_gt_f32_e64 s[0:1], 0, v53
	v_pk_mul_f32 v[52:53], v[62:63], v[62:63]
	v_pk_add_f32 v[24:25], v[26:27], v[28:29]
	v_cndmask_b32_e64 v11, v61, v51, s[0:1]
	v_pk_fma_f32 v[50:51], v[64:65], s[42:43], v[18:19] op_sel_hi:[1,0,0]
	v_pk_mul_f32 v[52:53], v[52:53], s[64:65] op_sel_hi:[1,0]
	v_pk_fma_f32 v[50:51], v[64:65], v[50:51], s[48:49] op_sel_hi:[1,1,0]
	v_exp_f32_e32 v52, v52
	v_exp_f32_e32 v53, v53
	v_pk_fma_f32 v[50:51], v[64:65], v[50:51], s[50:51] op_sel_hi:[1,1,0]
	v_cmp_gt_f32_e64 s[0:1], 0, v62
	v_pk_fma_f32 v[50:51], v[64:65], v[50:51], s[56:57] op_sel_hi:[1,1,0]
	v_mul_f32_e32 v32, v33, v33
	v_pk_mul_f32 v[50:51], v[64:65], v[50:51]
	v_mul_f32_e32 v34, v35, v35
	v_pk_mul_f32 v[50:51], v[52:53], v[50:51]
	v_pk_add_f32 v[22:23], v[24:25], v[22:23]
	v_pk_mul_f32 v[60:61], v[62:63], v[50:51]
	v_pk_fma_f32 v[64:65], v[62:63], v[50:51], v[62:63] neg_lo:[1,0,0] neg_hi:[1,0,0]
	global_load_dwordx4 v[50:53], v[20:21], off offset:1792
	v_cndmask_b32_e64 v67, v64, v60, s[0:1]
	v_cmp_gt_f32_e64 s[0:1], 0, v63
	v_pk_add_f32 v[12:13], v[30:31], v[12:13]
	v_mul_f32_e32 v36, v37, v37
	v_cndmask_b32_e64 v61, v65, v61, s[0:1]
	s_waitcnt vmcnt(1)
	v_lshlrev_b32_e32 v20, 16, v4
	v_and_b32_e32 v21, 0xffff0000, v4
	v_fma_f32 v68, |v20|, s40, 1.0
	v_fma_f32 v69, |v21|, s40, 1.0
	v_pk_mul_f32 v[64:65], v[20:21], v[20:21]
	v_rcp_f32_e32 v68, v68
	v_rcp_f32_e32 v69, v69
	v_mul_f32_e32 v14, v15, v15
	v_pk_mul_f32 v[64:65], v[64:65], s[64:65] op_sel_hi:[1,0]
	v_pk_add_f32 v[12:13], v[12:13], v[22:23]
	v_pk_fma_f32 v[62:63], v[68:69], s[42:43], v[18:19] op_sel_hi:[1,0,0]
	v_pk_add_f32 v[22:23], v[32:33], v[34:35]
	v_mul_f32_e32 v38, v39, v39
	v_mul_f32_e32 v40, v41, v41
	v_pk_fma_f32 v[62:63], v[68:69], v[62:63], s[48:49] op_sel_hi:[1,1,0]
	v_exp_f32_e32 v64, v64
	v_exp_f32_e32 v65, v65
	v_pk_add_f32 v[12:13], v[22:23], v[12:13]
	v_pk_add_f32 v[14:15], v[36:37], v[14:15]
	v_mul_f32_e32 v42, v43, v43
	v_mul_f32_e32 v8, v9, v9
	v_pk_fma_f32 v[62:63], v[68:69], v[62:63], s[50:51] op_sel_hi:[1,1,0]
	v_pk_add_f32 v[12:13], v[14:15], v[12:13]
	v_pk_add_f32 v[14:15], v[38:39], v[40:41]
	v_mul_f32_e32 v44, v45, v45
	v_mul_f32_e32 v46, v47, v47
	v_pk_fma_f32 v[62:63], v[68:69], v[62:63], s[56:57] op_sel_hi:[1,1,0]
	v_pk_add_f32 v[12:13], v[14:15], v[12:13]
	v_pk_add_f32 v[8:9], v[42:43], v[8:9]
	v_pk_mul_f32 v[62:63], v[68:69], v[62:63]
	v_pk_add_f32 v[8:9], v[8:9], v[12:13]
	v_pk_add_f32 v[12:13], v[44:45], v[46:47]
	v_lshlrev_b32_e32 v4, 16, v5
	v_and_b32_e32 v5, 0xffff0000, v5
	v_pk_mul_f32 v[62:63], v[64:65], v[62:63]
	v_pk_add_f32 v[8:9], v[12:13], v[8:9]
	v_max_f32_e32 v110, 0, v20
	v_fma_f32 v69, -|v20|, v62, v110
	v_max_f32_e32 v111, 0, v21
	v_fma_f32 v21, -|v21|, v63, v111
	v_fma_f32 v12, |v4|, s40, 1.0
	v_fma_f32 v13, |v5|, s40, 1.0
	v_mul_f32_e32 v48, v49, v49
	v_mul_f32_e32 v10, v11, v11
	v_rcp_f32_e32 v12, v12
	v_rcp_f32_e32 v13, v13
	v_mul_f32_e32 v66, v67, v67
	v_mul_f32_e32 v60, v61, v61
	v_pk_add_f32 v[10:11], v[48:49], v[10:11]
	v_mul_f32_e32 v68, v69, v69
	v_mul_f32_e32 v20, v21, v21
	v_pk_add_f32 v[8:9], v[10:11], v[8:9]
	v_pk_add_f32 v[10:11], v[66:67], v[60:61]
	v_pk_mul_f32 v[14:15], v[4:5], v[4:5]
	v_pk_add_f32 v[8:9], v[10:11], v[8:9]
	v_pk_add_f32 v[10:11], v[68:69], v[20:21]
	v_pk_mul_f32 v[14:15], v[14:15], s[64:65] op_sel_hi:[1,0]
	v_pk_add_f32 v[8:9], v[10:11], v[8:9]
	v_pk_fma_f32 v[10:11], v[12:13], s[42:43], v[18:19] op_sel_hi:[1,0,0]
	v_exp_f32_e32 v14, v14
	v_pk_fma_f32 v[10:11], v[12:13], v[10:11], s[48:49] op_sel_hi:[1,1,0]
	v_exp_f32_e32 v15, v15
	v_pk_fma_f32 v[10:11], v[12:13], v[10:11], s[50:51] op_sel_hi:[1,1,0]
	v_cmp_gt_f32_e64 s[0:1], 0, v4
	v_pk_fma_f32 v[10:11], v[12:13], v[10:11], s[56:57] op_sel_hi:[1,1,0]
	s_waitcnt vmcnt(0)
	v_lshlrev_b32_e32 v24, 16, v50
	v_pk_mul_f32 v[10:11], v[12:13], v[10:11]
	v_and_b32_e32 v25, 0xffff0000, v50
	v_pk_mul_f32 v[10:11], v[14:15], v[10:11]
	v_and_b32_e32 v27, 0x7fffffff, v25
	v_pk_mul_f32 v[12:13], v[4:5], v[10:11]
	v_pk_fma_f32 v[10:11], v[4:5], v[10:11], v[4:5] neg_lo:[1,0,0] neg_hi:[1,0,0]
	v_and_b32_e32 v26, 0x7fffffff, v24
	v_cndmask_b32_e64 v15, v10, v12, s[0:1]
	v_cmp_gt_f32_e64 s[0:1], 0, v5
	v_lshlrev_b32_e32 v10, 16, v6
	v_and_b32_e32 v12, 0x7fffffff, v10
	v_cndmask_b32_e64 v5, v11, v13, s[0:1]
	v_and_b32_e32 v11, 0xffff0000, v6
	v_and_b32_e32 v13, 0x7fffffff, v11
	v_pk_fma_f32 v[12:13], v[12:13], s[40:41], 1.0 op_sel_hi:[1,0,0]
	v_mul_f32_e32 v14, v15, v15
	v_rcp_f32_e32 v12, v12
	v_rcp_f32_e32 v13, v13
	v_mul_f32_e32 v4, v5, v5
	v_pk_mul_f32 v[20:21], v[10:11], v[10:11]
	v_pk_add_f32 v[4:5], v[14:15], v[4:5]
	v_pk_fma_f32 v[14:15], v[12:13], s[42:43], v[18:19] op_sel_hi:[1,0,0]
	v_pk_mul_f32 v[20:21], v[20:21], s[64:65] op_sel_hi:[1,0]
	v_pk_fma_f32 v[14:15], v[12:13], v[14:15], s[48:49] op_sel_hi:[1,1,0]
	v_exp_f32_e32 v20, v20
	v_exp_f32_e32 v21, v21
	v_pk_fma_f32 v[14:15], v[12:13], v[14:15], s[50:51] op_sel_hi:[1,1,0]
	v_lshlrev_b32_e32 v6, 16, v7
	v_and_b32_e32 v7, 0xffff0000, v7
	v_pk_fma_f32 v[14:15], v[12:13], v[14:15], s[56:57] op_sel_hi:[1,1,0]
	v_pk_mul_f32 v[12:13], v[12:13], v[14:15]
	v_fma_f32 v22, |v6|, s40, 1.0
	v_fma_f32 v23, |v7|, s40, 1.0
	v_pk_mul_f32 v[12:13], v[20:21], v[12:13]
	v_rcp_f32_e32 v22, v22
	v_rcp_f32_e32 v23, v23
	v_max_f32_e32 v112, 0, v10
	v_fma_f32 v21, -|v10|, v12, v112
	v_max_f32_e32 v113, 0, v11
	v_fma_f32 v11, -|v11|, v13, v113
	v_pk_fma_f32 v[26:27], v[26:27], s[40:41], 1.0 op_sel_hi:[1,0,0]
	v_lshlrev_b32_e32 v28, 16, v51
	v_rcp_f32_e32 v26, v26
	v_rcp_f32_e32 v27, v27
	v_pk_mul_f32 v[14:15], v[6:7], v[6:7]
	v_pk_fma_f32 v[12:13], v[22:23], s[42:43], v[18:19] op_sel_hi:[1,0,0]
	v_pk_mul_f32 v[14:15], v[14:15], s[64:65] op_sel_hi:[1,0]
	v_pk_fma_f32 v[12:13], v[22:23], v[12:13], s[48:49] op_sel_hi:[1,1,0]
	v_exp_f32_e32 v14, v14
	v_exp_f32_e32 v15, v15
	v_pk_fma_f32 v[12:13], v[22:23], v[12:13], s[50:51] op_sel_hi:[1,1,0]
	v_cmp_gt_f32_e64 s[0:1], 0, v6
	v_pk_fma_f32 v[12:13], v[22:23], v[12:13], s[56:57] op_sel_hi:[1,1,0]
	v_and_b32_e32 v29, 0xffff0000, v51
	v_pk_mul_f32 v[12:13], v[22:23], v[12:13]
	v_pk_mul_f32 v[12:13], v[14:15], v[12:13]
	v_pk_mul_f32 v[14:15], v[6:7], v[12:13]
	v_pk_fma_f32 v[12:13], v[6:7], v[12:13], v[6:7] neg_lo:[1,0,0] neg_hi:[1,0,0]
	v_fma_f32 v30, |v28|, s40, 1.0
	v_fma_f32 v31, |v29|, s40, 1.0
	v_cndmask_b32_e64 v23, v12, v14, s[0:1]
	v_cmp_gt_f32_e64 s[0:1], 0, v7
	v_rcp_f32_e32 v30, v30
	v_rcp_f32_e32 v31, v31
	v_cndmask_b32_e64 v7, v13, v15, s[0:1]
	v_pk_mul_f32 v[14:15], v[24:25], v[24:25]
	v_pk_fma_f32 v[12:13], v[26:27], s[42:43], v[18:19] op_sel_hi:[1,0,0]
	v_pk_mul_f32 v[14:15], v[14:15], s[64:65] op_sel_hi:[1,0]
	v_pk_fma_f32 v[12:13], v[26:27], v[12:13], s[48:49] op_sel_hi:[1,1,0]
	v_exp_f32_e32 v14, v14
	v_exp_f32_e32 v15, v15
	v_pk_fma_f32 v[12:13], v[26:27], v[12:13], s[50:51] op_sel_hi:[1,1,0]
	v_cmp_gt_f32_e64 s[0:1], 0, v24
	v_pk_fma_f32 v[12:13], v[26:27], v[12:13], s[56:57] op_sel_hi:[1,1,0]
	v_lshlrev_b32_e32 v32, 16, v52
	v_pk_mul_f32 v[12:13], v[26:27], v[12:13]
	v_and_b32_e32 v33, 0xffff0000, v52
	v_pk_mul_f32 v[12:13], v[14:15], v[12:13]
	v_pk_mul_f32 v[14:15], v[24:25], v[12:13]
	v_pk_fma_f32 v[12:13], v[24:25], v[12:13], v[24:25] neg_lo:[1,0,0] neg_hi:[1,0,0]
	v_cndmask_b32_e64 v27, v12, v14, s[0:1]
	v_cmp_gt_f32_e64 s[0:1], 0, v25
	v_pk_mul_f32 v[24:25], v[28:29], v[28:29]
	v_fma_f32 v34, |v32|, s40, 1.0
	v_fma_f32 v35, |v33|, s40, 1.0
	v_cndmask_b32_e64 v13, v13, v15, s[0:1]
	v_pk_fma_f32 v[14:15], v[30:31], s[42:43], v[18:19] op_sel_hi:[1,0,0]
	v_pk_mul_f32 v[24:25], v[24:25], s[64:65] op_sel_hi:[1,0]
	v_pk_fma_f32 v[14:15], v[30:31], v[14:15], s[48:49] op_sel_hi:[1,1,0]
	v_exp_f32_e32 v24, v24
	v_exp_f32_e32 v25, v25
	v_pk_fma_f32 v[14:15], v[30:31], v[14:15], s[50:51] op_sel_hi:[1,1,0]
	v_rcp_f32_e32 v34, v34
	v_pk_fma_f32 v[14:15], v[30:31], v[14:15], s[56:57] op_sel_hi:[1,1,0]
	v_rcp_f32_e32 v35, v35
	v_pk_mul_f32 v[14:15], v[30:31], v[14:15]
	v_cmp_gt_f32_e64 s[0:1], 0, v28
	v_pk_mul_f32 v[14:15], v[24:25], v[14:15]
	v_lshlrev_b32_e32 v36, 16, v53
	v_pk_mul_f32 v[24:25], v[28:29], v[14:15]
	v_pk_fma_f32 v[14:15], v[28:29], v[14:15], v[28:29] neg_lo:[1,0,0] neg_hi:[1,0,0]
	v_and_b32_e32 v37, 0xffff0000, v53
	v_cndmask_b32_e64 v31, v14, v24, s[0:1]
	v_cmp_gt_f32_e64 s[0:1], 0, v29
	v_pk_mul_f32 v[28:29], v[32:33], v[32:33]
	v_cndmask_b32_e64 v15, v15, v25, s[0:1]
	v_pk_fma_f32 v[24:25], v[34:35], s[42:43], v[18:19] op_sel_hi:[1,0,0]
	v_pk_mul_f32 v[28:29], v[28:29], s[64:65] op_sel_hi:[1,0]
	v_pk_fma_f32 v[24:25], v[34:35], v[24:25], s[48:49] op_sel_hi:[1,1,0]
	v_exp_f32_e32 v28, v28
	v_exp_f32_e32 v29, v29
	v_pk_fma_f32 v[24:25], v[34:35], v[24:25], s[50:51] op_sel_hi:[1,1,0]
	v_pk_fma_f32 v[24:25], v[34:35], v[24:25], s[56:57] op_sel_hi:[1,1,0]
	v_fma_f32 v38, |v36|, s40, 1.0
	v_fma_f32 v39, |v37|, s40, 1.0
	v_pk_mul_f32 v[24:25], v[34:35], v[24:25]
	v_rcp_f32_e32 v38, v38
	v_pk_mul_f32 v[24:25], v[28:29], v[24:25]
	v_rcp_f32_e32 v39, v39
	v_max_f32_e32 v114, 0, v32
	v_fma_f32 v35, -|v32|, v24, v114
	v_max_f32_e32 v115, 0, v33
	v_fma_f32 v25, -|v33|, v25, v115
	v_pk_fma_f32 v[18:19], v[38:39], s[42:43], v[18:19] op_sel_hi:[1,0,0]
	v_mul_f32_e32 v20, v21, v21
	v_pk_fma_f32 v[18:19], v[38:39], v[18:19], s[48:49] op_sel_hi:[1,1,0]
	v_mul_f32_e32 v10, v11, v11
	v_pk_mul_f32 v[28:29], v[36:37], v[36:37]
	v_pk_fma_f32 v[18:19], v[38:39], v[18:19], s[50:51] op_sel_hi:[1,1,0]
	v_pk_mul_f32 v[28:29], v[28:29], s[64:65] op_sel_hi:[1,0]
	v_pk_fma_f32 v[18:19], v[38:39], v[18:19], s[56:57] op_sel_hi:[1,1,0]
	v_exp_f32_e32 v28, v28
	v_exp_f32_e32 v29, v29
	v_pk_mul_f32 v[18:19], v[38:39], v[18:19]
	v_mul_f32_e32 v22, v23, v23
	v_mul_f32_e32 v6, v7, v7
	v_pk_mul_f32 v[18:19], v[28:29], v[18:19]
	v_pk_add_f32 v[4:5], v[4:5], v[8:9]
	v_pk_add_f32 v[8:9], v[20:21], v[10:11]
	v_mul_f32_e32 v26, v27, v27
	v_mul_f32_e32 v12, v13, v13
	v_max_f32_e32 v116, 0, v36
	v_fma_f32 v33, -|v36|, v18, v116
	v_max_f32_e32 v117, 0, v37
	v_fma_f32 v19, -|v37|, v19, v117
	v_pk_add_f32 v[4:5], v[8:9], v[4:5]
	v_pk_add_f32 v[6:7], v[22:23], v[6:7]
	v_mul_f32_e32 v30, v31, v31
	v_mul_f32_e32 v14, v15, v15
	v_pk_add_f32 v[4:5], v[6:7], v[4:5]
	v_pk_add_f32 v[6:7], v[26:27], v[12:13]
	v_mul_f32_e32 v34, v35, v35
	v_mul_f32_e32 v24, v25, v25
	v_pk_add_f32 v[4:5], v[6:7], v[4:5]
	v_pk_add_f32 v[6:7], v[30:31], v[14:15]
	v_mul_f32_e32 v32, v33, v33
	v_mul_f32_e32 v18, v19, v19
	v_pk_add_f32 v[4:5], v[6:7], v[4:5]
	v_pk_add_f32 v[6:7], v[34:35], v[24:25]
	s_nop 0
	v_pk_add_f32 v[4:5], v[6:7], v[4:5]
	v_pk_add_f32 v[6:7], v[32:33], v[18:19]
	s_nop 0
	v_pk_add_f32 v[4:5], v[6:7], v[4:5]
	ds_bpermute_b32 v7, v56, v5
	ds_bpermute_b32 v6, v56, v4
	s_waitcnt lgkmcnt(0)
	v_pk_add_f32 v[4:5], v[4:5], v[6:7]
	ds_bpermute_b32 v7, v57, v5
	ds_bpermute_b32 v6, v57, v4
	s_waitcnt lgkmcnt(0)
	v_pk_add_f32 v[4:5], v[4:5], v[6:7]
	ds_bpermute_b32 v7, v58, v5
	ds_bpermute_b32 v6, v58, v4
	s_waitcnt lgkmcnt(0)
	v_pk_add_f32 v[4:5], v[4:5], v[6:7]
	ds_bpermute_b32 v7, v59, v5
	ds_bpermute_b32 v6, v59, v4
	s_and_saveexec_b64 s[0:1], vcc
	s_cbranch_execz .LBB0_451
	s_waitcnt lgkmcnt(0)
	v_pk_add_f32 v[4:5], v[4:5], v[6:7]
	s_nop 0
	v_pk_mul_f32 v[4:5], v[4:5], s[66:67] op_sel_hi:[1,0]
	s_nop 0
	v_fma_f32 v4, -v5, v5, v4
	v_max_f32_e32 v4, 0, v4
	v_add_f32_e32 v4, 0x358637bd, v4
	v_mul_f32_e32 v6, 0x4b800000, v4
	v_cmp_gt_f32_e32 vcc, s36, v4
	s_nop 1
	v_cndmask_b32_e32 v4, v4, v6, vcc
	v_rsq_f32_e32 v4, v4
	v_lshl_add_u32 v6, v16, 2, 0
	v_add_u32_e32 v7, 0x11000, v6
	ds_write_b32 v7, v5
	v_mul_f32_e32 v5, 0x45800000, v4
	v_cndmask_b32_e32 v4, v4, v5, vcc
	v_add_u32_e32 v5, 0x11200, v6
	ds_write_b32 v5, v4

.LBB0_453:
	v_lshl_add_u64 v[4:5], s[12:13], 0, v[32:33]
	v_add_co_u32_e32 v18, vcc, 0x696e000, v4
	s_add_u32 s0, s16, s70
	s_nop 0
	v_addc_co_u32_e32 v19, vcc, 0, v5, vcc
	global_load_dwordx4 v[8:11], v[18:19], off
	global_load_dwordx4 v[4:7], v[18:19], off offset:2048
	s_addc_u32 s1, s38, s71
	s_add_u32 s4, s88, s70
	s_addc_u32 s5, s89, s71
	global_load_dwordx2 v[20:21], v2, s[0:1]
	global_load_dwordx2 v[22:23], v2, s[4:5]
	v_mov_b64_e32 v[16:17], s[44:45]
	ds_read_b64 v[14:15], v68
	ds_read_b64 v[12:13], v69
	s_waitcnt vmcnt(3)
	v_lshlrev_b32_e32 v24, 16, v8
	v_and_b32_e32 v25, 0xffff0000, v8
	s_waitcnt vmcnt(2)
	v_lshlrev_b32_e32 v34, 16, v4
	v_and_b32_e32 v35, 0xffff0000, v4
	v_fma_f32 v36, |v24|, s40, 1.0
	v_fma_f32 v37, |v25|, s40, 1.0
	v_fma_f32 v40, |v34|, s40, 1.0
	v_fma_f32 v41, |v35|, s40, 1.0
	v_rcp_f32_e32 v36, v36
	v_rcp_f32_e32 v37, v37
	v_rcp_f32_e32 v40, v40
	v_rcp_f32_e32 v41, v41
	v_pk_mul_f32 v[38:39], v[24:25], v[24:25]
	v_pk_mul_f32 v[42:43], v[34:35], v[34:35]
	v_pk_mul_f32 v[38:39], v[38:39], s[64:65] op_sel_hi:[1,0]
	v_pk_fma_f32 v[44:45], v[36:37], s[42:43], v[16:17] op_sel_hi:[1,0,0]
	v_pk_mul_f32 v[42:43], v[42:43], s[64:65] op_sel_hi:[1,0]
	v_exp_f32_e32 v38, v38
	v_exp_f32_e32 v39, v39
	v_pk_fma_f32 v[46:47], v[40:41], s[42:43], v[16:17] op_sel_hi:[1,0,0]
	v_pk_fma_f32 v[44:45], v[36:37], v[44:45], s[48:49] op_sel_hi:[1,1,0]
	v_exp_f32_e32 v42, v42
	v_exp_f32_e32 v43, v43
	v_pk_fma_f32 v[46:47], v[40:41], v[46:47], s[48:49] op_sel_hi:[1,1,0]
	v_pk_fma_f32 v[44:45], v[36:37], v[44:45], s[50:51] op_sel_hi:[1,1,0]
	v_pk_fma_f32 v[46:47], v[40:41], v[46:47], s[50:51] op_sel_hi:[1,1,0]
	v_pk_fma_f32 v[44:45], v[36:37], v[44:45], s[56:57] op_sel_hi:[1,1,0]
	v_pk_fma_f32 v[46:47], v[40:41], v[46:47], s[56:57] op_sel_hi:[1,1,0]
	v_pk_mul_f32 v[36:37], v[36:37], v[44:45]
	v_pk_mul_f32 v[40:41], v[40:41], v[46:47]
	v_pk_mul_f32 v[36:37], v[38:39], v[36:37]
	v_pk_mul_f32 v[38:39], v[42:43], v[40:41]
	v_max_f32_e32 v80, 0, v24
	v_fma_f32 v3, -|v24|, v36, v80
	v_max_f32_e32 v81, 0, v25
	v_fma_f32 v4, -|v25|, v37, v81
	v_max_f32_e32 v82, 0, v34
	v_fma_f32 v8, -|v34|, v38, v82
	v_max_f32_e32 v83, 0, v35
	v_fma_f32 v24, -|v35|, v39, v83
	s_waitcnt lgkmcnt(1)
	v_sub_f32_e32 v3, v3, v14
	s_waitcnt lgkmcnt(0)
	v_mul_f32_e32 v3, v12, v3
	v_sub_f32_e32 v4, v4, v14
	v_mul_f32_e32 v4, v12, v4
	v_sub_f32_e32 v8, v8, v15
	v_mul_f32_e32 v8, v13, v8
	v_sub_f32_e32 v24, v24, v15
	v_mul_f32_e32 v24, v13, v24
	s_waitcnt vmcnt(0)
	v_fma_f32 v3, v20, v3, v22
	v_fma_f32 v4, v21, v4, v23
	v_fma_f32 v8, v20, v8, v22
	v_fmac_f32_e32 v23, v21, v24
	v_cvt_pk_bf16_f32 v3, v3, v8
	ds_write_b32 v70, v3
	v_cvt_pk_bf16_f32 v3, v4, v23
	global_load_dwordx2 v[22:23], v2, s[0:1] offset:8
	global_load_dwordx2 v[20:21], v2, s[4:5] offset:8
	v_lshlrev_b32_e32 v8, 16, v9
	v_and_b32_e32 v9, 0xffff0000, v9
	v_lshlrev_b32_e32 v4, 16, v5
	v_and_b32_e32 v5, 0xffff0000, v5
	v_fma_f32 v24, |v8|, s40, 1.0
	v_fma_f32 v25, |v9|, s40, 1.0
	v_fma_f32 v36, |v4|, s40, 1.0
	v_fma_f32 v37, |v5|, s40, 1.0
	v_rcp_f32_e32 v24, v24
	v_rcp_f32_e32 v25, v25
	v_rcp_f32_e32 v36, v36
	v_rcp_f32_e32 v37, v37
	v_pk_mul_f32 v[34:35], v[8:9], v[8:9]
	v_pk_mul_f32 v[38:39], v[4:5], v[4:5]
	v_pk_mul_f32 v[34:35], v[34:35], s[64:65] op_sel_hi:[1,0]
	v_pk_fma_f32 v[40:41], v[24:25], s[42:43], v[16:17] op_sel_hi:[1,0,0]
	v_pk_mul_f32 v[38:39], v[38:39], s[64:65] op_sel_hi:[1,0]
	v_exp_f32_e32 v34, v34
	v_exp_f32_e32 v35, v35
	v_pk_fma_f32 v[42:43], v[36:37], s[42:43], v[16:17] op_sel_hi:[1,0,0]
	v_pk_fma_f32 v[40:41], v[24:25], v[40:41], s[48:49] op_sel_hi:[1,1,0]
	v_exp_f32_e32 v38, v38
	v_exp_f32_e32 v39, v39
	v_pk_fma_f32 v[42:43], v[36:37], v[42:43], s[48:49] op_sel_hi:[1,1,0]
	v_pk_fma_f32 v[40:41], v[24:25], v[40:41], s[50:51] op_sel_hi:[1,1,0]
	v_pk_fma_f32 v[42:43], v[36:37], v[42:43], s[50:51] op_sel_hi:[1,1,0]
	v_pk_fma_f32 v[40:41], v[24:25], v[40:41], s[56:57] op_sel_hi:[1,1,0]
	v_pk_fma_f32 v[42:43], v[36:37], v[42:43], s[56:57] op_sel_hi:[1,1,0]
	v_pk_mul_f32 v[24:25], v[24:25], v[40:41]
	v_pk_mul_f32 v[36:37], v[36:37], v[42:43]
	v_pk_mul_f32 v[24:25], v[34:35], v[24:25]
	v_pk_mul_f32 v[34:35], v[38:39], v[36:37]
	v_max_f32_e32 v84, 0, v8
	v_fma_f32 v8, -|v8|, v24, v84
	v_max_f32_e32 v85, 0, v9
	v_fma_f32 v9, -|v9|, v25, v85
	v_max_f32_e32 v86, 0, v4
	v_fma_f32 v4, -|v4|, v34, v86
	v_max_f32_e32 v90, 0, v5
	v_fma_f32 v5, -|v5|, v35, v90
	v_sub_f32_e32 v8, v8, v14
	v_mul_f32_e32 v8, v12, v8
	v_sub_f32_e32 v9, v9, v14
	v_mul_f32_e32 v9, v12, v9
	v_sub_f32_e32 v4, v4, v15
	v_mul_f32_e32 v4, v13, v4
	v_sub_f32_e32 v5, v5, v15
	ds_write_b32 v70, v3 offset:272
	v_mul_f32_e32 v5, v13, v5
	s_waitcnt vmcnt(0)
	v_fma_f32 v3, v22, v8, v20
	v_fma_f32 v8, v23, v9, v21
	v_fma_f32 v4, v22, v4, v20
	v_cvt_pk_bf16_f32 v3, v3, v4
	v_fmac_f32_e32 v21, v23, v5
	ds_write_b32 v70, v3 offset:544
	v_cvt_pk_bf16_f32 v3, v8, v21
	global_load_dwordx2 v[8:9], v2, s[0:1] offset:16
	global_load_dwordx2 v[4:5], v2, s[4:5] offset:16
	v_lshlrev_b32_e32 v20, 16, v10
	v_and_b32_e32 v21, 0xffff0000, v10
	v_lshlrev_b32_e32 v22, 16, v6
	v_and_b32_e32 v23, 0xffff0000, v6
	v_fma_f32 v24, |v20|, s40, 1.0
	v_fma_f32 v25, |v21|, s40, 1.0
	v_fma_f32 v36, |v22|, s40, 1.0
	v_fma_f32 v37, |v23|, s40, 1.0
	v_rcp_f32_e32 v24, v24
	v_rcp_f32_e32 v25, v25
	v_rcp_f32_e32 v36, v36
	v_rcp_f32_e32 v37, v37
	v_pk_mul_f32 v[34:35], v[20:21], v[20:21]
	v_pk_mul_f32 v[38:39], v[22:23], v[22:23]
	v_pk_mul_f32 v[34:35], v[34:35], s[64:65] op_sel_hi:[1,0]
	v_pk_fma_f32 v[40:41], v[24:25], s[42:43], v[16:17] op_sel_hi:[1,0,0]
	v_pk_mul_f32 v[38:39], v[38:39], s[64:65] op_sel_hi:[1,0]
	v_exp_f32_e32 v34, v34
	v_exp_f32_e32 v35, v35
	v_pk_fma_f32 v[42:43], v[36:37], s[42:43], v[16:17] op_sel_hi:[1,0,0]
	v_pk_fma_f32 v[40:41], v[24:25], v[40:41], s[48:49] op_sel_hi:[1,1,0]
	v_exp_f32_e32 v38, v38
	v_exp_f32_e32 v39, v39
	v_pk_fma_f32 v[42:43], v[36:37], v[42:43], s[48:49] op_sel_hi:[1,1,0]
	v_pk_fma_f32 v[40:41], v[24:25], v[40:41], s[50:51] op_sel_hi:[1,1,0]
	v_pk_fma_f32 v[42:43], v[36:37], v[42:43], s[50:51] op_sel_hi:[1,1,0]
	v_pk_fma_f32 v[40:41], v[24:25], v[40:41], s[56:57] op_sel_hi:[1,1,0]
	v_pk_fma_f32 v[42:43], v[36:37], v[42:43], s[56:57] op_sel_hi:[1,1,0]
	v_pk_mul_f32 v[24:25], v[24:25], v[40:41]
	v_pk_mul_f32 v[36:37], v[36:37], v[42:43]
	v_pk_mul_f32 v[24:25], v[34:35], v[24:25]
	v_pk_mul_f32 v[34:35], v[38:39], v[36:37]
	v_max_f32_e32 v91, 0, v20
	v_fma_f32 v6, -|v20|, v24, v91
	v_max_f32_e32 v92, 0, v21
	v_fma_f32 v10, -|v21|, v25, v92
	v_max_f32_e32 v93, 0, v22
	v_fma_f32 v20, -|v22|, v34, v93
	v_max_f32_e32 v94, 0, v23
	v_fma_f32 v21, -|v23|, v35, v94
	v_sub_f32_e32 v6, v6, v14
	v_mul_f32_e32 v6, v12, v6
	v_sub_f32_e32 v10, v10, v14
	v_mul_f32_e32 v10, v12, v10
	v_sub_f32_e32 v20, v20, v15
	v_mul_f32_e32 v20, v13, v20
	v_sub_f32_e32 v21, v21, v15
	v_mul_f32_e32 v21, v13, v21
	ds_write_b32 v70, v3 offset:816
	s_waitcnt vmcnt(0)
	v_fma_f32 v3, v8, v6, v4
	v_fma_f32 v6, v9, v10, v5
	v_fma_f32 v4, v8, v20, v4
	v_fmac_f32_e32 v5, v9, v21
	v_cvt_pk_bf16_f32 v3, v3, v4
	ds_write_b32 v70, v3 offset:1088
	v_cvt_pk_bf16_f32 v3, v6, v5
	global_load_dwordx2 v[8:9], v2, s[0:1] offset:24
	global_load_dwordx2 v[4:5], v2, s[4:5] offset:24
	v_lshlrev_b32_e32 v10, 16, v11
	v_and_b32_e32 v11, 0xffff0000, v11
	v_lshlrev_b32_e32 v6, 16, v7
	v_and_b32_e32 v7, 0xffff0000, v7
	v_fma_f32 v20, |v10|, s40, 1.0
	v_fma_f32 v21, |v11|, s40, 1.0
	v_fma_f32 v24, |v6|, s40, 1.0
	v_fma_f32 v25, |v7|, s40, 1.0
	v_rcp_f32_e32 v20, v20
	v_rcp_f32_e32 v21, v21
	v_rcp_f32_e32 v24, v24
	v_rcp_f32_e32 v25, v25
	v_pk_mul_f32 v[22:23], v[10:11], v[10:11]
	v_pk_mul_f32 v[34:35], v[6:7], v[6:7]
	v_pk_mul_f32 v[22:23], v[22:23], s[64:65] op_sel_hi:[1,0]
	v_pk_fma_f32 v[36:37], v[20:21], s[42:43], v[16:17] op_sel_hi:[1,0,0]
	v_pk_mul_f32 v[34:35], v[34:35], s[64:65] op_sel_hi:[1,0]
	v_exp_f32_e32 v22, v22
	v_exp_f32_e32 v23, v23
	v_pk_fma_f32 v[38:39], v[24:25], s[42:43], v[16:17] op_sel_hi:[1,0,0]
	v_pk_fma_f32 v[36:37], v[20:21], v[36:37], s[48:49] op_sel_hi:[1,1,0]
	v_exp_f32_e32 v34, v34
	v_exp_f32_e32 v35, v35
	v_pk_fma_f32 v[38:39], v[24:25], v[38:39], s[48:49] op_sel_hi:[1,1,0]
	v_pk_fma_f32 v[36:37], v[20:21], v[36:37], s[50:51] op_sel_hi:[1,1,0]
	v_pk_fma_f32 v[38:39], v[24:25], v[38:39], s[50:51] op_sel_hi:[1,1,0]
	v_pk_fma_f32 v[36:37], v[20:21], v[36:37], s[56:57] op_sel_hi:[1,1,0]
	v_pk_fma_f32 v[38:39], v[24:25], v[38:39], s[56:57] op_sel_hi:[1,1,0]
	v_pk_mul_f32 v[20:21], v[20:21], v[36:37]
	v_pk_mul_f32 v[24:25], v[24:25], v[38:39]
	v_pk_mul_f32 v[20:21], v[22:23], v[20:21]
	v_pk_mul_f32 v[22:23], v[34:35], v[24:25]
	v_max_f32_e32 v95, 0, v10
	v_fma_f32 v10, -|v10|, v20, v95
	v_max_f32_e32 v96, 0, v11
	v_fma_f32 v11, -|v11|, v21, v96
	v_max_f32_e32 v97, 0, v6
	v_fma_f32 v6, -|v6|, v22, v97
	v_max_f32_e32 v98, 0, v7
	v_fma_f32 v7, -|v7|, v23, v98
	v_sub_f32_e32 v10, v10, v14
	v_mul_f32_e32 v10, v12, v10
	v_sub_f32_e32 v11, v11, v14
	v_mul_f32_e32 v11, v12, v11
	v_sub_f32_e32 v6, v6, v15
	v_mul_f32_e32 v6, v13, v6
	v_sub_f32_e32 v7, v7, v15
	v_mul_f32_e32 v7, v13, v7
	ds_write_b32 v70, v3 offset:1360
	s_waitcnt vmcnt(0)
	v_fma_f32 v3, v8, v10, v4
	v_fma_f32 v10, v9, v11, v5
	v_fma_f32 v4, v8, v6, v4
	v_fmac_f32_e32 v5, v9, v7
	v_cvt_pk_bf16_f32 v3, v3, v4
	ds_write_b32 v70, v3 offset:1632
	v_cvt_pk_bf16_f32 v3, v10, v5
	global_load_dwordx4 v[8:11], v[18:19], off offset:16
	global_load_dwordx4 v[4:7], v[18:19], off offset:2064
	global_load_dwordx2 v[22:23], v2, s[0:1] offset:32
	global_load_dwordx2 v[20:21], v2, s[4:5] offset:32
	ds_write_b32 v70, v3 offset:1904
	s_waitcnt vmcnt(3)
	v_lshlrev_b32_e32 v24, 16, v8
	v_and_b32_e32 v25, 0xffff0000, v8
	s_waitcnt vmcnt(2)
	v_lshlrev_b32_e32 v34, 16, v4
	v_and_b32_e32 v35, 0xffff0000, v4
	v_fma_f32 v36, |v24|, s40, 1.0
	v_fma_f32 v37, |v25|, s40, 1.0
	v_fma_f32 v40, |v34|, s40, 1.0
	v_fma_f32 v41, |v35|, s40, 1.0
	v_rcp_f32_e32 v36, v36
	v_rcp_f32_e32 v37, v37
	v_rcp_f32_e32 v40, v40
	v_rcp_f32_e32 v41, v41
	v_pk_mul_f32 v[38:39], v[24:25], v[24:25]
	v_pk_mul_f32 v[42:43], v[34:35], v[34:35]
	v_pk_mul_f32 v[38:39], v[38:39], s[64:65] op_sel_hi:[1,0]
	v_pk_fma_f32 v[44:45], v[36:37], s[42:43], v[16:17] op_sel_hi:[1,0,0]
	v_pk_mul_f32 v[42:43], v[42:43], s[64:65] op_sel_hi:[1,0]
	v_exp_f32_e32 v38, v38
	v_exp_f32_e32 v39, v39
	v_pk_fma_f32 v[46:47], v[40:41], s[42:43], v[16:17] op_sel_hi:[1,0,0]
	v_pk_fma_f32 v[44:45], v[36:37], v[44:45], s[48:49] op_sel_hi:[1,1,0]
	v_exp_f32_e32 v42, v42
	v_exp_f32_e32 v43, v43
	v_pk_fma_f32 v[46:47], v[40:41], v[46:47], s[48:49] op_sel_hi:[1,1,0]
	v_pk_fma_f32 v[44:45], v[36:37], v[44:45], s[50:51] op_sel_hi:[1,1,0]
	v_pk_fma_f32 v[46:47], v[40:41], v[46:47], s[50:51] op_sel_hi:[1,1,0]
	v_pk_fma_f32 v[44:45], v[36:37], v[44:45], s[56:57] op_sel_hi:[1,1,0]
	v_pk_fma_f32 v[46:47], v[40:41], v[46:47], s[56:57] op_sel_hi:[1,1,0]
	v_pk_mul_f32 v[36:37], v[36:37], v[44:45]
	v_pk_mul_f32 v[40:41], v[40:41], v[46:47]
	v_pk_mul_f32 v[36:37], v[38:39], v[36:37]
	v_pk_mul_f32 v[38:39], v[42:43], v[40:41]
	v_max_f32_e32 v99, 0, v24
	v_fma_f32 v3, -|v24|, v36, v99
	v_max_f32_e32 v100, 0, v25
	v_fma_f32 v4, -|v25|, v37, v100
	v_max_f32_e32 v104, 0, v34
	v_fma_f32 v8, -|v34|, v38, v104
	v_max_f32_e32 v105, 0, v35
	v_fma_f32 v24, -|v35|, v39, v105
	v_sub_f32_e32 v3, v3, v14
	v_mul_f32_e32 v3, v12, v3
	v_sub_f32_e32 v4, v4, v14
	v_mul_f32_e32 v4, v12, v4
	v_sub_f32_e32 v8, v8, v15
	v_mul_f32_e32 v8, v13, v8
	v_sub_f32_e32 v24, v24, v15
	v_mul_f32_e32 v24, v13, v24
	s_waitcnt vmcnt(0)
	v_fma_f32 v3, v22, v3, v20
	v_fma_f32 v4, v23, v4, v21
	v_fma_f32 v8, v22, v8, v20
	v_fmac_f32_e32 v21, v23, v24
	v_cvt_pk_bf16_f32 v3, v3, v8
	ds_write_b32 v70, v3 offset:2176
	v_cvt_pk_bf16_f32 v3, v4, v21
	global_load_dwordx2 v[22:23], v2, s[0:1] offset:40
	global_load_dwordx2 v[20:21], v2, s[4:5] offset:40
	v_lshlrev_b32_e32 v8, 16, v9
	v_and_b32_e32 v9, 0xffff0000, v9
	v_lshlrev_b32_e32 v4, 16, v5
	v_and_b32_e32 v5, 0xffff0000, v5
	v_fma_f32 v24, |v8|, s40, 1.0
	v_fma_f32 v25, |v9|, s40, 1.0
	v_fma_f32 v36, |v4|, s40, 1.0
	v_fma_f32 v37, |v5|, s40, 1.0
	v_rcp_f32_e32 v24, v24
	v_rcp_f32_e32 v25, v25
	v_rcp_f32_e32 v36, v36
	v_rcp_f32_e32 v37, v37
	v_pk_mul_f32 v[34:35], v[8:9], v[8:9]
	v_pk_mul_f32 v[38:39], v[4:5], v[4:5]
	v_pk_mul_f32 v[34:35], v[34:35], s[64:65] op_sel_hi:[1,0]
	v_pk_fma_f32 v[40:41], v[24:25], s[42:43], v[16:17] op_sel_hi:[1,0,0]
	v_pk_mul_f32 v[38:39], v[38:39], s[64:65] op_sel_hi:[1,0]
	v_exp_f32_e32 v34, v34
	v_exp_f32_e32 v35, v35
	v_pk_fma_f32 v[42:43], v[36:37], s[42:43], v[16:17] op_sel_hi:[1,0,0]
	v_pk_fma_f32 v[40:41], v[24:25], v[40:41], s[48:49] op_sel_hi:[1,1,0]
	v_exp_f32_e32 v38, v38
	v_exp_f32_e32 v39, v39
	v_pk_fma_f32 v[42:43], v[36:37], v[42:43], s[48:49] op_sel_hi:[1,1,0]
	v_pk_fma_f32 v[40:41], v[24:25], v[40:41], s[50:51] op_sel_hi:[1,1,0]
	v_pk_fma_f32 v[42:43], v[36:37], v[42:43], s[50:51] op_sel_hi:[1,1,0]
	v_pk_fma_f32 v[40:41], v[24:25], v[40:41], s[56:57] op_sel_hi:[1,1,0]
	v_pk_fma_f32 v[42:43], v[36:37], v[42:43], s[56:57] op_sel_hi:[1,1,0]
	v_pk_mul_f32 v[24:25], v[24:25], v[40:41]
	v_pk_mul_f32 v[36:37], v[36:37], v[42:43]
	v_pk_mul_f32 v[24:25], v[34:35], v[24:25]
	v_pk_mul_f32 v[34:35], v[38:39], v[36:37]
	v_max_f32_e32 v106, 0, v8
	v_fma_f32 v8, -|v8|, v24, v106
	v_max_f32_e32 v107, 0, v9
	v_fma_f32 v9, -|v9|, v25, v107
	v_max_f32_e32 v108, 0, v4
	v_fma_f32 v4, -|v4|, v34, v108
	v_max_f32_e32 v109, 0, v5
	v_fma_f32 v5, -|v5|, v35, v109
	v_sub_f32_e32 v8, v8, v14
	v_mul_f32_e32 v8, v12, v8
	v_sub_f32_e32 v9, v9, v14
	v_mul_f32_e32 v9, v12, v9
	v_sub_f32_e32 v4, v4, v15
	v_mul_f32_e32 v4, v13, v4
	v_sub_f32_e32 v5, v5, v15
	ds_write_b32 v70, v3 offset:2448
	v_mul_f32_e32 v5, v13, v5
	s_waitcnt vmcnt(0)
	v_fma_f32 v3, v22, v8, v20
	v_fma_f32 v8, v23, v9, v21
	v_fma_f32 v4, v22, v4, v20
	v_cvt_pk_bf16_f32 v3, v3, v4
	v_fmac_f32_e32 v21, v23, v5
	ds_write_b32 v70, v3 offset:2720
	v_cvt_pk_bf16_f32 v3, v8, v21
	global_load_dwordx2 v[8:9], v2, s[0:1] offset:48
	global_load_dwordx2 v[4:5], v2, s[4:5] offset:48
	v_lshlrev_b32_e32 v20, 16, v10
	v_and_b32_e32 v21, 0xffff0000, v10
	v_lshlrev_b32_e32 v22, 16, v6
	v_and_b32_e32 v23, 0xffff0000, v6
	v_fma_f32 v24, |v20|, s40, 1.0
	v_fma_f32 v25, |v21|, s40, 1.0
	v_fma_f32 v36, |v22|, s40, 1.0
	v_fma_f32 v37, |v23|, s40, 1.0
	v_rcp_f32_e32 v24, v24
	v_rcp_f32_e32 v25, v25
	v_rcp_f32_e32 v36, v36
	v_rcp_f32_e32 v37, v37
	v_pk_mul_f32 v[34:35], v[20:21], v[20:21]
	v_pk_mul_f32 v[38:39], v[22:23], v[22:23]
	v_pk_mul_f32 v[34:35], v[34:35], s[64:65] op_sel_hi:[1,0]
	v_pk_fma_f32 v[40:41], v[24:25], s[42:43], v[16:17] op_sel_hi:[1,0,0]
	v_pk_mul_f32 v[38:39], v[38:39], s[64:65] op_sel_hi:[1,0]
	v_exp_f32_e32 v34, v34
	v_exp_f32_e32 v35, v35
	v_pk_fma_f32 v[42:43], v[36:37], s[42:43], v[16:17] op_sel_hi:[1,0,0]
	v_pk_fma_f32 v[40:41], v[24:25], v[40:41], s[48:49] op_sel_hi:[1,1,0]
	v_exp_f32_e32 v38, v38
	v_exp_f32_e32 v39, v39
	v_pk_fma_f32 v[42:43], v[36:37], v[42:43], s[48:49] op_sel_hi:[1,1,0]
	v_pk_fma_f32 v[40:41], v[24:25], v[40:41], s[50:51] op_sel_hi:[1,1,0]
	v_pk_fma_f32 v[42:43], v[36:37], v[42:43], s[50:51] op_sel_hi:[1,1,0]
	v_pk_fma_f32 v[40:41], v[24:25], v[40:41], s[56:57] op_sel_hi:[1,1,0]
	v_pk_fma_f32 v[42:43], v[36:37], v[42:43], s[56:57] op_sel_hi:[1,1,0]
	v_pk_mul_f32 v[24:25], v[24:25], v[40:41]
	v_pk_mul_f32 v[36:37], v[36:37], v[42:43]
	v_pk_mul_f32 v[24:25], v[34:35], v[24:25]
	v_pk_mul_f32 v[34:35], v[38:39], v[36:37]
	v_max_f32_e32 v110, 0, v20
	v_fma_f32 v6, -|v20|, v24, v110
	v_max_f32_e32 v111, 0, v21
	v_fma_f32 v10, -|v21|, v25, v111
	v_max_f32_e32 v112, 0, v22
	v_fma_f32 v20, -|v22|, v34, v112
	v_max_f32_e32 v113, 0, v23
	v_fma_f32 v21, -|v23|, v35, v113
	v_sub_f32_e32 v6, v6, v14
	v_mul_f32_e32 v6, v12, v6
	v_sub_f32_e32 v10, v10, v14
	v_mul_f32_e32 v10, v12, v10
	v_sub_f32_e32 v20, v20, v15
	v_mul_f32_e32 v20, v13, v20
	v_sub_f32_e32 v21, v21, v15
	v_mul_f32_e32 v21, v13, v21
	ds_write_b32 v70, v3 offset:2992
	s_waitcnt vmcnt(0)
	v_fma_f32 v3, v8, v6, v4
	v_fma_f32 v6, v9, v10, v5
	v_fma_f32 v4, v8, v20, v4
	v_fmac_f32_e32 v5, v9, v21
	v_cvt_pk_bf16_f32 v3, v3, v4
	ds_write_b32 v70, v3 offset:3264
	v_cvt_pk_bf16_f32 v3, v6, v5
	global_load_dwordx2 v[8:9], v2, s[0:1] offset:56
	global_load_dwordx2 v[4:5], v2, s[4:5] offset:56
	v_lshlrev_b32_e32 v10, 16, v11
	v_and_b32_e32 v11, 0xffff0000, v11
	v_lshlrev_b32_e32 v6, 16, v7
	v_and_b32_e32 v7, 0xffff0000, v7
	v_fma_f32 v20, |v10|, s40, 1.0
	v_fma_f32 v21, |v11|, s40, 1.0
	v_fma_f32 v24, |v6|, s40, 1.0
	v_fma_f32 v25, |v7|, s40, 1.0
	v_rcp_f32_e32 v20, v20
	v_rcp_f32_e32 v21, v21
	v_rcp_f32_e32 v24, v24
	v_rcp_f32_e32 v25, v25
	v_pk_mul_f32 v[22:23], v[10:11], v[10:11]
	v_pk_mul_f32 v[34:35], v[6:7], v[6:7]
	v_pk_mul_f32 v[22:23], v[22:23], s[64:65] op_sel_hi:[1,0]
	v_pk_fma_f32 v[36:37], v[20:21], s[42:43], v[16:17] op_sel_hi:[1,0,0]
	v_pk_mul_f32 v[34:35], v[34:35], s[64:65] op_sel_hi:[1,0]
	v_exp_f32_e32 v22, v22
	v_exp_f32_e32 v23, v23
	v_pk_fma_f32 v[38:39], v[24:25], s[42:43], v[16:17] op_sel_hi:[1,0,0]
	v_pk_fma_f32 v[36:37], v[20:21], v[36:37], s[48:49] op_sel_hi:[1,1,0]
	v_exp_f32_e32 v34, v34
	v_exp_f32_e32 v35, v35
	v_pk_fma_f32 v[38:39], v[24:25], v[38:39], s[48:49] op_sel_hi:[1,1,0]
	v_pk_fma_f32 v[36:37], v[20:21], v[36:37], s[50:51] op_sel_hi:[1,1,0]
	v_pk_fma_f32 v[38:39], v[24:25], v[38:39], s[50:51] op_sel_hi:[1,1,0]
	v_pk_fma_f32 v[36:37], v[20:21], v[36:37], s[56:57] op_sel_hi:[1,1,0]
	v_pk_fma_f32 v[38:39], v[24:25], v[38:39], s[56:57] op_sel_hi:[1,1,0]
	v_pk_mul_f32 v[20:21], v[20:21], v[36:37]
	v_pk_mul_f32 v[24:25], v[24:25], v[38:39]
	v_pk_mul_f32 v[20:21], v[22:23], v[20:21]
	v_pk_mul_f32 v[22:23], v[34:35], v[24:25]
	v_max_f32_e32 v114, 0, v10
	v_fma_f32 v10, -|v10|, v20, v114
	v_max_f32_e32 v115, 0, v11
	v_fma_f32 v11, -|v11|, v21, v115
	v_max_f32_e32 v116, 0, v6
	v_fma_f32 v6, -|v6|, v22, v116
	v_max_f32_e32 v117, 0, v7
	v_fma_f32 v7, -|v7|, v23, v117
	v_sub_f32_e32 v10, v10, v14
	v_mul_f32_e32 v10, v12, v10
	v_sub_f32_e32 v11, v11, v14
	v_mul_f32_e32 v11, v12, v11
	v_sub_f32_e32 v6, v6, v15
	v_mul_f32_e32 v6, v13, v6
	v_sub_f32_e32 v7, v7, v15
	v_mul_f32_e32 v7, v13, v7
	ds_write_b32 v70, v3 offset:3536
	s_waitcnt vmcnt(0)
	v_fma_f32 v3, v8, v10, v4
	v_fma_f32 v10, v9, v11, v5
	v_fma_f32 v4, v8, v6, v4
	v_fmac_f32_e32 v5, v9, v7
	v_cvt_pk_bf16_f32 v3, v3, v4
	ds_write_b32 v70, v3 offset:3808
	v_cvt_pk_bf16_f32 v3, v10, v5
	global_load_dwordx4 v[8:11], v[18:19], off offset:32
	global_load_dwordx4 v[4:7], v[18:19], off offset:2080
	global_load_dwordx2 v[22:23], v2, s[0:1] offset:64
	global_load_dwordx2 v[20:21], v2, s[4:5] offset:64
	ds_write_b32 v70, v3 offset:4080
	s_waitcnt vmcnt(3)
	v_lshlrev_b32_e32 v24, 16, v8
	v_and_b32_e32 v25, 0xffff0000, v8
	s_waitcnt vmcnt(2)
	v_lshlrev_b32_e32 v34, 16, v4
	v_and_b32_e32 v35, 0xffff0000, v4
	v_fma_f32 v36, |v24|, s40, 1.0
	v_fma_f32 v37, |v25|, s40, 1.0
	v_fma_f32 v40, |v34|, s40, 1.0
	v_fma_f32 v41, |v35|, s40, 1.0
	v_rcp_f32_e32 v36, v36
	v_rcp_f32_e32 v37, v37
	v_rcp_f32_e32 v40, v40
	v_rcp_f32_e32 v41, v41
	v_pk_mul_f32 v[38:39], v[24:25], v[24:25]
	v_pk_mul_f32 v[42:43], v[34:35], v[34:35]
	v_pk_mul_f32 v[38:39], v[38:39], s[64:65] op_sel_hi:[1,0]
	v_pk_fma_f32 v[44:45], v[36:37], s[42:43], v[16:17] op_sel_hi:[1,0,0]
	v_pk_mul_f32 v[42:43], v[42:43], s[64:65] op_sel_hi:[1,0]
	v_exp_f32_e32 v38, v38
	v_exp_f32_e32 v39, v39
	v_pk_fma_f32 v[46:47], v[40:41], s[42:43], v[16:17] op_sel_hi:[1,0,0]
	v_pk_fma_f32 v[44:45], v[36:37], v[44:45], s[48:49] op_sel_hi:[1,1,0]
	v_exp_f32_e32 v42, v42
	v_exp_f32_e32 v43, v43
	v_pk_fma_f32 v[46:47], v[40:41], v[46:47], s[48:49] op_sel_hi:[1,1,0]
	v_pk_fma_f32 v[44:45], v[36:37], v[44:45], s[50:51] op_sel_hi:[1,1,0]
	v_pk_fma_f32 v[46:47], v[40:41], v[46:47], s[50:51] op_sel_hi:[1,1,0]
	v_pk_fma_f32 v[44:45], v[36:37], v[44:45], s[56:57] op_sel_hi:[1,1,0]
	v_pk_fma_f32 v[46:47], v[40:41], v[46:47], s[56:57] op_sel_hi:[1,1,0]
	v_pk_mul_f32 v[36:37], v[36:37], v[44:45]
	v_pk_mul_f32 v[40:41], v[40:41], v[46:47]
	v_pk_mul_f32 v[36:37], v[38:39], v[36:37]
	v_pk_mul_f32 v[38:39], v[42:43], v[40:41]
	v_max_f32_e32 v80, 0, v24
	v_fma_f32 v3, -|v24|, v36, v80
	v_max_f32_e32 v81, 0, v25
	v_fma_f32 v4, -|v25|, v37, v81
	v_max_f32_e32 v82, 0, v34
	v_fma_f32 v8, -|v34|, v38, v82
	v_max_f32_e32 v83, 0, v35
	v_fma_f32 v24, -|v35|, v39, v83
	v_sub_f32_e32 v3, v3, v14
	v_mul_f32_e32 v3, v12, v3
	v_sub_f32_e32 v4, v4, v14
	v_mul_f32_e32 v4, v12, v4
	v_sub_f32_e32 v8, v8, v15
	v_mul_f32_e32 v8, v13, v8
	v_sub_f32_e32 v24, v24, v15
	v_mul_f32_e32 v24, v13, v24
	s_waitcnt vmcnt(0)
	v_fma_f32 v3, v22, v3, v20
	v_fma_f32 v4, v23, v4, v21
	v_fma_f32 v8, v22, v8, v20
	v_fmac_f32_e32 v21, v23, v24
	v_cvt_pk_bf16_f32 v3, v3, v8
	ds_write_b32 v70, v3 offset:4352
	v_cvt_pk_bf16_f32 v3, v4, v21
	global_load_dwordx2 v[22:23], v2, s[0:1] offset:72
	global_load_dwordx2 v[20:21], v2, s[4:5] offset:72
	v_lshlrev_b32_e32 v8, 16, v9
	v_and_b32_e32 v9, 0xffff0000, v9
	v_lshlrev_b32_e32 v4, 16, v5
	v_and_b32_e32 v5, 0xffff0000, v5
	v_fma_f32 v24, |v8|, s40, 1.0
	v_fma_f32 v25, |v9|, s40, 1.0
	v_fma_f32 v36, |v4|, s40, 1.0
	v_fma_f32 v37, |v5|, s40, 1.0
	v_rcp_f32_e32 v24, v24
	v_rcp_f32_e32 v25, v25
	v_rcp_f32_e32 v36, v36
	v_rcp_f32_e32 v37, v37
	v_pk_mul_f32 v[34:35], v[8:9], v[8:9]
	v_pk_mul_f32 v[38:39], v[4:5], v[4:5]
	v_pk_mul_f32 v[34:35], v[34:35], s[64:65] op_sel_hi:[1,0]
	v_pk_fma_f32 v[40:41], v[24:25], s[42:43], v[16:17] op_sel_hi:[1,0,0]
	v_pk_mul_f32 v[38:39], v[38:39], s[64:65] op_sel_hi:[1,0]
	v_exp_f32_e32 v34, v34
	v_exp_f32_e32 v35, v35
	v_pk_fma_f32 v[42:43], v[36:37], s[42:43], v[16:17] op_sel_hi:[1,0,0]
	v_pk_fma_f32 v[40:41], v[24:25], v[40:41], s[48:49] op_sel_hi:[1,1,0]
	v_exp_f32_e32 v38, v38
	v_exp_f32_e32 v39, v39
	v_pk_fma_f32 v[42:43], v[36:37], v[42:43], s[48:49] op_sel_hi:[1,1,0]
	v_pk_fma_f32 v[40:41], v[24:25], v[40:41], s[50:51] op_sel_hi:[1,1,0]
	v_pk_fma_f32 v[42:43], v[36:37], v[42:43], s[50:51] op_sel_hi:[1,1,0]
	v_pk_fma_f32 v[40:41], v[24:25], v[40:41], s[56:57] op_sel_hi:[1,1,0]
	v_pk_fma_f32 v[42:43], v[36:37], v[42:43], s[56:57] op_sel_hi:[1,1,0]
	v_pk_mul_f32 v[24:25], v[24:25], v[40:41]
	v_pk_mul_f32 v[36:37], v[36:37], v[42:43]
	v_pk_mul_f32 v[24:25], v[34:35], v[24:25]
	v_pk_mul_f32 v[34:35], v[38:39], v[36:37]
	v_max_f32_e32 v84, 0, v8
	v_fma_f32 v8, -|v8|, v24, v84
	v_max_f32_e32 v85, 0, v9
	v_fma_f32 v9, -|v9|, v25, v85
	v_max_f32_e32 v86, 0, v4
	v_fma_f32 v4, -|v4|, v34, v86
	v_max_f32_e32 v90, 0, v5
	v_fma_f32 v5, -|v5|, v35, v90
	v_sub_f32_e32 v8, v8, v14
	v_mul_f32_e32 v8, v12, v8
	v_sub_f32_e32 v9, v9, v14
	v_mul_f32_e32 v9, v12, v9
	v_sub_f32_e32 v4, v4, v15
	v_mul_f32_e32 v4, v13, v4
	v_sub_f32_e32 v5, v5, v15
	ds_write_b32 v70, v3 offset:4624
	v_mul_f32_e32 v5, v13, v5
	s_waitcnt vmcnt(0)
	v_fma_f32 v3, v22, v8, v20
	v_fma_f32 v8, v23, v9, v21
	v_fma_f32 v4, v22, v4, v20
	v_cvt_pk_bf16_f32 v3, v3, v4
	v_fmac_f32_e32 v21, v23, v5
	ds_write_b32 v70, v3 offset:4896
	v_cvt_pk_bf16_f32 v3, v8, v21
	global_load_dwordx2 v[8:9], v2, s[0:1] offset:80
	global_load_dwordx2 v[4:5], v2, s[4:5] offset:80
	v_lshlrev_b32_e32 v20, 16, v10
	v_and_b32_e32 v21, 0xffff0000, v10
	v_lshlrev_b32_e32 v22, 16, v6
	v_and_b32_e32 v23, 0xffff0000, v6
	v_fma_f32 v24, |v20|, s40, 1.0
	v_fma_f32 v25, |v21|, s40, 1.0
	v_fma_f32 v36, |v22|, s40, 1.0
	v_fma_f32 v37, |v23|, s40, 1.0
	v_rcp_f32_e32 v24, v24
	v_rcp_f32_e32 v25, v25
	v_rcp_f32_e32 v36, v36
	v_rcp_f32_e32 v37, v37
	v_pk_mul_f32 v[34:35], v[20:21], v[20:21]
	v_pk_mul_f32 v[38:39], v[22:23], v[22:23]
	v_pk_mul_f32 v[34:35], v[34:35], s[64:65] op_sel_hi:[1,0]
	v_pk_fma_f32 v[40:41], v[24:25], s[42:43], v[16:17] op_sel_hi:[1,0,0]
	v_pk_mul_f32 v[38:39], v[38:39], s[64:65] op_sel_hi:[1,0]
	v_exp_f32_e32 v34, v34
	v_exp_f32_e32 v35, v35
	v_pk_fma_f32 v[42:43], v[36:37], s[42:43], v[16:17] op_sel_hi:[1,0,0]
	v_pk_fma_f32 v[40:41], v[24:25], v[40:41], s[48:49] op_sel_hi:[1,1,0]
	v_exp_f32_e32 v38, v38
	v_exp_f32_e32 v39, v39
	v_pk_fma_f32 v[42:43], v[36:37], v[42:43], s[48:49] op_sel_hi:[1,1,0]
	v_pk_fma_f32 v[40:41], v[24:25], v[40:41], s[50:51] op_sel_hi:[1,1,0]
	v_pk_fma_f32 v[42:43], v[36:37], v[42:43], s[50:51] op_sel_hi:[1,1,0]
	v_pk_fma_f32 v[40:41], v[24:25], v[40:41], s[56:57] op_sel_hi:[1,1,0]
	v_pk_fma_f32 v[42:43], v[36:37], v[42:43], s[56:57] op_sel_hi:[1,1,0]
	v_pk_mul_f32 v[24:25], v[24:25], v[40:41]
	v_pk_mul_f32 v[36:37], v[36:37], v[42:43]
	v_pk_mul_f32 v[24:25], v[34:35], v[24:25]
	v_pk_mul_f32 v[34:35], v[38:39], v[36:37]
	v_max_f32_e32 v91, 0, v20
	v_fma_f32 v6, -|v20|, v24, v91
	v_max_f32_e32 v92, 0, v21
	v_fma_f32 v10, -|v21|, v25, v92
	v_max_f32_e32 v93, 0, v22
	v_fma_f32 v20, -|v22|, v34, v93
	v_max_f32_e32 v94, 0, v23
	v_fma_f32 v21, -|v23|, v35, v94
	v_sub_f32_e32 v6, v6, v14
	v_mul_f32_e32 v6, v12, v6
	v_sub_f32_e32 v10, v10, v14
	v_mul_f32_e32 v10, v12, v10
	v_sub_f32_e32 v20, v20, v15
	v_mul_f32_e32 v20, v13, v20
	v_sub_f32_e32 v21, v21, v15
	v_mul_f32_e32 v21, v13, v21
	ds_write_b32 v70, v3 offset:5168
	s_waitcnt vmcnt(0)
	v_fma_f32 v3, v8, v6, v4
	v_fma_f32 v6, v9, v10, v5
	v_fma_f32 v4, v8, v20, v4
	v_fmac_f32_e32 v5, v9, v21
	v_cvt_pk_bf16_f32 v3, v3, v4
	ds_write_b32 v70, v3 offset:5440
	v_cvt_pk_bf16_f32 v3, v6, v5
	global_load_dwordx2 v[8:9], v2, s[0:1] offset:88
	global_load_dwordx2 v[4:5], v2, s[4:5] offset:88
	v_lshlrev_b32_e32 v10, 16, v11
	v_and_b32_e32 v11, 0xffff0000, v11
	v_lshlrev_b32_e32 v6, 16, v7
	v_and_b32_e32 v7, 0xffff0000, v7
	v_fma_f32 v20, |v10|, s40, 1.0
	v_fma_f32 v21, |v11|, s40, 1.0
	v_fma_f32 v24, |v6|, s40, 1.0
	v_fma_f32 v25, |v7|, s40, 1.0
	v_rcp_f32_e32 v20, v20
	v_rcp_f32_e32 v21, v21
	v_rcp_f32_e32 v24, v24
	v_rcp_f32_e32 v25, v25
	v_pk_mul_f32 v[22:23], v[10:11], v[10:11]
	v_pk_mul_f32 v[34:35], v[6:7], v[6:7]
	v_pk_mul_f32 v[22:23], v[22:23], s[64:65] op_sel_hi:[1,0]
	v_pk_fma_f32 v[36:37], v[20:21], s[42:43], v[16:17] op_sel_hi:[1,0,0]
	v_pk_mul_f32 v[34:35], v[34:35], s[64:65] op_sel_hi:[1,0]
	v_exp_f32_e32 v22, v22
	v_exp_f32_e32 v23, v23
	v_pk_fma_f32 v[38:39], v[24:25], s[42:43], v[16:17] op_sel_hi:[1,0,0]
	v_pk_fma_f32 v[36:37], v[20:21], v[36:37], s[48:49] op_sel_hi:[1,1,0]
	v_exp_f32_e32 v34, v34
	v_exp_f32_e32 v35, v35
	v_pk_fma_f32 v[38:39], v[24:25], v[38:39], s[48:49] op_sel_hi:[1,1,0]
	v_pk_fma_f32 v[36:37], v[20:21], v[36:37], s[50:51] op_sel_hi:[1,1,0]
	v_pk_fma_f32 v[38:39], v[24:25], v[38:39], s[50:51] op_sel_hi:[1,1,0]
	v_pk_fma_f32 v[36:37], v[20:21], v[36:37], s[56:57] op_sel_hi:[1,1,0]
	v_pk_fma_f32 v[38:39], v[24:25], v[38:39], s[56:57] op_sel_hi:[1,1,0]
	v_pk_mul_f32 v[20:21], v[20:21], v[36:37]
	v_pk_mul_f32 v[24:25], v[24:25], v[38:39]
	v_pk_mul_f32 v[20:21], v[22:23], v[20:21]
	v_pk_mul_f32 v[22:23], v[34:35], v[24:25]
	v_max_f32_e32 v95, 0, v10
	v_fma_f32 v10, -|v10|, v20, v95
	v_max_f32_e32 v96, 0, v11
	v_fma_f32 v11, -|v11|, v21, v96
	v_max_f32_e32 v97, 0, v6
	v_fma_f32 v6, -|v6|, v22, v97
	v_max_f32_e32 v98, 0, v7
	v_fma_f32 v7, -|v7|, v23, v98
	v_sub_f32_e32 v10, v10, v14
	v_mul_f32_e32 v10, v12, v10
	v_sub_f32_e32 v11, v11, v14
	v_mul_f32_e32 v11, v12, v11
	v_sub_f32_e32 v6, v6, v15
	v_mul_f32_e32 v6, v13, v6
	v_sub_f32_e32 v7, v7, v15
	v_mul_f32_e32 v7, v13, v7
	ds_write_b32 v70, v3 offset:5712
	s_waitcnt vmcnt(0)
	v_fma_f32 v3, v8, v10, v4
	v_fma_f32 v10, v9, v11, v5
	v_fma_f32 v4, v8, v6, v4
	v_fmac_f32_e32 v5, v9, v7
	v_cvt_pk_bf16_f32 v3, v3, v4
	ds_write_b32 v70, v3 offset:5984
	v_cvt_pk_bf16_f32 v3, v10, v5
	global_load_dwordx4 v[8:11], v[18:19], off offset:48
	global_load_dwordx4 v[4:7], v[18:19], off offset:2096
	global_load_dwordx2 v[20:21], v2, s[0:1] offset:96
	s_nop 0
	global_load_dwordx2 v[18:19], v2, s[4:5] offset:96
	ds_write_b32 v70, v3 offset:6256
	s_waitcnt vmcnt(3)
	v_lshlrev_b32_e32 v22, 16, v8
	v_and_b32_e32 v23, 0xffff0000, v8
	s_waitcnt vmcnt(2)
	v_lshlrev_b32_e32 v24, 16, v4
	v_and_b32_e32 v25, 0xffff0000, v4
	v_fma_f32 v34, |v22|, s40, 1.0
	v_fma_f32 v35, |v23|, s40, 1.0
	v_fma_f32 v38, |v24|, s40, 1.0
	v_fma_f32 v39, |v25|, s40, 1.0
	v_rcp_f32_e32 v34, v34
	v_rcp_f32_e32 v35, v35
	v_rcp_f32_e32 v38, v38
	v_rcp_f32_e32 v39, v39
	v_pk_mul_f32 v[36:37], v[22:23], v[22:23]
	v_pk_mul_f32 v[40:41], v[24:25], v[24:25]
	v_pk_mul_f32 v[36:37], v[36:37], s[64:65] op_sel_hi:[1,0]
	v_pk_fma_f32 v[42:43], v[34:35], s[42:43], v[16:17] op_sel_hi:[1,0,0]
	v_pk_mul_f32 v[40:41], v[40:41], s[64:65] op_sel_hi:[1,0]
	v_exp_f32_e32 v36, v36
	v_exp_f32_e32 v37, v37
	v_pk_fma_f32 v[44:45], v[38:39], s[42:43], v[16:17] op_sel_hi:[1,0,0]
	v_pk_fma_f32 v[42:43], v[34:35], v[42:43], s[48:49] op_sel_hi:[1,1,0]
	v_exp_f32_e32 v40, v40
	v_exp_f32_e32 v41, v41
	v_pk_fma_f32 v[44:45], v[38:39], v[44:45], s[48:49] op_sel_hi:[1,1,0]
	v_pk_fma_f32 v[42:43], v[34:35], v[42:43], s[50:51] op_sel_hi:[1,1,0]
	v_pk_fma_f32 v[44:45], v[38:39], v[44:45], s[50:51] op_sel_hi:[1,1,0]
	v_pk_fma_f32 v[42:43], v[34:35], v[42:43], s[56:57] op_sel_hi:[1,1,0]
	v_pk_fma_f32 v[44:45], v[38:39], v[44:45], s[56:57] op_sel_hi:[1,1,0]
	v_pk_mul_f32 v[34:35], v[34:35], v[42:43]
	v_pk_mul_f32 v[38:39], v[38:39], v[44:45]
	v_pk_mul_f32 v[34:35], v[36:37], v[34:35]
	v_pk_mul_f32 v[36:37], v[40:41], v[38:39]
	v_max_f32_e32 v99, 0, v22
	v_fma_f32 v3, -|v22|, v34, v99
	v_max_f32_e32 v100, 0, v23
	v_fma_f32 v4, -|v23|, v35, v100
	v_max_f32_e32 v104, 0, v24
	v_fma_f32 v8, -|v24|, v36, v104
	v_max_f32_e32 v105, 0, v25
	v_fma_f32 v22, -|v25|, v37, v105
	v_sub_f32_e32 v3, v3, v14
	v_mul_f32_e32 v3, v12, v3
	v_sub_f32_e32 v4, v4, v14
	v_mul_f32_e32 v4, v12, v4
	v_sub_f32_e32 v8, v8, v15
	v_mul_f32_e32 v8, v13, v8
	v_sub_f32_e32 v22, v22, v15
	v_mul_f32_e32 v22, v13, v22
	s_waitcnt vmcnt(0)
	v_fma_f32 v3, v20, v3, v18
	v_fma_f32 v4, v21, v4, v19
	v_fma_f32 v8, v20, v8, v18
	v_fmac_f32_e32 v19, v21, v22
	v_cvt_pk_bf16_f32 v3, v3, v8
	ds_write_b32 v70, v3 offset:6528
	v_cvt_pk_bf16_f32 v3, v4, v19
	global_load_dwordx2 v[20:21], v2, s[0:1] offset:104
	global_load_dwordx2 v[18:19], v2, s[4:5] offset:104
	v_lshlrev_b32_e32 v8, 16, v9
	v_and_b32_e32 v9, 0xffff0000, v9
	v_lshlrev_b32_e32 v4, 16, v5
	v_and_b32_e32 v5, 0xffff0000, v5
	v_fma_f32 v22, |v8|, s40, 1.0
	v_fma_f32 v23, |v9|, s40, 1.0
	v_fma_f32 v34, |v4|, s40, 1.0
	v_fma_f32 v35, |v5|, s40, 1.0
	v_rcp_f32_e32 v22, v22
	v_rcp_f32_e32 v23, v23
	v_rcp_f32_e32 v34, v34
	v_rcp_f32_e32 v35, v35
	v_pk_mul_f32 v[24:25], v[8:9], v[8:9]
	v_pk_mul_f32 v[36:37], v[4:5], v[4:5]
	v_pk_mul_f32 v[24:25], v[24:25], s[64:65] op_sel_hi:[1,0]
	v_pk_fma_f32 v[38:39], v[22:23], s[42:43], v[16:17] op_sel_hi:[1,0,0]
	v_pk_mul_f32 v[36:37], v[36:37], s[64:65] op_sel_hi:[1,0]
	v_exp_f32_e32 v24, v24
	v_exp_f32_e32 v25, v25
	v_pk_fma_f32 v[40:41], v[34:35], s[42:43], v[16:17] op_sel_hi:[1,0,0]
	v_pk_fma_f32 v[38:39], v[22:23], v[38:39], s[48:49] op_sel_hi:[1,1,0]
	v_exp_f32_e32 v36, v36
	v_exp_f32_e32 v37, v37
	v_pk_fma_f32 v[40:41], v[34:35], v[40:41], s[48:49] op_sel_hi:[1,1,0]
	v_pk_fma_f32 v[38:39], v[22:23], v[38:39], s[50:51] op_sel_hi:[1,1,0]
	v_pk_fma_f32 v[40:41], v[34:35], v[40:41], s[50:51] op_sel_hi:[1,1,0]
	v_pk_fma_f32 v[38:39], v[22:23], v[38:39], s[56:57] op_sel_hi:[1,1,0]
	v_pk_fma_f32 v[40:41], v[34:35], v[40:41], s[56:57] op_sel_hi:[1,1,0]
	v_pk_mul_f32 v[22:23], v[22:23], v[38:39]
	v_pk_mul_f32 v[34:35], v[34:35], v[40:41]
	v_pk_mul_f32 v[22:23], v[24:25], v[22:23]
	v_pk_mul_f32 v[24:25], v[36:37], v[34:35]
	v_max_f32_e32 v106, 0, v8
	v_fma_f32 v8, -|v8|, v22, v106
	v_max_f32_e32 v107, 0, v9
	v_fma_f32 v9, -|v9|, v23, v107
	v_max_f32_e32 v108, 0, v4
	v_fma_f32 v4, -|v4|, v24, v108
	v_max_f32_e32 v109, 0, v5
	v_fma_f32 v5, -|v5|, v25, v109
	v_sub_f32_e32 v8, v8, v14
	v_mul_f32_e32 v8, v12, v8
	v_sub_f32_e32 v9, v9, v14
	v_mul_f32_e32 v9, v12, v9
	v_sub_f32_e32 v4, v4, v15
	v_mul_f32_e32 v4, v13, v4
	v_sub_f32_e32 v5, v5, v15
	ds_write_b32 v70, v3 offset:6800
	v_mul_f32_e32 v5, v13, v5
	s_waitcnt vmcnt(0)
	v_fma_f32 v3, v20, v8, v18
	v_fma_f32 v8, v21, v9, v19
	v_fma_f32 v4, v20, v4, v18
	v_cvt_pk_bf16_f32 v3, v3, v4
	v_fmac_f32_e32 v19, v21, v5
	ds_write_b32 v70, v3 offset:7072
	v_cvt_pk_bf16_f32 v3, v8, v19
	global_load_dwordx2 v[8:9], v2, s[0:1] offset:112
	global_load_dwordx2 v[4:5], v2, s[4:5] offset:112
	v_lshlrev_b32_e32 v18, 16, v10
	v_and_b32_e32 v19, 0xffff0000, v10
	v_lshlrev_b32_e32 v20, 16, v6
	v_and_b32_e32 v21, 0xffff0000, v6
	v_fma_f32 v22, |v18|, s40, 1.0
	v_fma_f32 v23, |v19|, s40, 1.0
	v_fma_f32 v34, |v20|, s40, 1.0
	v_fma_f32 v35, |v21|, s40, 1.0
	v_rcp_f32_e32 v22, v22
	v_rcp_f32_e32 v23, v23
	v_rcp_f32_e32 v34, v34
	v_rcp_f32_e32 v35, v35
	v_pk_mul_f32 v[24:25], v[18:19], v[18:19]
	v_pk_mul_f32 v[36:37], v[20:21], v[20:21]
	v_pk_mul_f32 v[24:25], v[24:25], s[64:65] op_sel_hi:[1,0]
	v_pk_fma_f32 v[38:39], v[22:23], s[42:43], v[16:17] op_sel_hi:[1,0,0]
	v_pk_mul_f32 v[36:37], v[36:37], s[64:65] op_sel_hi:[1,0]
	v_exp_f32_e32 v24, v24
	v_exp_f32_e32 v25, v25
	v_pk_fma_f32 v[40:41], v[34:35], s[42:43], v[16:17] op_sel_hi:[1,0,0]
	v_pk_fma_f32 v[38:39], v[22:23], v[38:39], s[48:49] op_sel_hi:[1,1,0]
	v_exp_f32_e32 v36, v36
	v_exp_f32_e32 v37, v37
	v_pk_fma_f32 v[40:41], v[34:35], v[40:41], s[48:49] op_sel_hi:[1,1,0]
	v_pk_fma_f32 v[38:39], v[22:23], v[38:39], s[50:51] op_sel_hi:[1,1,0]
	v_pk_fma_f32 v[40:41], v[34:35], v[40:41], s[50:51] op_sel_hi:[1,1,0]
	v_pk_fma_f32 v[38:39], v[22:23], v[38:39], s[56:57] op_sel_hi:[1,1,0]
	v_pk_fma_f32 v[40:41], v[34:35], v[40:41], s[56:57] op_sel_hi:[1,1,0]
	v_pk_mul_f32 v[22:23], v[22:23], v[38:39]
	v_pk_mul_f32 v[34:35], v[34:35], v[40:41]
	v_pk_mul_f32 v[22:23], v[24:25], v[22:23]
	v_pk_mul_f32 v[24:25], v[36:37], v[34:35]
	v_max_f32_e32 v110, 0, v18
	v_fma_f32 v6, -|v18|, v22, v110
	v_max_f32_e32 v111, 0, v19
	v_fma_f32 v10, -|v19|, v23, v111
	v_max_f32_e32 v112, 0, v20
	v_fma_f32 v18, -|v20|, v24, v112
	v_max_f32_e32 v113, 0, v21
	v_fma_f32 v19, -|v21|, v25, v113
	v_sub_f32_e32 v6, v6, v14
	v_mul_f32_e32 v6, v12, v6
	v_sub_f32_e32 v10, v10, v14
	v_mul_f32_e32 v10, v12, v10
	v_sub_f32_e32 v18, v18, v15
	v_mul_f32_e32 v18, v13, v18
	v_sub_f32_e32 v19, v19, v15
	v_mul_f32_e32 v19, v13, v19
	ds_write_b32 v70, v3 offset:7344
	s_andn2_b64 vcc, exec, s[80:81]
	s_waitcnt vmcnt(0)
	v_fma_f32 v3, v8, v6, v4
	v_fma_f32 v6, v9, v10, v5
	v_fma_f32 v4, v8, v18, v4
	v_fmac_f32_e32 v5, v9, v19
	v_cvt_pk_bf16_f32 v3, v3, v4
	ds_write_b32 v70, v3 offset:7616
	v_cvt_pk_bf16_f32 v3, v6, v5
	global_load_dwordx2 v[8:9], v2, s[0:1] offset:120
	global_load_dwordx2 v[4:5], v2, s[4:5] offset:120
	v_lshlrev_b32_e32 v10, 16, v11
	v_and_b32_e32 v11, 0xffff0000, v11
	v_cndmask_b32_e64 v6, 0, 1, s[80:81]
	v_cmp_ne_u32_e64 s[4:5], 1, v6
	v_lshlrev_b32_e32 v6, 16, v7
	v_and_b32_e32 v7, 0xffff0000, v7
	v_fma_f32 v18, |v10|, s40, 1.0
	v_fma_f32 v19, |v11|, s40, 1.0
	v_rcp_f32_e32 v18, v18
	v_rcp_f32_e32 v19, v19
	v_fma_f32 v22, |v6|, s40, 1.0
	v_fma_f32 v23, |v7|, s40, 1.0
	v_pk_mul_f32 v[20:21], v[10:11], v[10:11]
	v_rcp_f32_e32 v22, v22
	v_rcp_f32_e32 v23, v23
	v_pk_mul_f32 v[20:21], v[20:21], s[64:65] op_sel_hi:[1,0]
	v_pk_fma_f32 v[34:35], v[18:19], s[42:43], v[16:17] op_sel_hi:[1,0,0]
	v_pk_mul_f32 v[24:25], v[6:7], v[6:7]
	v_exp_f32_e32 v20, v20
	v_exp_f32_e32 v21, v21
	v_pk_fma_f32 v[34:35], v[18:19], v[34:35], s[48:49] op_sel_hi:[1,1,0]
	v_pk_mul_f32 v[24:25], v[24:25], s[64:65] op_sel_hi:[1,0]
	v_pk_fma_f32 v[16:17], v[22:23], s[42:43], v[16:17] op_sel_hi:[1,0,0]
	v_pk_fma_f32 v[34:35], v[18:19], v[34:35], s[50:51] op_sel_hi:[1,1,0]
	v_exp_f32_e32 v24, v24
	v_exp_f32_e32 v25, v25
	v_pk_fma_f32 v[16:17], v[22:23], v[16:17], s[48:49] op_sel_hi:[1,1,0]
	v_pk_fma_f32 v[34:35], v[18:19], v[34:35], s[56:57] op_sel_hi:[1,1,0]
	v_pk_fma_f32 v[16:17], v[22:23], v[16:17], s[50:51] op_sel_hi:[1,1,0]
	v_pk_mul_f32 v[18:19], v[18:19], v[34:35]
	v_pk_fma_f32 v[16:17], v[22:23], v[16:17], s[56:57] op_sel_hi:[1,1,0]
	v_pk_mul_f32 v[18:19], v[20:21], v[18:19]
	v_pk_mul_f32 v[16:17], v[22:23], v[16:17]
	v_max_f32_e32 v114, 0, v10
	v_fma_f32 v10, -|v10|, v18, v114
	v_max_f32_e32 v115, 0, v11
	v_fma_f32 v11, -|v11|, v19, v115
	v_pk_mul_f32 v[16:17], v[24:25], v[16:17]
	ds_write_b32 v70, v3 offset:7888
	v_max_f32_e32 v116, 0, v6
	v_fma_f32 v6, -|v6|, v16, v116
	v_max_f32_e32 v117, 0, v7
	v_fma_f32 v7, -|v7|, v17, v117
	v_sub_f32_e32 v10, v10, v14
	v_sub_f32_e32 v11, v11, v14
	v_sub_f32_e32 v6, v6, v15
	v_mul_f32_e32 v10, v12, v10
	v_sub_f32_e32 v7, v7, v15
	v_mul_f32_e32 v11, v12, v11
	v_mul_f32_e32 v6, v13, v6
	v_mul_f32_e32 v7, v13, v7
	s_waitcnt vmcnt(0)
	v_fma_f32 v3, v8, v10, v4
	v_fma_f32 v10, v9, v11, v5
	v_fma_f32 v4, v8, v6, v4
	v_fmac_f32_e32 v5, v9, v7
	v_cvt_pk_bf16_f32 v3, v3, v4
	ds_write_b32 v70, v3 offset:8160
	v_cvt_pk_bf16_f32 v3, v10, v5
	v_lshl_add_u64 v[4:5], s[12:13], 0, v[28:29]
	ds_write_b32 v70, v3 offset:8432
	s_cbranch_vccnz .LBB0_458
	v_add_co_u32_e32 v6, vcc, 0x2688000, v4
	s_nop 1
	v_addc_co_u32_e32 v7, vcc, 0, v5, vcc
	global_load_dwordx4 v[6:9], v[6:7], off
	v_cndmask_b32_e64 v3, 0, 1, s[82:83]
	v_cmp_ne_u32_e64 s[6:7], 1, v3
	s_andn2_b64 vcc, exec, s[82:83]
	s_cbranch_vccz .LBB0_459
